# GEMM K-loops: loop-edge edit - counter/pointer bumps and exit test rotated in front of the loop-back barrier
# speedup vs baseline: 1.0016x; 1.0016x over previous
; #define PG8_STAGE(bufoff, gbase, voff) do { _Pragma("unroll") for (int _i = 0; _i < 2; ++_i) \
;     __builtin_amdgcn_global_load_lds((const unsigned*)((const char*)(gbase) + (voff)[_i]), (PG8_LAS unsigned*)(lds + (bufoff) + ldsw + _i * 8192), 16, 0, 0); } while (0)
; #define PG8_LDA(dst, b, h) do { _Pragma("unroll") for (int m = 0; m < 4; ++m) _Pragma("unroll") for (int k = 0; k < 2; ++k) dst[m][k] = *(const PG8_LAS bf16x8*)(lds + PG8_SA(b, h) + aoff + m * 2048 + k * 1024); } while (0)
; #define PG8_LDB(dst, b, h) do { _Pragma("unroll") for (int n = 0; n < 2; ++n) _Pragma("unroll") for (int k = 0; k < 2; ++k) dst[n][k] = *(const PG8_LAS bf16x8*)(lds + PG8_SB(b, h) + boff + n * 2048 + k * 1024); } while (0)
; #define PG8_WAIT_V(n) asm volatile("s_waitcnt vmcnt(" #n ")" ::: "memory")
; #define PG8_WAIT_L(n) asm volatile("s_waitcnt lgkmcnt(" #n ")" ::: "memory")
; #define PG8_BAR __builtin_amdgcn_s_barrier()
; template <class Epi, class Sched>
; DI void gemm_phase(PG8_LAS unsigned char* lds, const Gemm g, const Sched& S, const Epi& E) {
;     ...
;     for (int t = 0; t < nt; t += 2) {
;       const bool last = (t == nt - 2);
;       const char* a1 = cA + (size_t)(t + 1) * kstep;
;       const char* a2 = last ? nA : cA + (size_t)(t + 2) * kstep; const char* b2 = last ? nB : cB + (size_t)(t + 2) * kstep;
;       const char* a3 = a2 + kstep; const char* b3 = b2 + kstep;
;       PG8_LDB(B0, 0, 0); PG8_LDB(B1, 0, 1); PG8_SCHED; PG8_LDA(At, 0, 0); PG8_STAGE(PG8_SA(1, 1), a1 + hstepA, voffA);
;       PG8_WAIT_V(8); PG8_WAIT_L(0); PG8_BAR; PG8_MMA(0, 0, At, B0); PG8_MMA(0, 1, At, B1); PG8_BAR; PG8_SCHED;
;       PG8_LDA(At, 0, 1); PG8_STAGE(PG8_SB(0, 0), b2, voffB); PG8_STAGE(PG8_SB(0, 1), b2 + hstepB, voffB); PG8_STAGE(PG8_SA(0, 0), a2, voffA);
;       PG8_WAIT_V(8); PG8_WAIT_L(0); PG8_BAR; PG8_MMA(1, 0, At, B0); PG8_MMA(1, 1, At, B1); PG8_BAR; PG8_SCHED;
;       PG8_LDB(B0, 1, 0); PG8_LDB(B1, 1, 1); PG8_SCHED; PG8_LDA(At, 1, 0); PG8_STAGE(PG8_SA(0, 1), a2 + hstepA, voffA);
;       PG8_WAIT_V(8); PG8_WAIT_L(0); PG8_BAR; PG8_MMA(0, 0, At, B0); PG8_MMA(0, 1, At, B1); PG8_BAR; PG8_SCHED;
;       PG8_LDA(At, 1, 1); PG8_STAGE(PG8_SB(1, 0), b3, voffB); PG8_STAGE(PG8_SB(1, 1), b3 + hstepB, voffB); PG8_STAGE(PG8_SA(1, 0), a3, voffA);
;       PG8_WAIT_V(8); PG8_WAIT_L(0); PG8_BAR; PG8_MMA(1, 0, At, B0); PG8_MMA(1, 1, At, B1); PG8_BAR; PG8_SCHED;
;     }
.LBB0_286:
	ds_read_b128 v[146:149], v180
	ds_read_b128 v[150:153], v180 offset:1024
	ds_read_b128 v[154:157], v180 offset:2048
	ds_read_b128 v[158:161], v180 offset:3072
	ds_read_b128 v[162:165], v181
	ds_read_b128 v[166:169], v181 offset:1024
	ds_read_b128 v[170:173], v181 offset:2048
	ds_read_b128 v[174:177], v181 offset:3072
	s_add_u32 s16, s6, 0xfffc0080
	s_addc_u32 s30, s7, -1
	s_cmp_eq_u32 s69, 12
	s_cselect_b32 s35, s1, s30
	s_cselect_b32 s34, s5, s16
	s_cselect_b32 s31, s21, s68
	s_cselect_b32 s30, s23, s67
	v_lshl_add_u64 v[178:179], s[6:7], 0, v[140:141]
	s_add_i32 m0, s3, 0xc000
	ds_read_b128 v[186:189], v182
	ds_read_b128 v[190:193], v182 offset:1024
	ds_read_b128 v[194:197], v182 offset:2048
	ds_read_b128 v[198:201], v182 offset:3072
	ds_read_b128 v[202:205], v182 offset:4096
	ds_read_b128 v[206:209], v182 offset:5120
	ds_read_b128 v[214:217], v182 offset:6144
	ds_read_b128 v[218:221], v182 offset:7168
	global_load_lds_dwordx4 v[178:179], off
	v_lshl_add_u64 v[178:179], s[6:7], 0, v[142:143]
	s_add_i32 m0, s3, 0xe000
	s_nop 0
	global_load_lds_dwordx4 v[178:179], off
	s_waitcnt vmcnt(8)
	s_waitcnt lgkmcnt(0)
	s_barrier
	s_setprio 1
	s_waitcnt lgkmcnt(0)
	v_mfma_f32_16x16x32_bf16 v[122:125], v[146:149], v[186:189], v[122:125]
	v_mfma_f32_16x16x32_bf16 v[126:129], v[154:157], v[186:189], v[126:129]
	v_mfma_f32_16x16x32_bf16 v[106:109], v[146:149], v[194:197], v[106:109]
	v_mfma_f32_16x16x32_bf16 v[110:113], v[154:157], v[194:197], v[110:113]
	v_mfma_f32_16x16x32_bf16 v[90:93], v[146:149], v[202:205], v[90:93]
	v_mfma_f32_16x16x32_bf16 v[94:97], v[154:157], v[202:205], v[94:97]
	v_mfma_f32_16x16x32_bf16 v[74:77], v[146:149], v[214:217], v[74:77]
	v_mfma_f32_16x16x32_bf16 v[78:81], v[154:157], v[214:217], v[78:81]
	v_mfma_f32_16x16x32_bf16 v[122:125], v[150:153], v[190:193], v[122:125]
	v_mfma_f32_16x16x32_bf16 v[126:129], v[158:161], v[190:193], v[126:129]
	v_mfma_f32_16x16x32_bf16 v[106:109], v[150:153], v[198:201], v[106:109]
	v_mfma_f32_16x16x32_bf16 v[110:113], v[158:161], v[198:201], v[110:113]
	v_mfma_f32_16x16x32_bf16 v[90:93], v[150:153], v[206:209], v[90:93]
	v_mfma_f32_16x16x32_bf16 v[94:97], v[158:161], v[206:209], v[94:97]
	v_mfma_f32_16x16x32_bf16 v[74:77], v[150:153], v[218:221], v[74:77]
	v_mfma_f32_16x16x32_bf16 v[78:81], v[158:161], v[218:221], v[78:81]
	s_setprio 0
	s_setprio 1
	v_mfma_f32_16x16x32_bf16 v[114:117], v[162:165], v[186:189], v[114:117]
	v_mfma_f32_16x16x32_bf16 v[118:121], v[170:173], v[186:189], v[118:121]
	v_mfma_f32_16x16x32_bf16 v[98:101], v[162:165], v[194:197], v[98:101]
	v_mfma_f32_16x16x32_bf16 v[102:105], v[170:173], v[194:197], v[102:105]
	v_mfma_f32_16x16x32_bf16 v[82:85], v[162:165], v[202:205], v[82:85]
	v_mfma_f32_16x16x32_bf16 v[86:89], v[170:173], v[202:205], v[86:89]
	v_mfma_f32_16x16x32_bf16 v[66:69], v[162:165], v[214:217], v[66:69]
	v_mfma_f32_16x16x32_bf16 v[70:73], v[170:173], v[214:217], v[70:73]
	v_mfma_f32_16x16x32_bf16 v[114:117], v[166:169], v[190:193], v[114:117]
	v_mfma_f32_16x16x32_bf16 v[118:121], v[174:177], v[190:193], v[118:121]
	v_mfma_f32_16x16x32_bf16 v[98:101], v[166:169], v[198:201], v[98:101]
	v_mfma_f32_16x16x32_bf16 v[102:105], v[174:177], v[198:201], v[102:105]
	v_mfma_f32_16x16x32_bf16 v[82:85], v[166:169], v[206:209], v[82:85]
	v_mfma_f32_16x16x32_bf16 v[86:89], v[174:177], v[206:209], v[86:89]
	v_mfma_f32_16x16x32_bf16 v[66:69], v[166:169], v[218:221], v[66:69]
	v_mfma_f32_16x16x32_bf16 v[70:73], v[174:177], v[218:221], v[70:73]
	s_setprio 0
	s_barrier
	s_add_i32 s16, s40, s2
	v_lshl_add_u64 v[178:179], s[30:31], 0, v[132:133]
	s_mov_b32 m0, s16
	ds_read_b128 v[186:189], v182 offset:16384
	ds_read_b128 v[190:193], v182 offset:17408
	ds_read_b128 v[194:197], v182 offset:18432
	ds_read_b128 v[198:201], v182 offset:19456
	ds_read_b128 v[202:205], v182 offset:20480
	ds_read_b128 v[206:209], v182 offset:21504
	ds_read_b128 v[214:217], v182 offset:22528
	ds_read_b128 v[218:221], v182 offset:23552
	global_load_lds_dwordx4 v[178:179], off
	s_add_i32 m0, s16, 0x2000
	s_add_u32 s56, s30, 0x40000
	v_lshl_add_u64 v[210:211], s[30:31], 0, v[136:137]
	s_addc_u32 s57, s31, 0
	s_add_i32 s16, s41, s2
	global_load_lds_dwordx4 v[210:211], off
	v_lshl_add_u64 v[222:223], s[56:57], 0, v[132:133]
	s_mov_b32 m0, s16
	v_lshl_add_u64 v[224:225], s[34:35], 0, v[134:135]
	global_load_lds_dwordx4 v[222:223], off
	v_lshl_add_u64 v[222:223], s[56:57], 0, v[136:137]
	s_add_i32 m0, s16, 0x2000
	s_nop 0
	global_load_lds_dwordx4 v[222:223], off
	v_lshl_add_u64 v[222:223], s[34:35], 0, v[130:131]
	s_mov_b32 m0, s3
	s_nop 0
	global_load_lds_dwordx4 v[222:223], off
	s_mov_b32 m0, s17
	s_nop 0
	global_load_lds_dwordx4 v[224:225], off
	s_waitcnt vmcnt(8)
	s_waitcnt lgkmcnt(0)
	s_barrier
; #define PG8_STAGE(bufoff, gbase, voff) do { _Pragma("unroll") for (int _i = 0; _i < 2; ++_i) \
;     __builtin_amdgcn_global_load_lds((const unsigned*)((const char*)(gbase) + (voff)[_i]), (PG8_LAS unsigned*)(lds + (bufoff) + ldsw + _i * 8192), 16, 0, 0); } while (0)
; #define PG8_LDA(dst, b, h) do { _Pragma("unroll") for (int m = 0; m < 4; ++m) _Pragma("unroll") for (int k = 0; k < 2; ++k) dst[m][k] = *(const PG8_LAS bf16x8*)(lds + PG8_SA(b, h) + aoff + m * 2048 + k * 1024); } while (0)
; #define PG8_LDB(dst, b, h) do { _Pragma("unroll") for (int n = 0; n < 2; ++n) _Pragma("unroll") for (int k = 0; k < 2; ++k) dst[n][k] = *(const PG8_LAS bf16x8*)(lds + PG8_SB(b, h) + boff + n * 2048 + k * 1024); } while (0)
; #define PG8_MMA(ai, bj, At, Bt) do { __builtin_amdgcn_s_setprio(1); _Pragma("unroll") for (int m = 0; m < 4; ++m) _Pragma("unroll") for (int n = 0; n < 2; ++n) _Pragma("unroll") for (int k = 0; k < 2; ++k) \
;     acc[ai][bj][m][n] = __builtin_amdgcn_mfma_f32_16x16x32_bf16(Bt[n][k], At[m][k], acc[ai][bj][m][n], 0, 0, 0); __builtin_amdgcn_s_setprio(0); } while (0)
; #define PG8_WAIT_V(n) asm volatile("s_waitcnt vmcnt(" #n ")" ::: "memory")
; #define PG8_WAIT_L(n) asm volatile("s_waitcnt lgkmcnt(" #n ")" ::: "memory")
; #define PG8_BAR __builtin_amdgcn_s_barrier()
; #define PG8_SCHED __builtin_amdgcn_sched_barrier(0)
; template <class Epi, class Sched>
; DI void gemm_phase(PG8_LAS unsigned char* lds, const Gemm g, const Sched& S, const Epi& E) {
;     ...
;       PG8_WAIT_V(8); PG8_WAIT_L(0); PG8_BAR; PG8_MMA(0, 0, At, B0); PG8_MMA(0, 1, At, B1); PG8_BAR; PG8_SCHED;
;       PG8_LDA(At, 0, 1); PG8_STAGE(PG8_SB(0, 0), b2, voffB); PG8_STAGE(PG8_SB(0, 1), b2 + hstepB, voffB); PG8_STAGE(PG8_SA(0, 0), a2, voffA);
;       PG8_WAIT_V(8); PG8_WAIT_L(0); PG8_BAR; PG8_MMA(1, 0, At, B0); PG8_MMA(1, 1, At, B1); PG8_BAR; PG8_SCHED;
;       PG8_LDB(B0, 1, 0); PG8_LDB(B1, 1, 1); PG8_SCHED; PG8_LDA(At, 1, 0); PG8_STAGE(PG8_SA(0, 1), a2 + hstepA, voffA);
;       PG8_WAIT_V(8); PG8_WAIT_L(0); PG8_BAR; PG8_MMA(0, 0, At, B0); PG8_MMA(0, 1, At, B1); PG8_BAR; PG8_SCHED;
;       PG8_LDA(At, 1, 1); PG8_STAGE(PG8_SB(1, 0), b3, voffB); PG8_STAGE(PG8_SB(1, 1), b3 + hstepB, voffB); PG8_STAGE(PG8_SA(1, 0), a3, voffA);
	s_setprio 1
	s_waitcnt lgkmcnt(0)
	v_mfma_f32_16x16x32_bf16 v[58:61], v[146:149], v[186:189], v[58:61]
	v_mfma_f32_16x16x32_bf16 v[62:65], v[154:157], v[186:189], v[62:65]
	v_mfma_f32_16x16x32_bf16 v[42:45], v[146:149], v[194:197], v[42:45]
	v_mfma_f32_16x16x32_bf16 v[46:49], v[154:157], v[194:197], v[46:49]
	v_mfma_f32_16x16x32_bf16 v[26:29], v[146:149], v[202:205], v[26:29]
	v_mfma_f32_16x16x32_bf16 v[30:33], v[154:157], v[202:205], v[30:33]
	v_mfma_f32_16x16x32_bf16 v[10:13], v[146:149], v[214:217], v[10:13]
	v_mfma_f32_16x16x32_bf16 v[14:17], v[154:157], v[214:217], v[14:17]
	v_mfma_f32_16x16x32_bf16 v[58:61], v[150:153], v[190:193], v[58:61]
	v_mfma_f32_16x16x32_bf16 v[62:65], v[158:161], v[190:193], v[62:65]
	v_mfma_f32_16x16x32_bf16 v[42:45], v[150:153], v[198:201], v[42:45]
	v_mfma_f32_16x16x32_bf16 v[46:49], v[158:161], v[198:201], v[46:49]
	v_mfma_f32_16x16x32_bf16 v[26:29], v[150:153], v[206:209], v[26:29]
	v_mfma_f32_16x16x32_bf16 v[30:33], v[158:161], v[206:209], v[30:33]
	v_mfma_f32_16x16x32_bf16 v[10:13], v[150:153], v[218:221], v[10:13]
	v_mfma_f32_16x16x32_bf16 v[14:17], v[158:161], v[218:221], v[14:17]
	s_setprio 0
	s_setprio 1
	v_mfma_f32_16x16x32_bf16 v[50:53], v[162:165], v[186:189], v[50:53]
	v_mfma_f32_16x16x32_bf16 v[54:57], v[170:173], v[186:189], v[54:57]
	v_mfma_f32_16x16x32_bf16 v[34:37], v[162:165], v[194:197], v[34:37]
	v_mfma_f32_16x16x32_bf16 v[38:41], v[170:173], v[194:197], v[38:41]
	v_mfma_f32_16x16x32_bf16 v[18:21], v[162:165], v[202:205], v[18:21]
	v_mfma_f32_16x16x32_bf16 v[22:25], v[170:173], v[202:205], v[22:25]
	v_mfma_f32_16x16x32_bf16 v[6:9], v[162:165], v[214:217], v[6:9]
	v_mfma_f32_16x16x32_bf16 v[2:5], v[170:173], v[214:217], v[2:5]
	v_mfma_f32_16x16x32_bf16 v[50:53], v[166:169], v[190:193], v[50:53]
	v_mfma_f32_16x16x32_bf16 v[54:57], v[174:177], v[190:193], v[54:57]
	v_mfma_f32_16x16x32_bf16 v[34:37], v[166:169], v[198:201], v[34:37]
	v_mfma_f32_16x16x32_bf16 v[38:41], v[174:177], v[198:201], v[38:41]
	v_mfma_f32_16x16x32_bf16 v[18:21], v[166:169], v[206:209], v[18:21]
	v_mfma_f32_16x16x32_bf16 v[22:25], v[174:177], v[206:209], v[22:25]
	v_mfma_f32_16x16x32_bf16 v[6:9], v[166:169], v[218:221], v[6:9]
	v_mfma_f32_16x16x32_bf16 v[2:5], v[174:177], v[218:221], v[2:5]
	s_setprio 0
	s_barrier
	ds_read_b128 v[146:149], v184
	ds_read_b128 v[150:153], v184 offset:1024
	ds_read_b128 v[154:157], v184 offset:2048
	ds_read_b128 v[158:161], v184 offset:3072
	ds_read_b128 v[162:165], v185
	ds_read_b128 v[166:169], v185 offset:1024
	ds_read_b128 v[170:173], v185 offset:2048
	ds_read_b128 v[174:177], v185 offset:3072
	s_add_u32 s34, s34, 0x40000
	s_addc_u32 s35, s35, 0
	s_mov_b32 m0, s19
	v_lshl_add_u64 v[226:227], s[34:35], 0, v[130:131]
	ds_read_b128 v[186:189], v182 offset:32768
	ds_read_b128 v[190:193], v182 offset:33792
	ds_read_b128 v[194:197], v182 offset:34816
	ds_read_b128 v[198:201], v182 offset:35840
	ds_read_b128 v[202:205], v182 offset:36864
	ds_read_b128 v[206:209], v182 offset:37888
	ds_read_b128 v[214:217], v182 offset:38912
	ds_read_b128 v[218:221], v182 offset:39936
	global_load_lds_dwordx4 v[226:227], off
	v_lshl_add_u64 v[226:227], s[34:35], 0, v[134:135]
	s_mov_b32 m0, s33
	s_nop 0
	global_load_lds_dwordx4 v[226:227], off
	s_waitcnt vmcnt(8)
	s_waitcnt lgkmcnt(0)
	s_barrier
	s_setprio 1
	s_waitcnt lgkmcnt(0)
	v_mfma_f32_16x16x32_bf16 v[122:125], v[146:149], v[186:189], v[122:125]
	v_mfma_f32_16x16x32_bf16 v[126:129], v[154:157], v[186:189], v[126:129]
	v_mfma_f32_16x16x32_bf16 v[106:109], v[146:149], v[194:197], v[106:109]
	v_mfma_f32_16x16x32_bf16 v[110:113], v[154:157], v[194:197], v[110:113]
	v_mfma_f32_16x16x32_bf16 v[90:93], v[146:149], v[202:205], v[90:93]
	v_mfma_f32_16x16x32_bf16 v[94:97], v[154:157], v[202:205], v[94:97]
	v_mfma_f32_16x16x32_bf16 v[74:77], v[146:149], v[214:217], v[74:77]
	v_mfma_f32_16x16x32_bf16 v[78:81], v[154:157], v[214:217], v[78:81]
	v_mfma_f32_16x16x32_bf16 v[122:125], v[150:153], v[190:193], v[122:125]
	v_mfma_f32_16x16x32_bf16 v[126:129], v[158:161], v[190:193], v[126:129]
	v_mfma_f32_16x16x32_bf16 v[106:109], v[150:153], v[198:201], v[106:109]
	v_mfma_f32_16x16x32_bf16 v[110:113], v[158:161], v[198:201], v[110:113]
	v_mfma_f32_16x16x32_bf16 v[90:93], v[150:153], v[206:209], v[90:93]
	v_mfma_f32_16x16x32_bf16 v[94:97], v[158:161], v[206:209], v[94:97]
	v_mfma_f32_16x16x32_bf16 v[74:77], v[150:153], v[218:221], v[74:77]
	v_mfma_f32_16x16x32_bf16 v[78:81], v[158:161], v[218:221], v[78:81]
	s_setprio 0
	s_setprio 1
	v_mfma_f32_16x16x32_bf16 v[114:117], v[162:165], v[186:189], v[114:117]
	v_mfma_f32_16x16x32_bf16 v[118:121], v[170:173], v[186:189], v[118:121]
	v_mfma_f32_16x16x32_bf16 v[98:101], v[162:165], v[194:197], v[98:101]
	v_mfma_f32_16x16x32_bf16 v[102:105], v[170:173], v[194:197], v[102:105]
	v_mfma_f32_16x16x32_bf16 v[82:85], v[162:165], v[202:205], v[82:85]
	v_mfma_f32_16x16x32_bf16 v[86:89], v[170:173], v[202:205], v[86:89]
	v_mfma_f32_16x16x32_bf16 v[66:69], v[162:165], v[214:217], v[66:69]
	v_mfma_f32_16x16x32_bf16 v[70:73], v[170:173], v[214:217], v[70:73]
	v_mfma_f32_16x16x32_bf16 v[114:117], v[166:169], v[190:193], v[114:117]
	v_mfma_f32_16x16x32_bf16 v[118:121], v[174:177], v[190:193], v[118:121]
	v_mfma_f32_16x16x32_bf16 v[98:101], v[166:169], v[198:201], v[98:101]
	v_mfma_f32_16x16x32_bf16 v[102:105], v[174:177], v[198:201], v[102:105]
	v_mfma_f32_16x16x32_bf16 v[82:85], v[166:169], v[206:209], v[82:85]
	v_mfma_f32_16x16x32_bf16 v[86:89], v[174:177], v[206:209], v[86:89]
	v_mfma_f32_16x16x32_bf16 v[66:69], v[166:169], v[218:221], v[66:69]
	v_mfma_f32_16x16x32_bf16 v[70:73], v[174:177], v[218:221], v[70:73]
	s_setprio 0
	s_barrier
; #define PG8_STAGE(bufoff, gbase, voff) do { _Pragma("unroll") for (int _i = 0; _i < 2; ++_i) \
;     __builtin_amdgcn_global_load_lds((const unsigned*)((const char*)(gbase) + (voff)[_i]), (PG8_LAS unsigned*)(lds + (bufoff) + ldsw + _i * 8192), 16, 0, 0); } while (0)
; #define PG8_LDA(dst, b, h) do { _Pragma("unroll") for (int m = 0; m < 4; ++m) _Pragma("unroll") for (int k = 0; k < 2; ++k) dst[m][k] = *(const PG8_LAS bf16x8*)(lds + PG8_SA(b, h) + aoff + m * 2048 + k * 1024); } while (0)
; #define PG8_BAR __builtin_amdgcn_s_barrier()
; DI void rows_rstd(float (&rs)[2][4], const float* ps, const Unit& u, int wr, int fr, int fq, int p_lo, int p_hi, float inv_dim) {
;   f32x4 pv[2][4];
; #pragma unroll
;   for (int ai = 0; ai < 2; ++ai)
; #pragma unroll
;     for (int m = 0; m < 4; ++m) pv[ai][m] = *(const f32x4*)(ps + (size_t)(u.pm * BM + ai * HALF + wr * 64 + m * 16 + fr) * 16 + 4 * fq);
; template <class Epi, class Sched>
; DI void gemm_phase(PG8_LAS unsigned char* lds, const Gemm g, const Sched& S, const Epi& E) {
;     ...
;     for (int t = 0; t < nt; t += 2) {
;       const bool last = (t == nt - 2);
;       const char* a1 = cA + (size_t)(t + 1) * kstep;
;       const char* a2 = last ? nA : cA + (size_t)(t + 2) * kstep; const char* b2 = last ? nB : cB + (size_t)(t + 2) * kstep;
;       const char* a3 = a2 + kstep; const char* b3 = b2 + kstep;
;       PG8_LDB(B0, 0, 0); PG8_LDB(B1, 0, 1); PG8_SCHED; PG8_LDA(At, 0, 0); PG8_STAGE(PG8_SA(1, 1), a1 + hstepA, voffA);
;       PG8_WAIT_V(8); PG8_WAIT_L(0); PG8_BAR; PG8_MMA(0, 0, At, B0); PG8_MMA(0, 1, At, B1); PG8_BAR; PG8_SCHED;
;       PG8_LDA(At, 0, 1); PG8_STAGE(PG8_SB(0, 0), b2, voffB); PG8_STAGE(PG8_SB(0, 1), b2 + hstepB, voffB); PG8_STAGE(PG8_SA(0, 0), a2, voffA);
;       PG8_WAIT_V(8); PG8_WAIT_L(0); PG8_BAR; PG8_MMA(1, 0, At, B0); PG8_MMA(1, 1, At, B1); PG8_BAR; PG8_SCHED;
;       PG8_LDB(B0, 1, 0); PG8_LDB(B1, 1, 1); PG8_SCHED; PG8_LDA(At, 1, 0); PG8_STAGE(PG8_SA(0, 1), a2 + hstepA, voffA);
;       PG8_WAIT_V(8); PG8_WAIT_L(0); PG8_BAR; PG8_MMA(0, 0, At, B0); PG8_MMA(0, 1, At, B1); PG8_BAR; PG8_SCHED;
;       PG8_LDA(At, 1, 1); PG8_STAGE(PG8_SB(1, 0), b3, voffB); PG8_STAGE(PG8_SB(1, 1), b3 + hstepB, voffB); PG8_STAGE(PG8_SA(1, 0), a3, voffA);
;       PG8_WAIT_V(8); PG8_WAIT_L(0); PG8_BAR; PG8_MMA(1, 0, At, B0); PG8_MMA(1, 1, At, B1); PG8_BAR; PG8_SCHED;
;     }
;     if (wr == 0) PG8_BAR;
	s_add_i32 s16, s65, s2
	v_lshl_add_u64 v[178:179], v[178:179], 0, s[12:13]
	s_mov_b32 m0, s16
	ds_read_b128 v[186:189], v182 offset:49152
	ds_read_b128 v[190:193], v182 offset:50176
	ds_read_b128 v[194:197], v182 offset:51200
	ds_read_b128 v[198:201], v182 offset:52224
	ds_read_b128 v[202:205], v182 offset:53248
	ds_read_b128 v[206:209], v182 offset:54272
	ds_read_b128 v[214:217], v182 offset:55296
	ds_read_b128 v[218:221], v182 offset:56320
	global_load_lds_dwordx4 v[178:179], off
	s_add_i32 m0, s16, 0x2000
	s_add_u32 s30, s30, 0x40080
	v_lshl_add_u64 v[178:179], v[210:211], 0, s[12:13]
	s_addc_u32 s31, s31, 0
	s_add_i32 s16, s66, s2
	global_load_lds_dwordx4 v[178:179], off
	v_lshl_add_u64 v[178:179], s[30:31], 0, v[132:133]
	s_mov_b32 m0, s16
	s_nop 0
	global_load_lds_dwordx4 v[178:179], off
	v_lshl_add_u64 v[178:179], s[30:31], 0, v[136:137]
	s_add_i32 m0, s16, 0x2000
	s_nop 0
	global_load_lds_dwordx4 v[178:179], off
	v_lshl_add_u64 v[178:179], v[222:223], 0, s[12:13]
	s_mov_b32 m0, s36
	s_nop 0
	global_load_lds_dwordx4 v[178:179], off
	v_lshl_add_u64 v[178:179], v[224:225], 0, s[12:13]
	s_mov_b32 m0, s37
	s_nop 0
	global_load_lds_dwordx4 v[178:179], off
	s_waitcnt vmcnt(8)
	s_waitcnt lgkmcnt(0)
	s_barrier
	s_setprio 1
	s_waitcnt lgkmcnt(0)
	v_mfma_f32_16x16x32_bf16 v[58:61], v[146:149], v[186:189], v[58:61]
	v_mfma_f32_16x16x32_bf16 v[62:65], v[154:157], v[186:189], v[62:65]
	v_mfma_f32_16x16x32_bf16 v[42:45], v[146:149], v[194:197], v[42:45]
	v_mfma_f32_16x16x32_bf16 v[46:49], v[154:157], v[194:197], v[46:49]
	v_mfma_f32_16x16x32_bf16 v[26:29], v[146:149], v[202:205], v[26:29]
	v_mfma_f32_16x16x32_bf16 v[30:33], v[154:157], v[202:205], v[30:33]
	v_mfma_f32_16x16x32_bf16 v[10:13], v[146:149], v[214:217], v[10:13]
	v_mfma_f32_16x16x32_bf16 v[14:17], v[154:157], v[214:217], v[14:17]
	v_mfma_f32_16x16x32_bf16 v[58:61], v[150:153], v[190:193], v[58:61]
	v_mfma_f32_16x16x32_bf16 v[62:65], v[158:161], v[190:193], v[62:65]
	v_mfma_f32_16x16x32_bf16 v[42:45], v[150:153], v[198:201], v[42:45]
	v_mfma_f32_16x16x32_bf16 v[46:49], v[158:161], v[198:201], v[46:49]
	v_mfma_f32_16x16x32_bf16 v[26:29], v[150:153], v[206:209], v[26:29]
	v_mfma_f32_16x16x32_bf16 v[30:33], v[158:161], v[206:209], v[30:33]
	v_mfma_f32_16x16x32_bf16 v[10:13], v[150:153], v[218:221], v[10:13]
	v_mfma_f32_16x16x32_bf16 v[14:17], v[158:161], v[218:221], v[14:17]
	s_setprio 0
	s_setprio 1
	v_mfma_f32_16x16x32_bf16 v[50:53], v[162:165], v[186:189], v[50:53]
	v_mfma_f32_16x16x32_bf16 v[54:57], v[170:173], v[186:189], v[54:57]
	v_mfma_f32_16x16x32_bf16 v[34:37], v[162:165], v[194:197], v[34:37]
	v_mfma_f32_16x16x32_bf16 v[38:41], v[170:173], v[194:197], v[38:41]
	v_mfma_f32_16x16x32_bf16 v[18:21], v[162:165], v[202:205], v[18:21]
	v_mfma_f32_16x16x32_bf16 v[22:25], v[170:173], v[202:205], v[22:25]
	v_mfma_f32_16x16x32_bf16 v[6:9], v[162:165], v[214:217], v[6:9]
	v_mfma_f32_16x16x32_bf16 v[2:5], v[170:173], v[214:217], v[2:5]
	v_mfma_f32_16x16x32_bf16 v[50:53], v[166:169], v[190:193], v[50:53]
	v_mfma_f32_16x16x32_bf16 v[54:57], v[174:177], v[190:193], v[54:57]
	v_mfma_f32_16x16x32_bf16 v[34:37], v[166:169], v[198:201], v[34:37]
	v_mfma_f32_16x16x32_bf16 v[38:41], v[174:177], v[198:201], v[38:41]
	v_mfma_f32_16x16x32_bf16 v[18:21], v[166:169], v[206:209], v[18:21]
	v_mfma_f32_16x16x32_bf16 v[22:25], v[174:177], v[206:209], v[22:25]
	v_mfma_f32_16x16x32_bf16 v[6:9], v[166:169], v[218:221], v[6:9]
	v_mfma_f32_16x16x32_bf16 v[2:5], v[174:177], v[218:221], v[2:5]
	s_setprio 0
	s_add_i32 s69, s69, 2
	s_add_u32 s6, s6, 0x100
	s_addc_u32 s7, s7, 0
	s_add_u32 s67, s67, 0x100
	s_addc_u32 s68, s68, 0
	s_cmp_gt_u32 s69, 13
	s_barrier
	s_cbranch_scc0 .LBB0_286
	v_lshl_add_u32 v166, s4, 8, v1
	v_or_b32_e32 v164, 16, v166
	v_ashrrev_i32_e32 v165, 31, v164
	v_or_b32_e32 v158, 32, v166
	v_lshlrev_b64 v[146:147], 6, v[164:165]
	v_ashrrev_i32_e32 v159, 31, v158
	v_lshl_add_u64 v[146:147], v[138:139], 0, v[146:147]
	v_lshlrev_b64 v[148:149], 6, v[158:159]
	v_ashrrev_i32_e32 v167, 31, v166
	v_lshl_add_u64 v[148:149], v[138:139], 0, v[148:149]
	global_load_dwordx4 v[160:163], v[146:147], off
	global_load_dwordx4 v[168:171], v[148:149], off
	v_lshlrev_b64 v[146:147], 6, v[166:167]
	v_lshl_add_u64 v[146:147], v[138:139], 0, v[146:147]
	global_load_dwordx4 v[172:175], v[146:147], off
	v_or_b32_e32 v156, 48, v166
	v_ashrrev_i32_e32 v157, 31, v156
	v_add_u32_e32 v154, 0x80, v166
	v_lshlrev_b64 v[146:147], 6, v[156:157]
	v_ashrrev_i32_e32 v155, 31, v154
	v_add_u32_e32 v150, 0x90, v166
	v_lshl_add_u64 v[146:147], v[138:139], 0, v[146:147]
	v_lshlrev_b64 v[148:149], 6, v[154:155]
	v_ashrrev_i32_e32 v151, 31, v150
	v_lshl_add_u64 v[148:149], v[138:139], 0, v[148:149]
	global_load_dwordx4 v[176:179], v[146:147], off
	global_load_dwordx4 v[186:189], v[148:149], off
	v_lshlrev_b64 v[146:147], 6, v[150:151]
	v_lshl_add_u64 v[146:147], v[138:139], 0, v[146:147]
	global_load_dwordx4 v[190:193], v[146:147], off
	v_add_u32_e32 v148, 0xa0, v166
	v_ashrrev_i32_e32 v149, 31, v148
	v_lshlrev_b64 v[146:147], 6, v[148:149]
	v_lshl_add_u64 v[146:147], v[138:139], 0, v[146:147]
	global_load_dwordx4 v[194:197], v[146:147], off
	v_add_u32_e32 v146, 0xb0, v166
	v_ashrrev_i32_e32 v147, 31, v146
	v_lshlrev_b64 v[152:153], 6, v[146:147]
	v_lshl_add_u64 v[152:153], v[138:139], 0, v[152:153]
	global_load_dwordx4 v[198:201], v[152:153], off
	s_and_b64 vcc, exec, s[14:15]
	s_cbranch_vccz .LBB0_289
	s_barrier

; #define PG8_STAGE(bufoff, gbase, voff) do { _Pragma("unroll") for (int _i = 0; _i < 2; ++_i) \
;     __builtin_amdgcn_global_load_lds((const unsigned*)((const char*)(gbase) + (voff)[_i]), (PG8_LAS unsigned*)(lds + (bufoff) + ldsw + _i * 8192), 16, 0, 0); } while (0)
; #define PG8_LDA(dst, b, h) do { _Pragma("unroll") for (int m = 0; m < 4; ++m) _Pragma("unroll") for (int k = 0; k < 2; ++k) dst[m][k] = *(const PG8_LAS bf16x8*)(lds + PG8_SA(b, h) + aoff + m * 2048 + k * 1024); } while (0)
; #define PG8_LDB(dst, b, h) do { _Pragma("unroll") for (int n = 0; n < 2; ++n) _Pragma("unroll") for (int k = 0; k < 2; ++k) dst[n][k] = *(const PG8_LAS bf16x8*)(lds + PG8_SB(b, h) + boff + n * 2048 + k * 1024); } while (0)
; #define PG8_WAIT_V(n) asm volatile("s_waitcnt vmcnt(" #n ")" ::: "memory")
; #define PG8_WAIT_L(n) asm volatile("s_waitcnt lgkmcnt(" #n ")" ::: "memory")
; #define PG8_BAR __builtin_amdgcn_s_barrier()
; template <class Epi, class Sched>
; DI void gemm_phase(PG8_LAS unsigned char* lds, const Gemm g, const Sched& S, const Epi& E) {
;     ...
;     for (int t = 0; t < nt; t += 2) {
;       const bool last = (t == nt - 2);
;       const char* a1 = cA + (size_t)(t + 1) * kstep;
;       const char* a2 = last ? nA : cA + (size_t)(t + 2) * kstep; const char* b2 = last ? nB : cB + (size_t)(t + 2) * kstep;
;       const char* a3 = a2 + kstep; const char* b3 = b2 + kstep;
;       PG8_LDB(B0, 0, 0); PG8_LDB(B1, 0, 1); PG8_SCHED; PG8_LDA(At, 0, 0); PG8_STAGE(PG8_SA(1, 1), a1 + hstepA, voffA);
;       PG8_WAIT_V(8); PG8_WAIT_L(0); PG8_BAR; PG8_MMA(0, 0, At, B0); PG8_MMA(0, 1, At, B1); PG8_BAR; PG8_SCHED;
;       PG8_LDA(At, 0, 1); PG8_STAGE(PG8_SB(0, 0), b2, voffB); PG8_STAGE(PG8_SB(0, 1), b2 + hstepB, voffB); PG8_STAGE(PG8_SA(0, 0), a2, voffA);
;       PG8_WAIT_V(8); PG8_WAIT_L(0); PG8_BAR; PG8_MMA(1, 0, At, B0); PG8_MMA(1, 1, At, B1); PG8_BAR; PG8_SCHED;
;       PG8_LDB(B0, 1, 0); PG8_LDB(B1, 1, 1); PG8_SCHED; PG8_LDA(At, 1, 0); PG8_STAGE(PG8_SA(0, 1), a2 + hstepA, voffA);
;       PG8_WAIT_V(8); PG8_WAIT_L(0); PG8_BAR; PG8_MMA(0, 0, At, B0); PG8_MMA(0, 1, At, B1); PG8_BAR; PG8_SCHED;
;       PG8_LDA(At, 1, 1); PG8_STAGE(PG8_SB(1, 0), b3, voffB); PG8_STAGE(PG8_SB(1, 1), b3 + hstepB, voffB); PG8_STAGE(PG8_SA(1, 0), a3, voffA);
;       PG8_WAIT_V(8); PG8_WAIT_L(0); PG8_BAR; PG8_MMA(1, 0, At, B0); PG8_MMA(1, 1, At, B1); PG8_BAR; PG8_SCHED;
;     }
.LBB0_563:
	ds_read_b128 v[128:131], v167
	ds_read_b128 v[132:135], v167 offset:1024
	ds_read_b128 v[136:139], v167 offset:2048
	ds_read_b128 v[140:143], v167 offset:3072
	ds_read_b128 v[158:161], v168
	ds_read_b128 v[162:165], v168 offset:1024
	ds_read_b128 v[172:175], v168 offset:2048
	ds_read_b128 v[176:179], v168 offset:3072
	s_add_u32 s16, s28, 0xfffc0080
	s_addc_u32 s17, s29, -1
	s_cmp_eq_u32 s70, 12
	s_cselect_b32 s35, s19, s17
	s_cselect_b32 s34, s27, s16
	s_cselect_b32 s31, s15, s69
	s_cselect_b32 s30, s67, s68
	v_lshl_add_u64 v[214:215], s[28:29], 0, v[154:155]
	s_add_i32 m0, s3, 0xc000
	ds_read_b128 v[180:183], v169
	ds_read_b128 v[184:187], v169 offset:1024
	ds_read_b128 v[188:191], v169 offset:2048
	ds_read_b128 v[192:195], v169 offset:3072
	ds_read_b128 v[196:199], v169 offset:4096
	ds_read_b128 v[200:203], v169 offset:5120
	ds_read_b128 v[204:207], v169 offset:6144
	ds_read_b128 v[208:211], v169 offset:7168
	global_load_lds_dwordx4 v[214:215], off
	v_lshl_add_u64 v[214:215], s[28:29], 0, v[156:157]
	s_add_i32 m0, s3, 0xe000
	s_nop 0
	global_load_lds_dwordx4 v[214:215], off
	s_waitcnt vmcnt(8)
	s_waitcnt lgkmcnt(0)
	s_barrier
	s_setprio 1
	s_waitcnt lgkmcnt(0)
	v_mfma_f32_16x16x32_bf16 v[124:127], v[128:131], v[180:183], v[124:127]
	v_mfma_f32_16x16x32_bf16 v[120:123], v[136:139], v[180:183], v[120:123]
	v_mfma_f32_16x16x32_bf16 v[108:111], v[128:131], v[188:191], v[108:111]
	v_mfma_f32_16x16x32_bf16 v[104:107], v[136:139], v[188:191], v[104:107]
	v_mfma_f32_16x16x32_bf16 v[92:95], v[128:131], v[196:199], v[92:95]
	v_mfma_f32_16x16x32_bf16 v[88:91], v[136:139], v[196:199], v[88:91]
	v_mfma_f32_16x16x32_bf16 v[76:79], v[128:131], v[204:207], v[76:79]
	v_mfma_f32_16x16x32_bf16 v[72:75], v[136:139], v[204:207], v[72:75]
	v_mfma_f32_16x16x32_bf16 v[124:127], v[132:135], v[184:187], v[124:127]
	v_mfma_f32_16x16x32_bf16 v[120:123], v[140:143], v[184:187], v[120:123]
	v_mfma_f32_16x16x32_bf16 v[108:111], v[132:135], v[192:195], v[108:111]
	v_mfma_f32_16x16x32_bf16 v[104:107], v[140:143], v[192:195], v[104:107]
	v_mfma_f32_16x16x32_bf16 v[92:95], v[132:135], v[200:203], v[92:95]
	v_mfma_f32_16x16x32_bf16 v[88:91], v[140:143], v[200:203], v[88:91]
	v_mfma_f32_16x16x32_bf16 v[76:79], v[132:135], v[208:211], v[76:79]
	v_mfma_f32_16x16x32_bf16 v[72:75], v[140:143], v[208:211], v[72:75]
	s_setprio 0
	s_setprio 1
	v_mfma_f32_16x16x32_bf16 v[116:119], v[158:161], v[180:183], v[116:119]
	v_mfma_f32_16x16x32_bf16 v[112:115], v[172:175], v[180:183], v[112:115]
	v_mfma_f32_16x16x32_bf16 v[100:103], v[158:161], v[188:191], v[100:103]
	v_mfma_f32_16x16x32_bf16 v[96:99], v[172:175], v[188:191], v[96:99]
	v_mfma_f32_16x16x32_bf16 v[84:87], v[158:161], v[196:199], v[84:87]
	v_mfma_f32_16x16x32_bf16 v[80:83], v[172:175], v[196:199], v[80:83]
	v_mfma_f32_16x16x32_bf16 v[68:71], v[158:161], v[204:207], v[68:71]
	v_mfma_f32_16x16x32_bf16 v[64:67], v[172:175], v[204:207], v[64:67]
	v_mfma_f32_16x16x32_bf16 v[116:119], v[162:165], v[184:187], v[116:119]
	v_mfma_f32_16x16x32_bf16 v[112:115], v[176:179], v[184:187], v[112:115]
	v_mfma_f32_16x16x32_bf16 v[100:103], v[162:165], v[192:195], v[100:103]
	v_mfma_f32_16x16x32_bf16 v[96:99], v[176:179], v[192:195], v[96:99]
	v_mfma_f32_16x16x32_bf16 v[84:87], v[162:165], v[200:203], v[84:87]
	v_mfma_f32_16x16x32_bf16 v[80:83], v[176:179], v[200:203], v[80:83]
	v_mfma_f32_16x16x32_bf16 v[68:71], v[162:165], v[208:211], v[68:71]
	v_mfma_f32_16x16x32_bf16 v[64:67], v[176:179], v[208:211], v[64:67]
	s_setprio 0
	s_barrier
	s_add_i32 s16, s55, s2
	v_lshl_add_u64 v[214:215], s[30:31], 0, v[146:147]
	s_mov_b32 m0, s16
	ds_read_b128 v[180:183], v169 offset:16384
	ds_read_b128 v[184:187], v169 offset:17408
	ds_read_b128 v[188:191], v169 offset:18432
	ds_read_b128 v[192:195], v169 offset:19456
	ds_read_b128 v[196:199], v169 offset:20480
	ds_read_b128 v[200:203], v169 offset:21504
	ds_read_b128 v[204:207], v169 offset:22528
	ds_read_b128 v[208:211], v169 offset:23552
	global_load_lds_dwordx4 v[214:215], off
	s_add_i32 m0, s16, 0x2000
	s_add_u32 s16, s30, 0x40000
	v_lshl_add_u64 v[216:217], s[30:31], 0, v[150:151]
	s_addc_u32 s17, s31, 0
	s_add_i32 s33, s64, s2
	global_load_lds_dwordx4 v[216:217], off
	v_lshl_add_u64 v[218:219], s[16:17], 0, v[146:147]
	s_mov_b32 m0, s33
	v_lshl_add_u64 v[220:221], s[34:35], 0, v[148:149]
	global_load_lds_dwordx4 v[218:219], off
	v_lshl_add_u64 v[218:219], s[16:17], 0, v[150:151]
	s_add_i32 m0, s33, 0x2000
	s_nop 0
	global_load_lds_dwordx4 v[218:219], off
	v_lshl_add_u64 v[218:219], s[34:35], 0, v[144:145]
	s_mov_b32 m0, s3
	s_nop 0
	global_load_lds_dwordx4 v[218:219], off
	s_mov_b32 m0, s36
	s_nop 0
	global_load_lds_dwordx4 v[220:221], off
	s_waitcnt vmcnt(8)
	s_waitcnt lgkmcnt(0)
	s_barrier
; #define PG8_STAGE(bufoff, gbase, voff) do { _Pragma("unroll") for (int _i = 0; _i < 2; ++_i) \
;     __builtin_amdgcn_global_load_lds((const unsigned*)((const char*)(gbase) + (voff)[_i]), (PG8_LAS unsigned*)(lds + (bufoff) + ldsw + _i * 8192), 16, 0, 0); } while (0)
; #define PG8_LDA(dst, b, h) do { _Pragma("unroll") for (int m = 0; m < 4; ++m) _Pragma("unroll") for (int k = 0; k < 2; ++k) dst[m][k] = *(const PG8_LAS bf16x8*)(lds + PG8_SA(b, h) + aoff + m * 2048 + k * 1024); } while (0)
; #define PG8_LDB(dst, b, h) do { _Pragma("unroll") for (int n = 0; n < 2; ++n) _Pragma("unroll") for (int k = 0; k < 2; ++k) dst[n][k] = *(const PG8_LAS bf16x8*)(lds + PG8_SB(b, h) + boff + n * 2048 + k * 1024); } while (0)
; #define PG8_MMA(ai, bj, At, Bt) do { __builtin_amdgcn_s_setprio(1); _Pragma("unroll") for (int m = 0; m < 4; ++m) _Pragma("unroll") for (int n = 0; n < 2; ++n) _Pragma("unroll") for (int k = 0; k < 2; ++k) \
;     acc[ai][bj][m][n] = __builtin_amdgcn_mfma_f32_16x16x32_bf16(Bt[n][k], At[m][k], acc[ai][bj][m][n], 0, 0, 0); __builtin_amdgcn_s_setprio(0); } while (0)
; #define PG8_WAIT_V(n) asm volatile("s_waitcnt vmcnt(" #n ")" ::: "memory")
; #define PG8_WAIT_L(n) asm volatile("s_waitcnt lgkmcnt(" #n ")" ::: "memory")
; #define PG8_BAR __builtin_amdgcn_s_barrier()
; #define PG8_SCHED __builtin_amdgcn_sched_barrier(0)
; template <class Epi, class Sched>
; DI void gemm_phase(PG8_LAS unsigned char* lds, const Gemm g, const Sched& S, const Epi& E) {
;     ...
;       PG8_WAIT_V(8); PG8_WAIT_L(0); PG8_BAR; PG8_MMA(0, 0, At, B0); PG8_MMA(0, 1, At, B1); PG8_BAR; PG8_SCHED;
;       PG8_LDA(At, 0, 1); PG8_STAGE(PG8_SB(0, 0), b2, voffB); PG8_STAGE(PG8_SB(0, 1), b2 + hstepB, voffB); PG8_STAGE(PG8_SA(0, 0), a2, voffA);
;       PG8_WAIT_V(8); PG8_WAIT_L(0); PG8_BAR; PG8_MMA(1, 0, At, B0); PG8_MMA(1, 1, At, B1); PG8_BAR; PG8_SCHED;
;       PG8_LDB(B0, 1, 0); PG8_LDB(B1, 1, 1); PG8_SCHED; PG8_LDA(At, 1, 0); PG8_STAGE(PG8_SA(0, 1), a2 + hstepA, voffA);
;       PG8_WAIT_V(8); PG8_WAIT_L(0); PG8_BAR; PG8_MMA(0, 0, At, B0); PG8_MMA(0, 1, At, B1); PG8_BAR; PG8_SCHED;
;       PG8_LDA(At, 1, 1); PG8_STAGE(PG8_SB(1, 0), b3, voffB); PG8_STAGE(PG8_SB(1, 1), b3 + hstepB, voffB); PG8_STAGE(PG8_SA(1, 0), a3, voffA);
	s_setprio 1
	s_waitcnt lgkmcnt(0)
	v_mfma_f32_16x16x32_bf16 v[60:63], v[128:131], v[180:183], v[60:63]
	v_mfma_f32_16x16x32_bf16 v[56:59], v[136:139], v[180:183], v[56:59]
	v_mfma_f32_16x16x32_bf16 v[44:47], v[128:131], v[188:191], v[44:47]
	v_mfma_f32_16x16x32_bf16 v[40:43], v[136:139], v[188:191], v[40:43]
	v_mfma_f32_16x16x32_bf16 v[28:31], v[128:131], v[196:199], v[28:31]
	v_mfma_f32_16x16x32_bf16 v[24:27], v[136:139], v[196:199], v[24:27]
	v_mfma_f32_16x16x32_bf16 v[12:15], v[128:131], v[204:207], v[12:15]
	v_mfma_f32_16x16x32_bf16 v[8:11], v[136:139], v[204:207], v[8:11]
	v_mfma_f32_16x16x32_bf16 v[60:63], v[132:135], v[184:187], v[60:63]
	v_mfma_f32_16x16x32_bf16 v[56:59], v[140:143], v[184:187], v[56:59]
	v_mfma_f32_16x16x32_bf16 v[44:47], v[132:135], v[192:195], v[44:47]
	v_mfma_f32_16x16x32_bf16 v[40:43], v[140:143], v[192:195], v[40:43]
	v_mfma_f32_16x16x32_bf16 v[28:31], v[132:135], v[200:203], v[28:31]
	v_mfma_f32_16x16x32_bf16 v[24:27], v[140:143], v[200:203], v[24:27]
	v_mfma_f32_16x16x32_bf16 v[12:15], v[132:135], v[208:211], v[12:15]
	v_mfma_f32_16x16x32_bf16 v[8:11], v[140:143], v[208:211], v[8:11]
	s_setprio 0
	s_setprio 1
	v_mfma_f32_16x16x32_bf16 v[52:55], v[158:161], v[180:183], v[52:55]
	v_mfma_f32_16x16x32_bf16 v[48:51], v[172:175], v[180:183], v[48:51]
	v_mfma_f32_16x16x32_bf16 v[36:39], v[158:161], v[188:191], v[36:39]
	v_mfma_f32_16x16x32_bf16 v[32:35], v[172:175], v[188:191], v[32:35]
	v_mfma_f32_16x16x32_bf16 v[20:23], v[158:161], v[196:199], v[20:23]
	v_mfma_f32_16x16x32_bf16 v[16:19], v[172:175], v[196:199], v[16:19]
	v_mfma_f32_16x16x32_bf16 v[4:7], v[158:161], v[204:207], v[4:7]
	v_mfma_f32_16x16x32_bf16 v[0:3], v[172:175], v[204:207], v[0:3]
	v_mfma_f32_16x16x32_bf16 v[52:55], v[162:165], v[184:187], v[52:55]
	v_mfma_f32_16x16x32_bf16 v[48:51], v[176:179], v[184:187], v[48:51]
	v_mfma_f32_16x16x32_bf16 v[36:39], v[162:165], v[192:195], v[36:39]
	v_mfma_f32_16x16x32_bf16 v[32:35], v[176:179], v[192:195], v[32:35]
	v_mfma_f32_16x16x32_bf16 v[20:23], v[162:165], v[200:203], v[20:23]
	v_mfma_f32_16x16x32_bf16 v[16:19], v[176:179], v[200:203], v[16:19]
	v_mfma_f32_16x16x32_bf16 v[4:7], v[162:165], v[208:211], v[4:7]
	v_mfma_f32_16x16x32_bf16 v[0:3], v[176:179], v[208:211], v[0:3]
	s_setprio 0
	s_barrier
	s_add_i32 s33, s41, 0x110
	v_add_u32_e32 v140, s33, v166
	ds_read_b128 v[128:131], v140
	ds_read_b128 v[132:135], v140 offset:1024
	ds_read_b128 v[136:139], v140 offset:2048
	ds_read_b128 v[140:143], v140 offset:3072
	ds_read_b128 v[158:161], v171
	ds_read_b128 v[162:165], v171 offset:1024
	ds_read_b128 v[172:175], v171 offset:2048
	ds_read_b128 v[176:179], v171 offset:3072
	s_add_u32 s16, s34, 0x40000
	s_addc_u32 s17, s35, 0
	s_mov_b32 m0, s37
	v_lshl_add_u64 v[222:223], s[16:17], 0, v[144:145]
	ds_read_b128 v[180:183], v169 offset:32768
	ds_read_b128 v[184:187], v169 offset:33792
	ds_read_b128 v[188:191], v169 offset:34816
	ds_read_b128 v[192:195], v169 offset:35840
	ds_read_b128 v[196:199], v169 offset:36864
	ds_read_b128 v[200:203], v169 offset:37888
	ds_read_b128 v[204:207], v169 offset:38912
	ds_read_b128 v[208:211], v169 offset:39936
	global_load_lds_dwordx4 v[222:223], off
	v_lshl_add_u64 v[222:223], s[16:17], 0, v[148:149]
	s_mov_b32 m0, s38
	s_nop 0
	global_load_lds_dwordx4 v[222:223], off
	s_waitcnt vmcnt(8)
	s_waitcnt lgkmcnt(0)
	s_barrier
	s_setprio 1
	s_waitcnt lgkmcnt(0)
	v_mfma_f32_16x16x32_bf16 v[124:127], v[128:131], v[180:183], v[124:127]
	v_mfma_f32_16x16x32_bf16 v[120:123], v[136:139], v[180:183], v[120:123]
	v_mfma_f32_16x16x32_bf16 v[108:111], v[128:131], v[188:191], v[108:111]
	v_mfma_f32_16x16x32_bf16 v[104:107], v[136:139], v[188:191], v[104:107]
	v_mfma_f32_16x16x32_bf16 v[92:95], v[128:131], v[196:199], v[92:95]
	v_mfma_f32_16x16x32_bf16 v[88:91], v[136:139], v[196:199], v[88:91]
	v_mfma_f32_16x16x32_bf16 v[76:79], v[128:131], v[204:207], v[76:79]
	v_mfma_f32_16x16x32_bf16 v[72:75], v[136:139], v[204:207], v[72:75]
	v_mfma_f32_16x16x32_bf16 v[124:127], v[132:135], v[184:187], v[124:127]
	v_mfma_f32_16x16x32_bf16 v[120:123], v[140:143], v[184:187], v[120:123]
	v_mfma_f32_16x16x32_bf16 v[108:111], v[132:135], v[192:195], v[108:111]
	v_mfma_f32_16x16x32_bf16 v[104:107], v[140:143], v[192:195], v[104:107]
	v_mfma_f32_16x16x32_bf16 v[92:95], v[132:135], v[200:203], v[92:95]
	v_mfma_f32_16x16x32_bf16 v[88:91], v[140:143], v[200:203], v[88:91]
	v_mfma_f32_16x16x32_bf16 v[76:79], v[132:135], v[208:211], v[76:79]
	v_mfma_f32_16x16x32_bf16 v[72:75], v[140:143], v[208:211], v[72:75]
	s_setprio 0
	s_setprio 1
	v_mfma_f32_16x16x32_bf16 v[116:119], v[158:161], v[180:183], v[116:119]
	v_mfma_f32_16x16x32_bf16 v[112:115], v[172:175], v[180:183], v[112:115]
	v_mfma_f32_16x16x32_bf16 v[100:103], v[158:161], v[188:191], v[100:103]
	v_mfma_f32_16x16x32_bf16 v[96:99], v[172:175], v[188:191], v[96:99]
	v_mfma_f32_16x16x32_bf16 v[84:87], v[158:161], v[196:199], v[84:87]
	v_mfma_f32_16x16x32_bf16 v[80:83], v[172:175], v[196:199], v[80:83]
	v_mfma_f32_16x16x32_bf16 v[68:71], v[158:161], v[204:207], v[68:71]
	v_mfma_f32_16x16x32_bf16 v[64:67], v[172:175], v[204:207], v[64:67]
	v_mfma_f32_16x16x32_bf16 v[116:119], v[162:165], v[184:187], v[116:119]
	v_mfma_f32_16x16x32_bf16 v[112:115], v[176:179], v[184:187], v[112:115]
	v_mfma_f32_16x16x32_bf16 v[100:103], v[162:165], v[192:195], v[100:103]
	v_mfma_f32_16x16x32_bf16 v[96:99], v[176:179], v[192:195], v[96:99]
	v_mfma_f32_16x16x32_bf16 v[84:87], v[162:165], v[200:203], v[84:87]
	v_mfma_f32_16x16x32_bf16 v[80:83], v[176:179], v[200:203], v[80:83]
	v_mfma_f32_16x16x32_bf16 v[68:71], v[162:165], v[208:211], v[68:71]
	v_mfma_f32_16x16x32_bf16 v[64:67], v[176:179], v[208:211], v[64:67]
	s_setprio 0
	s_barrier
; #define PG8_STAGE(bufoff, gbase, voff) do { _Pragma("unroll") for (int _i = 0; _i < 2; ++_i) \
;     __builtin_amdgcn_global_load_lds((const unsigned*)((const char*)(gbase) + (voff)[_i]), (PG8_LAS unsigned*)(lds + (bufoff) + ldsw + _i * 8192), 16, 0, 0); } while (0)
; #define PG8_LDA(dst, b, h) do { _Pragma("unroll") for (int m = 0; m < 4; ++m) _Pragma("unroll") for (int k = 0; k < 2; ++k) dst[m][k] = *(const PG8_LAS bf16x8*)(lds + PG8_SA(b, h) + aoff + m * 2048 + k * 1024); } while (0)
; #define PG8_LDB(dst, b, h) do { _Pragma("unroll") for (int n = 0; n < 2; ++n) _Pragma("unroll") for (int k = 0; k < 2; ++k) dst[n][k] = *(const PG8_LAS bf16x8*)(lds + PG8_SB(b, h) + boff + n * 2048 + k * 1024); } while (0)
; #define PG8_WAIT_V(n) asm volatile("s_waitcnt vmcnt(" #n ")" ::: "memory")
;   DI void operator()(const f32x4 (&acc)[2][2][4][2], const Unit& u, int wr, int wc, int fr, int fq) const {
;     ...
;     RES_LD(0)
; template <class Epi, class Sched>
; DI void gemm_phase(PG8_LAS unsigned char* lds, const Gemm g, const Sched& S, const Epi& E) {
;     ...
;     for (int t = 0; t < nt; t += 2) {
;       const bool last = (t == nt - 2);
;       const char* a1 = cA + (size_t)(t + 1) * kstep;
;       const char* a2 = last ? nA : cA + (size_t)(t + 2) * kstep; const char* b2 = last ? nB : cB + (size_t)(t + 2) * kstep;
;       const char* a3 = a2 + kstep; const char* b3 = b2 + kstep;
;       PG8_LDB(B0, 0, 0); PG8_LDB(B1, 0, 1); PG8_SCHED; PG8_LDA(At, 0, 0); PG8_STAGE(PG8_SA(1, 1), a1 + hstepA, voffA);
;       PG8_WAIT_V(8); PG8_WAIT_L(0); PG8_BAR; PG8_MMA(0, 0, At, B0); PG8_MMA(0, 1, At, B1); PG8_BAR; PG8_SCHED;
;       PG8_LDA(At, 0, 1); PG8_STAGE(PG8_SB(0, 0), b2, voffB); PG8_STAGE(PG8_SB(0, 1), b2 + hstepB, voffB); PG8_STAGE(PG8_SA(0, 0), a2, voffA);
;       PG8_WAIT_V(8); PG8_WAIT_L(0); PG8_BAR; PG8_MMA(1, 0, At, B0); PG8_MMA(1, 1, At, B1); PG8_BAR; PG8_SCHED;
;       PG8_LDB(B0, 1, 0); PG8_LDB(B1, 1, 1); PG8_SCHED; PG8_LDA(At, 1, 0); PG8_STAGE(PG8_SA(0, 1), a2 + hstepA, voffA);
;       PG8_WAIT_V(8); PG8_WAIT_L(0); PG8_BAR; PG8_MMA(0, 0, At, B0); PG8_MMA(0, 1, At, B1); PG8_BAR; PG8_SCHED;
;       PG8_LDA(At, 1, 1); PG8_STAGE(PG8_SB(1, 0), b3, voffB); PG8_STAGE(PG8_SB(1, 1), b3 + hstepB, voffB); PG8_STAGE(PG8_SA(1, 0), a3, voffA);
;       PG8_WAIT_V(8); PG8_WAIT_L(0); PG8_BAR; PG8_MMA(1, 0, At, B0); PG8_MMA(1, 1, At, B1); PG8_BAR; PG8_SCHED;
;     }
;     if (wr == 0) PG8_BAR;
	s_add_i32 s16, s33, s2
	v_lshl_add_u64 v[214:215], v[214:215], 0, s[8:9]
	s_mov_b32 m0, s16
	ds_read_b128 v[180:183], v169 offset:49152
	ds_read_b128 v[184:187], v169 offset:50176
	ds_read_b128 v[188:191], v169 offset:51200
	ds_read_b128 v[192:195], v169 offset:52224
	ds_read_b128 v[196:199], v169 offset:53248
	ds_read_b128 v[200:203], v169 offset:54272
	ds_read_b128 v[204:207], v169 offset:55296
	ds_read_b128 v[208:211], v169 offset:56320
	global_load_lds_dwordx4 v[214:215], off
	s_add_i32 m0, s16, 0x2000
	s_add_u32 s16, s30, 0x40080
	v_lshl_add_u64 v[214:215], v[216:217], 0, s[8:9]
	s_addc_u32 s17, s31, 0
	s_add_i32 s30, s65, s2
	global_load_lds_dwordx4 v[214:215], off
	v_lshl_add_u64 v[214:215], s[16:17], 0, v[146:147]
	s_mov_b32 m0, s30
	s_nop 0
	global_load_lds_dwordx4 v[214:215], off
	v_lshl_add_u64 v[214:215], s[16:17], 0, v[150:151]
	s_add_i32 m0, s30, 0x2000
	s_nop 0
	global_load_lds_dwordx4 v[214:215], off
	v_lshl_add_u64 v[214:215], v[218:219], 0, s[8:9]
	s_mov_b32 m0, s4
	s_nop 0
	global_load_lds_dwordx4 v[214:215], off
	v_lshl_add_u64 v[214:215], v[220:221], 0, s[8:9]
	s_mov_b32 m0, s5
	s_nop 0
	global_load_lds_dwordx4 v[214:215], off
	s_waitcnt vmcnt(8)
	s_waitcnt lgkmcnt(0)
	s_barrier
	s_setprio 1
	s_waitcnt lgkmcnt(0)
	v_mfma_f32_16x16x32_bf16 v[60:63], v[128:131], v[180:183], v[60:63]
	v_mfma_f32_16x16x32_bf16 v[56:59], v[136:139], v[180:183], v[56:59]
	v_mfma_f32_16x16x32_bf16 v[44:47], v[128:131], v[188:191], v[44:47]
	v_mfma_f32_16x16x32_bf16 v[40:43], v[136:139], v[188:191], v[40:43]
	v_mfma_f32_16x16x32_bf16 v[28:31], v[128:131], v[196:199], v[28:31]
	v_mfma_f32_16x16x32_bf16 v[24:27], v[136:139], v[196:199], v[24:27]
	v_mfma_f32_16x16x32_bf16 v[12:15], v[128:131], v[204:207], v[12:15]
	v_mfma_f32_16x16x32_bf16 v[8:11], v[136:139], v[204:207], v[8:11]
	v_mfma_f32_16x16x32_bf16 v[60:63], v[132:135], v[184:187], v[60:63]
	v_mfma_f32_16x16x32_bf16 v[56:59], v[140:143], v[184:187], v[56:59]
	v_mfma_f32_16x16x32_bf16 v[44:47], v[132:135], v[192:195], v[44:47]
	v_mfma_f32_16x16x32_bf16 v[40:43], v[140:143], v[192:195], v[40:43]
	v_mfma_f32_16x16x32_bf16 v[28:31], v[132:135], v[200:203], v[28:31]
	v_mfma_f32_16x16x32_bf16 v[24:27], v[140:143], v[200:203], v[24:27]
	v_mfma_f32_16x16x32_bf16 v[12:15], v[132:135], v[208:211], v[12:15]
	v_mfma_f32_16x16x32_bf16 v[8:11], v[140:143], v[208:211], v[8:11]
	s_setprio 0
	s_setprio 1
	v_mfma_f32_16x16x32_bf16 v[52:55], v[158:161], v[180:183], v[52:55]
	v_mfma_f32_16x16x32_bf16 v[48:51], v[172:175], v[180:183], v[48:51]
	v_mfma_f32_16x16x32_bf16 v[36:39], v[158:161], v[188:191], v[36:39]
	v_mfma_f32_16x16x32_bf16 v[32:35], v[172:175], v[188:191], v[32:35]
	v_mfma_f32_16x16x32_bf16 v[20:23], v[158:161], v[196:199], v[20:23]
	v_mfma_f32_16x16x32_bf16 v[16:19], v[172:175], v[196:199], v[16:19]
	v_mfma_f32_16x16x32_bf16 v[4:7], v[158:161], v[204:207], v[4:7]
	v_mfma_f32_16x16x32_bf16 v[0:3], v[172:175], v[204:207], v[0:3]
	v_mfma_f32_16x16x32_bf16 v[52:55], v[162:165], v[184:187], v[52:55]
	v_mfma_f32_16x16x32_bf16 v[48:51], v[176:179], v[184:187], v[48:51]
	v_mfma_f32_16x16x32_bf16 v[36:39], v[162:165], v[192:195], v[36:39]
	v_mfma_f32_16x16x32_bf16 v[32:35], v[176:179], v[192:195], v[32:35]
	v_mfma_f32_16x16x32_bf16 v[20:23], v[162:165], v[200:203], v[20:23]
	v_mfma_f32_16x16x32_bf16 v[16:19], v[176:179], v[200:203], v[16:19]
	v_mfma_f32_16x16x32_bf16 v[4:7], v[162:165], v[208:211], v[4:7]
	v_mfma_f32_16x16x32_bf16 v[0:3], v[176:179], v[208:211], v[0:3]
	s_setprio 0
	s_add_i32 s70, s70, 2
	s_add_u32 s28, s28, 0x100
	s_addc_u32 s29, s29, 0
	s_add_u32 s68, s68, 0x100
	s_addc_u32 s69, s69, 0
	s_cmp_gt_u32 s70, 13
	s_barrier
	s_cbranch_scc0 .LBB0_563
	v_lshl_add_u32 v164, s26, 8, v153
	v_ashrrev_i32_e32 v165, 31, v164
	s_lshl_b32 s16, s12, 8
	v_lshlrev_b64 v[128:129], 10, v[164:165]
	s_ashr_i32 s17, s16, 31
	v_lshl_add_u64 v[186:187], v[128:129], 0, s[16:17]
	v_or_b32_e32 v186, v186, v152
	v_lshl_add_u64 v[162:163], v[186:187], 2, s[44:45]
	s_mov_b64 s[16:17], 0x10000
	v_add_co_u32_e32 v130, vcc, s39, v162
	global_load_dwordx4 v[158:161], v[162:163], off offset:16
	global_load_dwordx4 v[174:177], v[162:163], off
	global_load_dwordx4 v[178:181], v[162:163], off offset:528
	global_load_dwordx4 v[182:185], v[162:163], off offset:512
	v_lshl_add_u64 v[128:129], v[162:163], 0, s[16:17]
	v_addc_co_u32_e32 v131, vcc, 0, v163, vcc
	s_mov_b64 s[16:17], 0x10200
	global_load_dwordx4 v[140:143], v[130:131], off
	global_load_dwordx4 v[136:139], v[128:129], off offset:16
	v_lshl_add_u64 v[128:129], v[162:163], 0, s[16:17]
	global_load_dwordx4 v[132:135], v[130:131], off offset:512
	s_nop 0
	global_load_dwordx4 v[128:131], v[128:129], off offset:16
	s_and_b64 vcc, exec, s[10:11]
	s_cbranch_vccz .LBB0_566
	s_barrier

; #define PG8_STAGE(bufoff, gbase, voff) do { _Pragma("unroll") for (int _i = 0; _i < 2; ++_i) \
;     __builtin_amdgcn_global_load_lds((const unsigned*)((const char*)(gbase) + (voff)[_i]), (PG8_LAS unsigned*)(lds + (bufoff) + ldsw + _i * 8192), 16, 0, 0); } while (0)
; #define PG8_LDA(dst, b, h) do { _Pragma("unroll") for (int m = 0; m < 4; ++m) _Pragma("unroll") for (int k = 0; k < 2; ++k) dst[m][k] = *(const PG8_LAS bf16x8*)(lds + PG8_SA(b, h) + aoff + m * 2048 + k * 1024); } while (0)
; #define PG8_LDB(dst, b, h) do { _Pragma("unroll") for (int n = 0; n < 2; ++n) _Pragma("unroll") for (int k = 0; k < 2; ++k) dst[n][k] = *(const PG8_LAS bf16x8*)(lds + PG8_SB(b, h) + boff + n * 2048 + k * 1024); } while (0)
; #define PG8_WAIT_V(n) asm volatile("s_waitcnt vmcnt(" #n ")" ::: "memory")
; #define PG8_WAIT_L(n) asm volatile("s_waitcnt lgkmcnt(" #n ")" ::: "memory")
; #define PG8_BAR __builtin_amdgcn_s_barrier()
; template <class Epi, class Sched>
; DI void gemm_phase(PG8_LAS unsigned char* lds, const Gemm g, const Sched& S, const Epi& E) {
;     ...
;     for (int t = 0; t < nt; t += 2) {
;       const bool last = (t == nt - 2);
;       const char* a1 = cA + (size_t)(t + 1) * kstep;
;       const char* a2 = last ? nA : cA + (size_t)(t + 2) * kstep; const char* b2 = last ? nB : cB + (size_t)(t + 2) * kstep;
;       const char* a3 = a2 + kstep; const char* b3 = b2 + kstep;
;       PG8_LDB(B0, 0, 0); PG8_LDB(B1, 0, 1); PG8_SCHED; PG8_LDA(At, 0, 0); PG8_STAGE(PG8_SA(1, 1), a1 + hstepA, voffA);
;       PG8_WAIT_V(8); PG8_WAIT_L(0); PG8_BAR; PG8_MMA(0, 0, At, B0); PG8_MMA(0, 1, At, B1); PG8_BAR; PG8_SCHED;
;       PG8_LDA(At, 0, 1); PG8_STAGE(PG8_SB(0, 0), b2, voffB); PG8_STAGE(PG8_SB(0, 1), b2 + hstepB, voffB); PG8_STAGE(PG8_SA(0, 0), a2, voffA);
;       PG8_WAIT_V(8); PG8_WAIT_L(0); PG8_BAR; PG8_MMA(1, 0, At, B0); PG8_MMA(1, 1, At, B1); PG8_BAR; PG8_SCHED;
;       PG8_LDB(B0, 1, 0); PG8_LDB(B1, 1, 1); PG8_SCHED; PG8_LDA(At, 1, 0); PG8_STAGE(PG8_SA(0, 1), a2 + hstepA, voffA);
;       PG8_WAIT_V(8); PG8_WAIT_L(0); PG8_BAR; PG8_MMA(0, 0, At, B0); PG8_MMA(0, 1, At, B1); PG8_BAR; PG8_SCHED;
;       PG8_LDA(At, 1, 1); PG8_STAGE(PG8_SB(1, 0), b3, voffB); PG8_STAGE(PG8_SB(1, 1), b3 + hstepB, voffB); PG8_STAGE(PG8_SA(1, 0), a3, voffA);
;       PG8_WAIT_V(8); PG8_WAIT_L(0); PG8_BAR; PG8_MMA(1, 0, At, B0); PG8_MMA(1, 1, At, B1); PG8_BAR; PG8_SCHED;
;     }
.LBB0_647:
	ds_read_b128 v[144:147], v157
	ds_read_b128 v[148:151], v157 offset:1024
	ds_read_b128 v[174:177], v157 offset:2048
	ds_read_b128 v[178:181], v157 offset:3072
	ds_read_b128 v[182:185], v161
	ds_read_b128 v[186:189], v161 offset:1024
	ds_read_b128 v[190:193], v161 offset:2048
	ds_read_b128 v[194:197], v161 offset:3072
	s_add_u32 s16, s6, 0xfffc0080
	s_addc_u32 s17, s7, -1
	s_cmp_eq_u32 s68, 12
	s_cselect_b32 s37, s1, s17
	s_cselect_b32 s36, s25, s16
	s_cselect_b32 s35, s23, s67
	s_cselect_b32 s34, s65, s66
	v_lshl_add_u64 v[154:155], s[6:7], 0, v[140:141]
	s_add_i32 m0, s21, 0xc000
	ds_read_b128 v[198:201], v165
	ds_read_b128 v[202:205], v165 offset:1024
	ds_read_b128 v[206:209], v165 offset:2048
	ds_read_b128 v[214:217], v165 offset:3072
	ds_read_b128 v[218:221], v165 offset:4096
	ds_read_b128 v[222:225], v165 offset:5120
	ds_read_b128 v[226:229], v165 offset:6144
	ds_read_b128 v[230:233], v165 offset:7168
	global_load_lds_dwordx4 v[154:155], off
	v_lshl_add_u64 v[154:155], s[6:7], 0, v[142:143]
	s_add_i32 m0, s21, 0xe000
	s_nop 0
	global_load_lds_dwordx4 v[154:155], off
	s_waitcnt vmcnt(8)
	s_waitcnt lgkmcnt(0)
	s_barrier
	s_setprio 1
	s_waitcnt lgkmcnt(0)
	v_mfma_f32_16x16x32_bf16 v[124:127], v[144:147], v[198:201], v[124:127]
	v_mfma_f32_16x16x32_bf16 v[120:123], v[174:177], v[198:201], v[120:123]
	v_mfma_f32_16x16x32_bf16 v[108:111], v[144:147], v[206:209], v[108:111]
	v_mfma_f32_16x16x32_bf16 v[104:107], v[174:177], v[206:209], v[104:107]
	v_mfma_f32_16x16x32_bf16 v[92:95], v[144:147], v[218:221], v[92:95]
	v_mfma_f32_16x16x32_bf16 v[88:91], v[174:177], v[218:221], v[88:91]
	v_mfma_f32_16x16x32_bf16 v[76:79], v[144:147], v[226:229], v[76:79]
	v_mfma_f32_16x16x32_bf16 v[72:75], v[174:177], v[226:229], v[72:75]
	v_mfma_f32_16x16x32_bf16 v[124:127], v[148:151], v[202:205], v[124:127]
	v_mfma_f32_16x16x32_bf16 v[120:123], v[178:181], v[202:205], v[120:123]
	v_mfma_f32_16x16x32_bf16 v[108:111], v[148:151], v[214:217], v[108:111]
	v_mfma_f32_16x16x32_bf16 v[104:107], v[178:181], v[214:217], v[104:107]
	v_mfma_f32_16x16x32_bf16 v[92:95], v[148:151], v[222:225], v[92:95]
	v_mfma_f32_16x16x32_bf16 v[88:91], v[178:181], v[222:225], v[88:91]
	v_mfma_f32_16x16x32_bf16 v[76:79], v[148:151], v[230:233], v[76:79]
	v_mfma_f32_16x16x32_bf16 v[72:75], v[178:181], v[230:233], v[72:75]
	s_setprio 0
	s_setprio 1
	v_mfma_f32_16x16x32_bf16 v[116:119], v[182:185], v[198:201], v[116:119]
	v_mfma_f32_16x16x32_bf16 v[112:115], v[190:193], v[198:201], v[112:115]
	v_mfma_f32_16x16x32_bf16 v[100:103], v[182:185], v[206:209], v[100:103]
	v_mfma_f32_16x16x32_bf16 v[96:99], v[190:193], v[206:209], v[96:99]
	v_mfma_f32_16x16x32_bf16 v[84:87], v[182:185], v[218:221], v[84:87]
	v_mfma_f32_16x16x32_bf16 v[80:83], v[190:193], v[218:221], v[80:83]
	v_mfma_f32_16x16x32_bf16 v[68:71], v[182:185], v[226:229], v[68:71]
	v_mfma_f32_16x16x32_bf16 v[64:67], v[190:193], v[226:229], v[64:67]
	v_mfma_f32_16x16x32_bf16 v[116:119], v[186:189], v[202:205], v[116:119]
	v_mfma_f32_16x16x32_bf16 v[112:115], v[194:197], v[202:205], v[112:115]
	v_mfma_f32_16x16x32_bf16 v[100:103], v[186:189], v[214:217], v[100:103]
	v_mfma_f32_16x16x32_bf16 v[96:99], v[194:197], v[214:217], v[96:99]
	v_mfma_f32_16x16x32_bf16 v[84:87], v[186:189], v[222:225], v[84:87]
	v_mfma_f32_16x16x32_bf16 v[80:83], v[194:197], v[222:225], v[80:83]
	v_mfma_f32_16x16x32_bf16 v[68:71], v[186:189], v[230:233], v[68:71]
	v_mfma_f32_16x16x32_bf16 v[64:67], v[194:197], v[230:233], v[64:67]
	s_setprio 0
	s_barrier
	s_add_i32 s16, s39, s2
	v_lshl_add_u64 v[154:155], s[34:35], 0, v[132:133]
	s_mov_b32 m0, s16
	ds_read_b128 v[198:201], v165 offset:16384
	ds_read_b128 v[202:205], v165 offset:17408
	ds_read_b128 v[206:209], v165 offset:18432
	ds_read_b128 v[214:217], v165 offset:19456
	ds_read_b128 v[218:221], v165 offset:20480
	ds_read_b128 v[222:225], v165 offset:21504
	ds_read_b128 v[226:229], v165 offset:22528
	ds_read_b128 v[230:233], v165 offset:23552
	global_load_lds_dwordx4 v[154:155], off
	s_add_i32 m0, s16, 0x2000
	s_add_u32 s16, s34, 0x40000
	v_lshl_add_u64 v[158:159], s[34:35], 0, v[128:129]
	s_addc_u32 s17, s35, 0
	s_add_i32 s33, s40, s2
	global_load_lds_dwordx4 v[158:159], off
	v_lshl_add_u64 v[162:163], s[16:17], 0, v[132:133]
	s_mov_b32 m0, s33
	v_lshl_add_u64 v[166:167], s[36:37], 0, v[130:131]
	global_load_lds_dwordx4 v[162:163], off
	v_lshl_add_u64 v[162:163], s[16:17], 0, v[128:129]
	s_add_i32 m0, s33, 0x2000
	s_nop 0
	global_load_lds_dwordx4 v[162:163], off
	v_lshl_add_u64 v[162:163], s[36:37], 0, v[134:135]
	s_mov_b32 m0, s21
	s_nop 0
	global_load_lds_dwordx4 v[162:163], off
	s_mov_b32 m0, s4
	s_nop 0
	global_load_lds_dwordx4 v[166:167], off
	s_waitcnt vmcnt(8)
	s_waitcnt lgkmcnt(0)
	s_barrier
; #define PG8_STAGE(bufoff, gbase, voff) do { _Pragma("unroll") for (int _i = 0; _i < 2; ++_i) \
;     __builtin_amdgcn_global_load_lds((const unsigned*)((const char*)(gbase) + (voff)[_i]), (PG8_LAS unsigned*)(lds + (bufoff) + ldsw + _i * 8192), 16, 0, 0); } while (0)
; #define PG8_LDA(dst, b, h) do { _Pragma("unroll") for (int m = 0; m < 4; ++m) _Pragma("unroll") for (int k = 0; k < 2; ++k) dst[m][k] = *(const PG8_LAS bf16x8*)(lds + PG8_SA(b, h) + aoff + m * 2048 + k * 1024); } while (0)
; #define PG8_LDB(dst, b, h) do { _Pragma("unroll") for (int n = 0; n < 2; ++n) _Pragma("unroll") for (int k = 0; k < 2; ++k) dst[n][k] = *(const PG8_LAS bf16x8*)(lds + PG8_SB(b, h) + boff + n * 2048 + k * 1024); } while (0)
; #define PG8_MMA(ai, bj, At, Bt) do { __builtin_amdgcn_s_setprio(1); _Pragma("unroll") for (int m = 0; m < 4; ++m) _Pragma("unroll") for (int n = 0; n < 2; ++n) _Pragma("unroll") for (int k = 0; k < 2; ++k) \
;     acc[ai][bj][m][n] = __builtin_amdgcn_mfma_f32_16x16x32_bf16(Bt[n][k], At[m][k], acc[ai][bj][m][n], 0, 0, 0); __builtin_amdgcn_s_setprio(0); } while (0)
; #define PG8_WAIT_V(n) asm volatile("s_waitcnt vmcnt(" #n ")" ::: "memory")
; #define PG8_WAIT_L(n) asm volatile("s_waitcnt lgkmcnt(" #n ")" ::: "memory")
; #define PG8_BAR __builtin_amdgcn_s_barrier()
; #define PG8_SCHED __builtin_amdgcn_sched_barrier(0)
; template <class Epi, class Sched>
; DI void gemm_phase(PG8_LAS unsigned char* lds, const Gemm g, const Sched& S, const Epi& E) {
;     ...
;       PG8_WAIT_V(8); PG8_WAIT_L(0); PG8_BAR; PG8_MMA(0, 0, At, B0); PG8_MMA(0, 1, At, B1); PG8_BAR; PG8_SCHED;
;       PG8_LDA(At, 0, 1); PG8_STAGE(PG8_SB(0, 0), b2, voffB); PG8_STAGE(PG8_SB(0, 1), b2 + hstepB, voffB); PG8_STAGE(PG8_SA(0, 0), a2, voffA);
;       PG8_WAIT_V(8); PG8_WAIT_L(0); PG8_BAR; PG8_MMA(1, 0, At, B0); PG8_MMA(1, 1, At, B1); PG8_BAR; PG8_SCHED;
;       PG8_LDB(B0, 1, 0); PG8_LDB(B1, 1, 1); PG8_SCHED; PG8_LDA(At, 1, 0); PG8_STAGE(PG8_SA(0, 1), a2 + hstepA, voffA);
;       PG8_WAIT_V(8); PG8_WAIT_L(0); PG8_BAR; PG8_MMA(0, 0, At, B0); PG8_MMA(0, 1, At, B1); PG8_BAR; PG8_SCHED;
;       PG8_LDA(At, 1, 1); PG8_STAGE(PG8_SB(1, 0), b3, voffB); PG8_STAGE(PG8_SB(1, 1), b3 + hstepB, voffB); PG8_STAGE(PG8_SA(1, 0), a3, voffA);
	s_setprio 1
	s_waitcnt lgkmcnt(0)
	v_mfma_f32_16x16x32_bf16 v[60:63], v[144:147], v[198:201], v[60:63]
	v_mfma_f32_16x16x32_bf16 v[56:59], v[174:177], v[198:201], v[56:59]
	v_mfma_f32_16x16x32_bf16 v[44:47], v[144:147], v[206:209], v[44:47]
	v_mfma_f32_16x16x32_bf16 v[40:43], v[174:177], v[206:209], v[40:43]
	v_mfma_f32_16x16x32_bf16 v[28:31], v[144:147], v[218:221], v[28:31]
	v_mfma_f32_16x16x32_bf16 v[24:27], v[174:177], v[218:221], v[24:27]
	v_mfma_f32_16x16x32_bf16 v[12:15], v[144:147], v[226:229], v[12:15]
	v_mfma_f32_16x16x32_bf16 v[8:11], v[174:177], v[226:229], v[8:11]
	v_mfma_f32_16x16x32_bf16 v[60:63], v[148:151], v[202:205], v[60:63]
	v_mfma_f32_16x16x32_bf16 v[56:59], v[178:181], v[202:205], v[56:59]
	v_mfma_f32_16x16x32_bf16 v[44:47], v[148:151], v[214:217], v[44:47]
	v_mfma_f32_16x16x32_bf16 v[40:43], v[178:181], v[214:217], v[40:43]
	v_mfma_f32_16x16x32_bf16 v[28:31], v[148:151], v[222:225], v[28:31]
	v_mfma_f32_16x16x32_bf16 v[24:27], v[178:181], v[222:225], v[24:27]
	v_mfma_f32_16x16x32_bf16 v[12:15], v[148:151], v[230:233], v[12:15]
	v_mfma_f32_16x16x32_bf16 v[8:11], v[178:181], v[230:233], v[8:11]
	s_setprio 0
	s_setprio 1
	v_mfma_f32_16x16x32_bf16 v[52:55], v[182:185], v[198:201], v[52:55]
	v_mfma_f32_16x16x32_bf16 v[48:51], v[190:193], v[198:201], v[48:51]
	v_mfma_f32_16x16x32_bf16 v[36:39], v[182:185], v[206:209], v[36:39]
	v_mfma_f32_16x16x32_bf16 v[32:35], v[190:193], v[206:209], v[32:35]
	v_mfma_f32_16x16x32_bf16 v[20:23], v[182:185], v[218:221], v[20:23]
	v_mfma_f32_16x16x32_bf16 v[16:19], v[190:193], v[218:221], v[16:19]
	v_mfma_f32_16x16x32_bf16 v[4:7], v[182:185], v[226:229], v[4:7]
	v_mfma_f32_16x16x32_bf16 v[0:3], v[190:193], v[226:229], v[0:3]
	v_mfma_f32_16x16x32_bf16 v[52:55], v[186:189], v[202:205], v[52:55]
	v_mfma_f32_16x16x32_bf16 v[48:51], v[194:197], v[202:205], v[48:51]
	v_mfma_f32_16x16x32_bf16 v[36:39], v[186:189], v[214:217], v[36:39]
	v_mfma_f32_16x16x32_bf16 v[32:35], v[194:197], v[214:217], v[32:35]
	v_mfma_f32_16x16x32_bf16 v[20:23], v[186:189], v[222:225], v[20:23]
	v_mfma_f32_16x16x32_bf16 v[16:19], v[194:197], v[222:225], v[16:19]
	v_mfma_f32_16x16x32_bf16 v[4:7], v[186:189], v[230:233], v[4:7]
	v_mfma_f32_16x16x32_bf16 v[0:3], v[194:197], v[230:233], v[0:3]
	s_setprio 0
	s_barrier
	ds_read_b128 v[144:147], v171
	ds_read_b128 v[148:151], v171 offset:1024
	ds_read_b128 v[174:177], v171 offset:2048
	ds_read_b128 v[178:181], v171 offset:3072
	ds_read_b128 v[182:185], v173
	ds_read_b128 v[186:189], v173 offset:1024
	ds_read_b128 v[190:193], v173 offset:2048
	ds_read_b128 v[194:197], v173 offset:3072
	s_add_u32 s16, s36, 0x40000
	s_addc_u32 s17, s37, 0
	s_mov_b32 m0, s5
	v_lshl_add_u64 v[210:211], s[16:17], 0, v[134:135]
	ds_read_b128 v[198:201], v165 offset:32768
	ds_read_b128 v[202:205], v165 offset:33792
	ds_read_b128 v[206:209], v165 offset:34816
	ds_read_b128 v[214:217], v165 offset:35840
	ds_read_b128 v[218:221], v165 offset:36864
	ds_read_b128 v[222:225], v165 offset:37888
	ds_read_b128 v[226:229], v165 offset:38912
	ds_read_b128 v[230:233], v165 offset:39936
	global_load_lds_dwordx4 v[210:211], off
	v_lshl_add_u64 v[210:211], s[16:17], 0, v[130:131]
	s_mov_b32 m0, s18
	s_nop 0
	global_load_lds_dwordx4 v[210:211], off
	s_waitcnt vmcnt(8)
	s_waitcnt lgkmcnt(0)
	s_barrier
	s_setprio 1
	s_waitcnt lgkmcnt(0)
	v_mfma_f32_16x16x32_bf16 v[124:127], v[144:147], v[198:201], v[124:127]
	v_mfma_f32_16x16x32_bf16 v[120:123], v[174:177], v[198:201], v[120:123]
	v_mfma_f32_16x16x32_bf16 v[108:111], v[144:147], v[206:209], v[108:111]
	v_mfma_f32_16x16x32_bf16 v[104:107], v[174:177], v[206:209], v[104:107]
	v_mfma_f32_16x16x32_bf16 v[92:95], v[144:147], v[218:221], v[92:95]
	v_mfma_f32_16x16x32_bf16 v[88:91], v[174:177], v[218:221], v[88:91]
	v_mfma_f32_16x16x32_bf16 v[76:79], v[144:147], v[226:229], v[76:79]
	v_mfma_f32_16x16x32_bf16 v[72:75], v[174:177], v[226:229], v[72:75]
	v_mfma_f32_16x16x32_bf16 v[124:127], v[148:151], v[202:205], v[124:127]
	v_mfma_f32_16x16x32_bf16 v[120:123], v[178:181], v[202:205], v[120:123]
	v_mfma_f32_16x16x32_bf16 v[108:111], v[148:151], v[214:217], v[108:111]
	v_mfma_f32_16x16x32_bf16 v[104:107], v[178:181], v[214:217], v[104:107]
	v_mfma_f32_16x16x32_bf16 v[92:95], v[148:151], v[222:225], v[92:95]
	v_mfma_f32_16x16x32_bf16 v[88:91], v[178:181], v[222:225], v[88:91]
	v_mfma_f32_16x16x32_bf16 v[76:79], v[148:151], v[230:233], v[76:79]
	v_mfma_f32_16x16x32_bf16 v[72:75], v[178:181], v[230:233], v[72:75]
	s_setprio 0
	s_setprio 1
	v_mfma_f32_16x16x32_bf16 v[116:119], v[182:185], v[198:201], v[116:119]
	v_mfma_f32_16x16x32_bf16 v[112:115], v[190:193], v[198:201], v[112:115]
	v_mfma_f32_16x16x32_bf16 v[100:103], v[182:185], v[206:209], v[100:103]
	v_mfma_f32_16x16x32_bf16 v[96:99], v[190:193], v[206:209], v[96:99]
	v_mfma_f32_16x16x32_bf16 v[84:87], v[182:185], v[218:221], v[84:87]
	v_mfma_f32_16x16x32_bf16 v[80:83], v[190:193], v[218:221], v[80:83]
	v_mfma_f32_16x16x32_bf16 v[68:71], v[182:185], v[226:229], v[68:71]
	v_mfma_f32_16x16x32_bf16 v[64:67], v[190:193], v[226:229], v[64:67]
	v_mfma_f32_16x16x32_bf16 v[116:119], v[186:189], v[202:205], v[116:119]
	v_mfma_f32_16x16x32_bf16 v[112:115], v[194:197], v[202:205], v[112:115]
	v_mfma_f32_16x16x32_bf16 v[100:103], v[186:189], v[214:217], v[100:103]
	v_mfma_f32_16x16x32_bf16 v[96:99], v[194:197], v[214:217], v[96:99]
	v_mfma_f32_16x16x32_bf16 v[84:87], v[186:189], v[222:225], v[84:87]
	v_mfma_f32_16x16x32_bf16 v[80:83], v[194:197], v[222:225], v[80:83]
	v_mfma_f32_16x16x32_bf16 v[68:71], v[186:189], v[230:233], v[68:71]
	v_mfma_f32_16x16x32_bf16 v[64:67], v[194:197], v[230:233], v[64:67]
	s_setprio 0
	s_barrier
; #define PG8_STAGE(bufoff, gbase, voff) do { _Pragma("unroll") for (int _i = 0; _i < 2; ++_i) \
;     __builtin_amdgcn_global_load_lds((const unsigned*)((const char*)(gbase) + (voff)[_i]), (PG8_LAS unsigned*)(lds + (bufoff) + ldsw + _i * 8192), 16, 0, 0); } while (0)
; #define PG8_LDA(dst, b, h) do { _Pragma("unroll") for (int m = 0; m < 4; ++m) _Pragma("unroll") for (int k = 0; k < 2; ++k) dst[m][k] = *(const PG8_LAS bf16x8*)(lds + PG8_SA(b, h) + aoff + m * 2048 + k * 1024); } while (0)
; #define PG8_BAR __builtin_amdgcn_s_barrier()
; DI void rows_rstd(float (&rs)[2][4], const float* ps, const Unit& u, int wr, int fr, int fq, int p_lo, int p_hi, float inv_dim) {
;   f32x4 pv[2][4];
; #pragma unroll
;   for (int ai = 0; ai < 2; ++ai)
; #pragma unroll
;     for (int m = 0; m < 4; ++m) pv[ai][m] = *(const f32x4*)(ps + (size_t)(u.pm * BM + ai * HALF + wr * 64 + m * 16 + fr) * 16 + 4 * fq);
; template <class Epi, class Sched>
; DI void gemm_phase(PG8_LAS unsigned char* lds, const Gemm g, const Sched& S, const Epi& E) {
;     ...
;     for (int t = 0; t < nt; t += 2) {
;       const bool last = (t == nt - 2);
;       const char* a1 = cA + (size_t)(t + 1) * kstep;
;       const char* a2 = last ? nA : cA + (size_t)(t + 2) * kstep; const char* b2 = last ? nB : cB + (size_t)(t + 2) * kstep;
;       const char* a3 = a2 + kstep; const char* b3 = b2 + kstep;
;       PG8_LDB(B0, 0, 0); PG8_LDB(B1, 0, 1); PG8_SCHED; PG8_LDA(At, 0, 0); PG8_STAGE(PG8_SA(1, 1), a1 + hstepA, voffA);
;       PG8_WAIT_V(8); PG8_WAIT_L(0); PG8_BAR; PG8_MMA(0, 0, At, B0); PG8_MMA(0, 1, At, B1); PG8_BAR; PG8_SCHED;
;       PG8_LDA(At, 0, 1); PG8_STAGE(PG8_SB(0, 0), b2, voffB); PG8_STAGE(PG8_SB(0, 1), b2 + hstepB, voffB); PG8_STAGE(PG8_SA(0, 0), a2, voffA);
;       PG8_WAIT_V(8); PG8_WAIT_L(0); PG8_BAR; PG8_MMA(1, 0, At, B0); PG8_MMA(1, 1, At, B1); PG8_BAR; PG8_SCHED;
;       PG8_LDB(B0, 1, 0); PG8_LDB(B1, 1, 1); PG8_SCHED; PG8_LDA(At, 1, 0); PG8_STAGE(PG8_SA(0, 1), a2 + hstepA, voffA);
;       PG8_WAIT_V(8); PG8_WAIT_L(0); PG8_BAR; PG8_MMA(0, 0, At, B0); PG8_MMA(0, 1, At, B1); PG8_BAR; PG8_SCHED;
;       PG8_LDA(At, 1, 1); PG8_STAGE(PG8_SB(1, 0), b3, voffB); PG8_STAGE(PG8_SB(1, 1), b3 + hstepB, voffB); PG8_STAGE(PG8_SA(1, 0), a3, voffA);
;       PG8_WAIT_V(8); PG8_WAIT_L(0); PG8_BAR; PG8_MMA(1, 0, At, B0); PG8_MMA(1, 1, At, B1); PG8_BAR; PG8_SCHED;
;     }
;     if (wr == 0) PG8_BAR;
	s_add_i32 s16, s45, s2
	v_lshl_add_u64 v[154:155], v[154:155], 0, s[10:11]
	s_mov_b32 m0, s16
	ds_read_b128 v[198:201], v165 offset:49152
	ds_read_b128 v[202:205], v165 offset:50176
	ds_read_b128 v[206:209], v165 offset:51200
	ds_read_b128 v[214:217], v165 offset:52224
	ds_read_b128 v[218:221], v165 offset:53248
	ds_read_b128 v[222:225], v165 offset:54272
	ds_read_b128 v[226:229], v165 offset:55296
	ds_read_b128 v[230:233], v165 offset:56320
	global_load_lds_dwordx4 v[154:155], off
	s_add_i32 m0, s16, 0x2000
	s_add_u32 s16, s34, 0x40080
	v_lshl_add_u64 v[154:155], v[158:159], 0, s[10:11]
	s_addc_u32 s17, s35, 0
	s_add_i32 s33, s53, s2
	global_load_lds_dwordx4 v[154:155], off
	v_lshl_add_u64 v[154:155], s[16:17], 0, v[132:133]
	s_mov_b32 m0, s33
	s_nop 0
	global_load_lds_dwordx4 v[154:155], off
	v_lshl_add_u64 v[154:155], s[16:17], 0, v[128:129]
	s_add_i32 m0, s33, 0x2000
	s_nop 0
	global_load_lds_dwordx4 v[154:155], off
	v_lshl_add_u64 v[154:155], v[162:163], 0, s[10:11]
	s_mov_b32 m0, s19
	s_nop 0
	global_load_lds_dwordx4 v[154:155], off
	v_lshl_add_u64 v[154:155], v[166:167], 0, s[10:11]
	s_mov_b32 m0, s38
	s_nop 0
	global_load_lds_dwordx4 v[154:155], off
	s_waitcnt vmcnt(8)
	s_waitcnt lgkmcnt(0)
	s_barrier
	s_setprio 1
	s_waitcnt lgkmcnt(0)
	v_mfma_f32_16x16x32_bf16 v[60:63], v[144:147], v[198:201], v[60:63]
	v_mfma_f32_16x16x32_bf16 v[56:59], v[174:177], v[198:201], v[56:59]
	v_mfma_f32_16x16x32_bf16 v[44:47], v[144:147], v[206:209], v[44:47]
	v_mfma_f32_16x16x32_bf16 v[40:43], v[174:177], v[206:209], v[40:43]
	v_mfma_f32_16x16x32_bf16 v[28:31], v[144:147], v[218:221], v[28:31]
	v_mfma_f32_16x16x32_bf16 v[24:27], v[174:177], v[218:221], v[24:27]
	v_mfma_f32_16x16x32_bf16 v[12:15], v[144:147], v[226:229], v[12:15]
	v_mfma_f32_16x16x32_bf16 v[8:11], v[174:177], v[226:229], v[8:11]
	v_mfma_f32_16x16x32_bf16 v[60:63], v[148:151], v[202:205], v[60:63]
	v_mfma_f32_16x16x32_bf16 v[56:59], v[178:181], v[202:205], v[56:59]
	v_mfma_f32_16x16x32_bf16 v[44:47], v[148:151], v[214:217], v[44:47]
	v_mfma_f32_16x16x32_bf16 v[40:43], v[178:181], v[214:217], v[40:43]
	v_mfma_f32_16x16x32_bf16 v[28:31], v[148:151], v[222:225], v[28:31]
	v_mfma_f32_16x16x32_bf16 v[24:27], v[178:181], v[222:225], v[24:27]
	v_mfma_f32_16x16x32_bf16 v[12:15], v[148:151], v[230:233], v[12:15]
	v_mfma_f32_16x16x32_bf16 v[8:11], v[178:181], v[230:233], v[8:11]
	s_setprio 0
	s_setprio 1
	v_mfma_f32_16x16x32_bf16 v[52:55], v[182:185], v[198:201], v[52:55]
	v_mfma_f32_16x16x32_bf16 v[48:51], v[190:193], v[198:201], v[48:51]
	v_mfma_f32_16x16x32_bf16 v[36:39], v[182:185], v[206:209], v[36:39]
	v_mfma_f32_16x16x32_bf16 v[32:35], v[190:193], v[206:209], v[32:35]
	v_mfma_f32_16x16x32_bf16 v[20:23], v[182:185], v[218:221], v[20:23]
	v_mfma_f32_16x16x32_bf16 v[16:19], v[190:193], v[218:221], v[16:19]
	v_mfma_f32_16x16x32_bf16 v[4:7], v[182:185], v[226:229], v[4:7]
	v_mfma_f32_16x16x32_bf16 v[0:3], v[190:193], v[226:229], v[0:3]
	v_mfma_f32_16x16x32_bf16 v[52:55], v[186:189], v[202:205], v[52:55]
	v_mfma_f32_16x16x32_bf16 v[48:51], v[194:197], v[202:205], v[48:51]
	v_mfma_f32_16x16x32_bf16 v[36:39], v[186:189], v[214:217], v[36:39]
	v_mfma_f32_16x16x32_bf16 v[32:35], v[194:197], v[214:217], v[32:35]
	v_mfma_f32_16x16x32_bf16 v[20:23], v[186:189], v[222:225], v[20:23]
	v_mfma_f32_16x16x32_bf16 v[16:19], v[194:197], v[222:225], v[16:19]
	v_mfma_f32_16x16x32_bf16 v[4:7], v[186:189], v[230:233], v[4:7]
	v_mfma_f32_16x16x32_bf16 v[0:3], v[194:197], v[230:233], v[0:3]
	s_setprio 0
	s_add_i32 s68, s68, 2
	s_add_u32 s6, s6, 0x100
	s_addc_u32 s7, s7, 0
	s_add_u32 s66, s66, 0x100
	s_addc_u32 s67, s67, 0
	s_cmp_gt_u32 s68, 13
	s_barrier
	s_cbranch_scc0 .LBB0_647
	v_lshl_add_u32 v166, s0, 8, v153
	v_or_b32_e32 v162, 16, v166
	v_ashrrev_i32_e32 v167, 31, v166
	v_ashrrev_i32_e32 v163, 31, v162
	v_or_b32_e32 v158, 32, v166
	v_lshlrev_b64 v[146:147], 6, v[166:167]
	v_lshlrev_b64 v[144:145], 6, v[162:163]
	v_ashrrev_i32_e32 v159, 31, v158
	v_lshl_add_u64 v[146:147], v[138:139], 0, v[146:147]
	v_or_b32_e32 v154, 48, v166
	v_lshl_add_u64 v[144:145], v[138:139], 0, v[144:145]
	global_load_dwordx4 v[174:177], v[146:147], off
	v_lshlrev_b64 v[146:147], 6, v[158:159]
	v_ashrrev_i32_e32 v155, 31, v154
	v_lshl_add_u64 v[146:147], v[138:139], 0, v[146:147]
	global_load_dwordx4 v[178:181], v[144:145], off
	global_load_dwordx4 v[182:185], v[146:147], off
	v_lshlrev_b64 v[144:145], 6, v[154:155]
	v_lshl_add_u64 v[144:145], v[138:139], 0, v[144:145]
	global_load_dwordx4 v[186:189], v[144:145], off
	v_add_u32_e32 v150, 0x80, v166
	v_ashrrev_i32_e32 v151, 31, v150
	v_lshlrev_b64 v[144:145], 6, v[150:151]
	v_add_u32_e32 v148, 0x90, v166
	v_lshl_add_u64 v[144:145], v[138:139], 0, v[144:145]
	v_ashrrev_i32_e32 v149, 31, v148
	global_load_dwordx4 v[190:193], v[144:145], off
	v_lshlrev_b64 v[144:145], 6, v[148:149]
	v_lshl_add_u64 v[144:145], v[138:139], 0, v[144:145]
	global_load_dwordx4 v[194:197], v[144:145], off
	v_and_b32_e32 v145, 64, v169
	v_add_u32_e32 v144, 0xb0, v166
	v_add_u32_e32 v146, 0xa0, v166
	v_add_u32_e32 v152, 64, v145
	v_ashrrev_i32_e32 v145, 31, v144
	v_ashrrev_i32_e32 v147, 31, v146
	v_lshlrev_b64 v[198:199], 6, v[144:145]
	v_lshlrev_b64 v[200:201], 6, v[146:147]
	v_lshl_add_u64 v[198:199], v[138:139], 0, v[198:199]
	v_lshl_add_u64 v[202:203], v[138:139], 0, v[200:201]
	global_load_dwordx4 v[198:201], v[198:199], off
	s_nop 0
	global_load_dwordx4 v[202:205], v[202:203], off
	s_and_b64 vcc, exec, s[12:13]
	s_cbranch_vccz .LBB0_650
	s_barrier

; #define PG8_STAGE(bufoff, gbase, voff) do { _Pragma("unroll") for (int _i = 0; _i < 2; ++_i) \
;     __builtin_amdgcn_global_load_lds((const unsigned*)((const char*)(gbase) + (voff)[_i]), (PG8_LAS unsigned*)(lds + (bufoff) + ldsw + _i * 8192), 16, 0, 0); } while (0)
; #define PG8_LDA(dst, b, h) do { _Pragma("unroll") for (int m = 0; m < 4; ++m) _Pragma("unroll") for (int k = 0; k < 2; ++k) dst[m][k] = *(const PG8_LAS bf16x8*)(lds + PG8_SA(b, h) + aoff + m * 2048 + k * 1024); } while (0)
; #define PG8_LDB(dst, b, h) do { _Pragma("unroll") for (int n = 0; n < 2; ++n) _Pragma("unroll") for (int k = 0; k < 2; ++k) dst[n][k] = *(const PG8_LAS bf16x8*)(lds + PG8_SB(b, h) + boff + n * 2048 + k * 1024); } while (0)
; #define PG8_WAIT_V(n) asm volatile("s_waitcnt vmcnt(" #n ")" ::: "memory")
; #define PG8_WAIT_L(n) asm volatile("s_waitcnt lgkmcnt(" #n ")" ::: "memory")
; #define PG8_BAR __builtin_amdgcn_s_barrier()
; template <class Epi, class Sched>
; DI void gemm_phase(PG8_LAS unsigned char* lds, const Gemm g, const Sched& S, const Epi& E) {
;     ...
;     for (int t = 0; t < nt; t += 2) {
;       const bool last = (t == nt - 2);
;       const char* a1 = cA + (size_t)(t + 1) * kstep;
;       const char* a2 = last ? nA : cA + (size_t)(t + 2) * kstep; const char* b2 = last ? nB : cB + (size_t)(t + 2) * kstep;
;       const char* a3 = a2 + kstep; const char* b3 = b2 + kstep;
;       PG8_LDB(B0, 0, 0); PG8_LDB(B1, 0, 1); PG8_SCHED; PG8_LDA(At, 0, 0); PG8_STAGE(PG8_SA(1, 1), a1 + hstepA, voffA);
;       PG8_WAIT_V(8); PG8_WAIT_L(0); PG8_BAR; PG8_MMA(0, 0, At, B0); PG8_MMA(0, 1, At, B1); PG8_BAR; PG8_SCHED;
;       PG8_LDA(At, 0, 1); PG8_STAGE(PG8_SB(0, 0), b2, voffB); PG8_STAGE(PG8_SB(0, 1), b2 + hstepB, voffB); PG8_STAGE(PG8_SA(0, 0), a2, voffA);
;       PG8_WAIT_V(8); PG8_WAIT_L(0); PG8_BAR; PG8_MMA(1, 0, At, B0); PG8_MMA(1, 1, At, B1); PG8_BAR; PG8_SCHED;
;       PG8_LDB(B0, 1, 0); PG8_LDB(B1, 1, 1); PG8_SCHED; PG8_LDA(At, 1, 0); PG8_STAGE(PG8_SA(0, 1), a2 + hstepA, voffA);
;       PG8_WAIT_V(8); PG8_WAIT_L(0); PG8_BAR; PG8_MMA(0, 0, At, B0); PG8_MMA(0, 1, At, B1); PG8_BAR; PG8_SCHED;
;       PG8_LDA(At, 1, 1); PG8_STAGE(PG8_SB(1, 0), b3, voffB); PG8_STAGE(PG8_SB(1, 1), b3 + hstepB, voffB); PG8_STAGE(PG8_SA(1, 0), a3, voffA);
;       PG8_WAIT_V(8); PG8_WAIT_L(0); PG8_BAR; PG8_MMA(1, 0, At, B0); PG8_MMA(1, 1, At, B1); PG8_BAR; PG8_SCHED;
;     }
.LBB0_721:
	ds_read_b128 v[128:131], v156
	ds_read_b128 v[132:135], v156 offset:1024
	ds_read_b128 v[150:153], v156 offset:2048
	ds_read_b128 v[162:165], v156 offset:3072
	ds_read_b128 v[166:169], v157
	ds_read_b128 v[170:173], v157 offset:1024
	ds_read_b128 v[174:177], v157 offset:2048
	ds_read_b128 v[178:181], v157 offset:3072
	s_add_u32 s26, s24, 0x100
	s_addc_u32 s27, s25, 0
	s_cmp_eq_u32 s65, 40
	s_cselect_b32 s31, s21, s27
	s_cselect_b32 s30, s20, s26
	s_cselect_b32 s29, s23, s64
	s_cselect_b32 s28, s22, s55
	v_lshl_add_u64 v[210:211], s[24:25], 0, v[146:147]
	s_add_i32 m0, s3, 0xc000
	ds_read_b128 v[182:185], v158
	ds_read_b128 v[186:189], v158 offset:1024
	ds_read_b128 v[190:193], v158 offset:2048
	ds_read_b128 v[194:197], v158 offset:3072
	ds_read_b128 v[198:201], v158 offset:4096
	ds_read_b128 v[202:205], v158 offset:5120
	ds_read_b128 v[206:209], v158 offset:6144
	ds_read_b128 v[214:217], v158 offset:7168
	global_load_lds_dwordx4 v[210:211], off
	v_lshl_add_u64 v[210:211], s[24:25], 0, v[148:149]
	s_add_i32 m0, s3, 0xe000
	s_nop 0
	global_load_lds_dwordx4 v[210:211], off
	s_waitcnt vmcnt(8)
	s_waitcnt lgkmcnt(0)
	s_barrier
	s_setprio 1
	s_waitcnt lgkmcnt(0)
	v_mfma_f32_16x16x32_bf16 v[124:127], v[128:131], v[182:185], v[124:127]
	v_mfma_f32_16x16x32_bf16 v[120:123], v[150:153], v[182:185], v[120:123]
	v_mfma_f32_16x16x32_bf16 v[108:111], v[128:131], v[190:193], v[108:111]
	v_mfma_f32_16x16x32_bf16 v[104:107], v[150:153], v[190:193], v[104:107]
	v_mfma_f32_16x16x32_bf16 v[92:95], v[128:131], v[198:201], v[92:95]
	v_mfma_f32_16x16x32_bf16 v[88:91], v[150:153], v[198:201], v[88:91]
	v_mfma_f32_16x16x32_bf16 v[76:79], v[128:131], v[206:209], v[76:79]
	v_mfma_f32_16x16x32_bf16 v[72:75], v[150:153], v[206:209], v[72:75]
	v_mfma_f32_16x16x32_bf16 v[124:127], v[132:135], v[186:189], v[124:127]
	v_mfma_f32_16x16x32_bf16 v[120:123], v[162:165], v[186:189], v[120:123]
	v_mfma_f32_16x16x32_bf16 v[108:111], v[132:135], v[194:197], v[108:111]
	v_mfma_f32_16x16x32_bf16 v[104:107], v[162:165], v[194:197], v[104:107]
	v_mfma_f32_16x16x32_bf16 v[92:95], v[132:135], v[202:205], v[92:95]
	v_mfma_f32_16x16x32_bf16 v[88:91], v[162:165], v[202:205], v[88:91]
	v_mfma_f32_16x16x32_bf16 v[76:79], v[132:135], v[214:217], v[76:79]
	v_mfma_f32_16x16x32_bf16 v[72:75], v[162:165], v[214:217], v[72:75]
	s_setprio 0
	s_setprio 1
	v_mfma_f32_16x16x32_bf16 v[116:119], v[166:169], v[182:185], v[116:119]
	v_mfma_f32_16x16x32_bf16 v[112:115], v[174:177], v[182:185], v[112:115]
	v_mfma_f32_16x16x32_bf16 v[100:103], v[166:169], v[190:193], v[100:103]
	v_mfma_f32_16x16x32_bf16 v[96:99], v[174:177], v[190:193], v[96:99]
	v_mfma_f32_16x16x32_bf16 v[84:87], v[166:169], v[198:201], v[84:87]
	v_mfma_f32_16x16x32_bf16 v[80:83], v[174:177], v[198:201], v[80:83]
	v_mfma_f32_16x16x32_bf16 v[68:71], v[166:169], v[206:209], v[68:71]
	v_mfma_f32_16x16x32_bf16 v[64:67], v[174:177], v[206:209], v[64:67]
	v_mfma_f32_16x16x32_bf16 v[116:119], v[170:173], v[186:189], v[116:119]
	v_mfma_f32_16x16x32_bf16 v[112:115], v[178:181], v[186:189], v[112:115]
	v_mfma_f32_16x16x32_bf16 v[100:103], v[170:173], v[194:197], v[100:103]
	v_mfma_f32_16x16x32_bf16 v[96:99], v[178:181], v[194:197], v[96:99]
	v_mfma_f32_16x16x32_bf16 v[84:87], v[170:173], v[202:205], v[84:87]
	v_mfma_f32_16x16x32_bf16 v[80:83], v[178:181], v[202:205], v[80:83]
	v_mfma_f32_16x16x32_bf16 v[68:71], v[170:173], v[214:217], v[68:71]
	v_mfma_f32_16x16x32_bf16 v[64:67], v[178:181], v[214:217], v[64:67]
	s_setprio 0
	s_barrier
	s_add_i32 s16, s37, s2
	v_lshl_add_u64 v[210:211], s[28:29], 0, v[138:139]
	s_mov_b32 m0, s16
	ds_read_b128 v[182:185], v158 offset:16384
	ds_read_b128 v[186:189], v158 offset:17408
	ds_read_b128 v[190:193], v158 offset:18432
	ds_read_b128 v[194:197], v158 offset:19456
	ds_read_b128 v[198:201], v158 offset:20480
	ds_read_b128 v[202:205], v158 offset:21504
	ds_read_b128 v[206:209], v158 offset:22528
	ds_read_b128 v[214:217], v158 offset:23552
	global_load_lds_dwordx4 v[210:211], off
	s_add_i32 m0, s16, 0x2000
	s_add_u32 s16, s28, 0xb0000
	v_lshl_add_u64 v[218:219], s[28:29], 0, v[142:143]
	s_addc_u32 s17, s29, 0
	s_add_i32 s24, s38, s2
	global_load_lds_dwordx4 v[218:219], off
	v_lshl_add_u64 v[220:221], s[16:17], 0, v[138:139]
	s_mov_b32 m0, s24
	v_lshl_add_u64 v[222:223], s[30:31], 0, v[140:141]
	global_load_lds_dwordx4 v[220:221], off
	v_lshl_add_u64 v[220:221], s[16:17], 0, v[142:143]
	s_add_i32 m0, s24, 0x2000
	s_nop 0
	global_load_lds_dwordx4 v[220:221], off
	v_lshl_add_u64 v[220:221], s[30:31], 0, v[136:137]
	s_mov_b32 m0, s3
	s_nop 0
	global_load_lds_dwordx4 v[220:221], off
	s_mov_b32 m0, s34
	s_nop 0
	global_load_lds_dwordx4 v[222:223], off
	s_waitcnt vmcnt(8)
	s_waitcnt lgkmcnt(0)
	s_barrier
; #define PG8_STAGE(bufoff, gbase, voff) do { _Pragma("unroll") for (int _i = 0; _i < 2; ++_i) \
;     __builtin_amdgcn_global_load_lds((const unsigned*)((const char*)(gbase) + (voff)[_i]), (PG8_LAS unsigned*)(lds + (bufoff) + ldsw + _i * 8192), 16, 0, 0); } while (0)
; #define PG8_LDA(dst, b, h) do { _Pragma("unroll") for (int m = 0; m < 4; ++m) _Pragma("unroll") for (int k = 0; k < 2; ++k) dst[m][k] = *(const PG8_LAS bf16x8*)(lds + PG8_SA(b, h) + aoff + m * 2048 + k * 1024); } while (0)
; #define PG8_LDB(dst, b, h) do { _Pragma("unroll") for (int n = 0; n < 2; ++n) _Pragma("unroll") for (int k = 0; k < 2; ++k) dst[n][k] = *(const PG8_LAS bf16x8*)(lds + PG8_SB(b, h) + boff + n * 2048 + k * 1024); } while (0)
; #define PG8_MMA(ai, bj, At, Bt) do { __builtin_amdgcn_s_setprio(1); _Pragma("unroll") for (int m = 0; m < 4; ++m) _Pragma("unroll") for (int n = 0; n < 2; ++n) _Pragma("unroll") for (int k = 0; k < 2; ++k) \
;     acc[ai][bj][m][n] = __builtin_amdgcn_mfma_f32_16x16x32_bf16(Bt[n][k], At[m][k], acc[ai][bj][m][n], 0, 0, 0); __builtin_amdgcn_s_setprio(0); } while (0)
; #define PG8_WAIT_V(n) asm volatile("s_waitcnt vmcnt(" #n ")" ::: "memory")
; #define PG8_WAIT_L(n) asm volatile("s_waitcnt lgkmcnt(" #n ")" ::: "memory")
; #define PG8_BAR __builtin_amdgcn_s_barrier()
; #define PG8_SCHED __builtin_amdgcn_sched_barrier(0)
; template <class Epi, class Sched>
; DI void gemm_phase(PG8_LAS unsigned char* lds, const Gemm g, const Sched& S, const Epi& E) {
;     ...
;       PG8_WAIT_V(8); PG8_WAIT_L(0); PG8_BAR; PG8_MMA(0, 0, At, B0); PG8_MMA(0, 1, At, B1); PG8_BAR; PG8_SCHED;
;       PG8_LDA(At, 0, 1); PG8_STAGE(PG8_SB(0, 0), b2, voffB); PG8_STAGE(PG8_SB(0, 1), b2 + hstepB, voffB); PG8_STAGE(PG8_SA(0, 0), a2, voffA);
;       PG8_WAIT_V(8); PG8_WAIT_L(0); PG8_BAR; PG8_MMA(1, 0, At, B0); PG8_MMA(1, 1, At, B1); PG8_BAR; PG8_SCHED;
;       PG8_LDB(B0, 1, 0); PG8_LDB(B1, 1, 1); PG8_SCHED; PG8_LDA(At, 1, 0); PG8_STAGE(PG8_SA(0, 1), a2 + hstepA, voffA);
;       PG8_WAIT_V(8); PG8_WAIT_L(0); PG8_BAR; PG8_MMA(0, 0, At, B0); PG8_MMA(0, 1, At, B1); PG8_BAR; PG8_SCHED;
;       PG8_LDA(At, 1, 1); PG8_STAGE(PG8_SB(1, 0), b3, voffB); PG8_STAGE(PG8_SB(1, 1), b3 + hstepB, voffB); PG8_STAGE(PG8_SA(1, 0), a3, voffA);
	s_setprio 1
	s_waitcnt lgkmcnt(0)
	v_mfma_f32_16x16x32_bf16 v[60:63], v[128:131], v[182:185], v[60:63]
	v_mfma_f32_16x16x32_bf16 v[56:59], v[150:153], v[182:185], v[56:59]
	v_mfma_f32_16x16x32_bf16 v[44:47], v[128:131], v[190:193], v[44:47]
	v_mfma_f32_16x16x32_bf16 v[40:43], v[150:153], v[190:193], v[40:43]
	v_mfma_f32_16x16x32_bf16 v[28:31], v[128:131], v[198:201], v[28:31]
	v_mfma_f32_16x16x32_bf16 v[24:27], v[150:153], v[198:201], v[24:27]
	v_mfma_f32_16x16x32_bf16 v[12:15], v[128:131], v[206:209], v[12:15]
	v_mfma_f32_16x16x32_bf16 v[8:11], v[150:153], v[206:209], v[8:11]
	v_mfma_f32_16x16x32_bf16 v[60:63], v[132:135], v[186:189], v[60:63]
	v_mfma_f32_16x16x32_bf16 v[56:59], v[162:165], v[186:189], v[56:59]
	v_mfma_f32_16x16x32_bf16 v[44:47], v[132:135], v[194:197], v[44:47]
	v_mfma_f32_16x16x32_bf16 v[40:43], v[162:165], v[194:197], v[40:43]
	v_mfma_f32_16x16x32_bf16 v[28:31], v[132:135], v[202:205], v[28:31]
	v_mfma_f32_16x16x32_bf16 v[24:27], v[162:165], v[202:205], v[24:27]
	v_mfma_f32_16x16x32_bf16 v[12:15], v[132:135], v[214:217], v[12:15]
	v_mfma_f32_16x16x32_bf16 v[8:11], v[162:165], v[214:217], v[8:11]
	s_setprio 0
	s_setprio 1
	v_mfma_f32_16x16x32_bf16 v[52:55], v[166:169], v[182:185], v[52:55]
	v_mfma_f32_16x16x32_bf16 v[48:51], v[174:177], v[182:185], v[48:51]
	v_mfma_f32_16x16x32_bf16 v[36:39], v[166:169], v[190:193], v[36:39]
	v_mfma_f32_16x16x32_bf16 v[32:35], v[174:177], v[190:193], v[32:35]
	v_mfma_f32_16x16x32_bf16 v[20:23], v[166:169], v[198:201], v[20:23]
	v_mfma_f32_16x16x32_bf16 v[16:19], v[174:177], v[198:201], v[16:19]
	v_mfma_f32_16x16x32_bf16 v[4:7], v[166:169], v[206:209], v[4:7]
	v_mfma_f32_16x16x32_bf16 v[0:3], v[174:177], v[206:209], v[0:3]
	v_mfma_f32_16x16x32_bf16 v[52:55], v[170:173], v[186:189], v[52:55]
	v_mfma_f32_16x16x32_bf16 v[48:51], v[178:181], v[186:189], v[48:51]
	v_mfma_f32_16x16x32_bf16 v[36:39], v[170:173], v[194:197], v[36:39]
	v_mfma_f32_16x16x32_bf16 v[32:35], v[178:181], v[194:197], v[32:35]
	v_mfma_f32_16x16x32_bf16 v[20:23], v[170:173], v[202:205], v[20:23]
	v_mfma_f32_16x16x32_bf16 v[16:19], v[178:181], v[202:205], v[16:19]
	v_mfma_f32_16x16x32_bf16 v[4:7], v[170:173], v[214:217], v[4:7]
	v_mfma_f32_16x16x32_bf16 v[0:3], v[178:181], v[214:217], v[0:3]
	s_setprio 0
	s_barrier
	s_mov_b32 s16, 0x18000
	s_add_i32 s24, s16, 0x110
	v_add_u32_e32 v161, s24, v155
	ds_read_b128 v[128:131], v161
	ds_read_b128 v[132:135], v161 offset:1024
	ds_read_b128 v[150:153], v161 offset:2048
	ds_read_b128 v[162:165], v161 offset:3072
	ds_read_b128 v[166:169], v160
	ds_read_b128 v[170:173], v160 offset:1024
	ds_read_b128 v[174:177], v160 offset:2048
	ds_read_b128 v[178:181], v160 offset:3072
	s_add_u32 s16, s30, 0xb0000
	s_addc_u32 s17, s31, 0
	s_mov_b32 m0, s18
	v_lshl_add_u64 v[224:225], s[16:17], 0, v[136:137]
	ds_read_b128 v[182:185], v158 offset:32768
	ds_read_b128 v[186:189], v158 offset:33792
	ds_read_b128 v[190:193], v158 offset:34816
	ds_read_b128 v[194:197], v158 offset:35840
	ds_read_b128 v[198:201], v158 offset:36864
	ds_read_b128 v[202:205], v158 offset:37888
	ds_read_b128 v[206:209], v158 offset:38912
	ds_read_b128 v[214:217], v158 offset:39936
	global_load_lds_dwordx4 v[224:225], off
	v_lshl_add_u64 v[224:225], s[16:17], 0, v[140:141]
	s_mov_b32 m0, s19
	s_nop 0
	global_load_lds_dwordx4 v[224:225], off
	s_waitcnt vmcnt(8)
	s_waitcnt lgkmcnt(0)
	s_barrier
	s_setprio 1
	s_waitcnt lgkmcnt(0)
	v_mfma_f32_16x16x32_bf16 v[124:127], v[128:131], v[182:185], v[124:127]
	v_mfma_f32_16x16x32_bf16 v[120:123], v[150:153], v[182:185], v[120:123]
	v_mfma_f32_16x16x32_bf16 v[108:111], v[128:131], v[190:193], v[108:111]
	v_mfma_f32_16x16x32_bf16 v[104:107], v[150:153], v[190:193], v[104:107]
	v_mfma_f32_16x16x32_bf16 v[92:95], v[128:131], v[198:201], v[92:95]
	v_mfma_f32_16x16x32_bf16 v[88:91], v[150:153], v[198:201], v[88:91]
	v_mfma_f32_16x16x32_bf16 v[76:79], v[128:131], v[206:209], v[76:79]
	v_mfma_f32_16x16x32_bf16 v[72:75], v[150:153], v[206:209], v[72:75]
	v_mfma_f32_16x16x32_bf16 v[124:127], v[132:135], v[186:189], v[124:127]
	v_mfma_f32_16x16x32_bf16 v[120:123], v[162:165], v[186:189], v[120:123]
	v_mfma_f32_16x16x32_bf16 v[108:111], v[132:135], v[194:197], v[108:111]
	v_mfma_f32_16x16x32_bf16 v[104:107], v[162:165], v[194:197], v[104:107]
	v_mfma_f32_16x16x32_bf16 v[92:95], v[132:135], v[202:205], v[92:95]
	v_mfma_f32_16x16x32_bf16 v[88:91], v[162:165], v[202:205], v[88:91]
	v_mfma_f32_16x16x32_bf16 v[76:79], v[132:135], v[214:217], v[76:79]
	v_mfma_f32_16x16x32_bf16 v[72:75], v[162:165], v[214:217], v[72:75]
	s_setprio 0
	s_setprio 1
	v_mfma_f32_16x16x32_bf16 v[116:119], v[166:169], v[182:185], v[116:119]
	v_mfma_f32_16x16x32_bf16 v[112:115], v[174:177], v[182:185], v[112:115]
	v_mfma_f32_16x16x32_bf16 v[100:103], v[166:169], v[190:193], v[100:103]
	v_mfma_f32_16x16x32_bf16 v[96:99], v[174:177], v[190:193], v[96:99]
	v_mfma_f32_16x16x32_bf16 v[84:87], v[166:169], v[198:201], v[84:87]
	v_mfma_f32_16x16x32_bf16 v[80:83], v[174:177], v[198:201], v[80:83]
	v_mfma_f32_16x16x32_bf16 v[68:71], v[166:169], v[206:209], v[68:71]
	v_mfma_f32_16x16x32_bf16 v[64:67], v[174:177], v[206:209], v[64:67]
	v_mfma_f32_16x16x32_bf16 v[116:119], v[170:173], v[186:189], v[116:119]
	v_mfma_f32_16x16x32_bf16 v[112:115], v[178:181], v[186:189], v[112:115]
	v_mfma_f32_16x16x32_bf16 v[100:103], v[170:173], v[194:197], v[100:103]
	v_mfma_f32_16x16x32_bf16 v[96:99], v[178:181], v[194:197], v[96:99]
	v_mfma_f32_16x16x32_bf16 v[84:87], v[170:173], v[202:205], v[84:87]
	v_mfma_f32_16x16x32_bf16 v[80:83], v[178:181], v[202:205], v[80:83]
	v_mfma_f32_16x16x32_bf16 v[68:71], v[170:173], v[214:217], v[68:71]
	v_mfma_f32_16x16x32_bf16 v[64:67], v[178:181], v[214:217], v[64:67]
	s_setprio 0
	s_barrier
; #define PG8_STAGE(bufoff, gbase, voff) do { _Pragma("unroll") for (int _i = 0; _i < 2; ++_i) \
;     __builtin_amdgcn_global_load_lds((const unsigned*)((const char*)(gbase) + (voff)[_i]), (PG8_LAS unsigned*)(lds + (bufoff) + ldsw + _i * 8192), 16, 0, 0); } while (0)
; #define PG8_LDA(dst, b, h) do { _Pragma("unroll") for (int m = 0; m < 4; ++m) _Pragma("unroll") for (int k = 0; k < 2; ++k) dst[m][k] = *(const PG8_LAS bf16x8*)(lds + PG8_SA(b, h) + aoff + m * 2048 + k * 1024); } while (0)
; #define PG8_WAIT_V(n) asm volatile("s_waitcnt vmcnt(" #n ")" ::: "memory")
; #define PG8_WAIT_L(n) asm volatile("s_waitcnt lgkmcnt(" #n ")" ::: "memory")
;   DI void operator()(const f32x4 (&acc)[2][2][4][2], const Unit& u, int wr, int wc, int fr, int fq) const {
;     ...
;     RES_LD(0)
; #pragma unroll
;     for (int i = 0; i < 8; ++i) {
;       const int ai = i >> 2, m = i & 3;
;       if (i + 1 < 8) RES_LD(i + 1)
; template <class Epi, class Sched>
; DI void gemm_phase(PG8_LAS unsigned char* lds, const Gemm g, const Sched& S, const Epi& E) {
;     ...
;     for (int t = 0; t < nt; t += 2) {
;       const bool last = (t == nt - 2);
;       const char* a1 = cA + (size_t)(t + 1) * kstep;
;       const char* a2 = last ? nA : cA + (size_t)(t + 2) * kstep; const char* b2 = last ? nB : cB + (size_t)(t + 2) * kstep;
;       const char* a3 = a2 + kstep; const char* b3 = b2 + kstep;
;       PG8_LDB(B0, 0, 0); PG8_LDB(B1, 0, 1); PG8_SCHED; PG8_LDA(At, 0, 0); PG8_STAGE(PG8_SA(1, 1), a1 + hstepA, voffA);
;       PG8_WAIT_V(8); PG8_WAIT_L(0); PG8_BAR; PG8_MMA(0, 0, At, B0); PG8_MMA(0, 1, At, B1); PG8_BAR; PG8_SCHED;
;       PG8_LDA(At, 0, 1); PG8_STAGE(PG8_SB(0, 0), b2, voffB); PG8_STAGE(PG8_SB(0, 1), b2 + hstepB, voffB); PG8_STAGE(PG8_SA(0, 0), a2, voffA);
;       PG8_WAIT_V(8); PG8_WAIT_L(0); PG8_BAR; PG8_MMA(1, 0, At, B0); PG8_MMA(1, 1, At, B1); PG8_BAR; PG8_SCHED;
;       PG8_LDB(B0, 1, 0); PG8_LDB(B1, 1, 1); PG8_SCHED; PG8_LDA(At, 1, 0); PG8_STAGE(PG8_SA(0, 1), a2 + hstepA, voffA);
;       PG8_WAIT_V(8); PG8_WAIT_L(0); PG8_BAR; PG8_MMA(0, 0, At, B0); PG8_MMA(0, 1, At, B1); PG8_BAR; PG8_SCHED;
;       PG8_LDA(At, 1, 1); PG8_STAGE(PG8_SB(1, 0), b3, voffB); PG8_STAGE(PG8_SB(1, 1), b3 + hstepB, voffB); PG8_STAGE(PG8_SA(1, 0), a3, voffA);
;       PG8_WAIT_V(8); PG8_WAIT_L(0); PG8_BAR; PG8_MMA(1, 0, At, B0); PG8_MMA(1, 1, At, B1); PG8_BAR; PG8_SCHED;
;     }
;     if (wr == 0) PG8_BAR;
	s_add_i32 s16, s24, s2
	v_lshl_add_u64 v[210:211], v[210:211], 0, s[10:11]
	s_mov_b32 m0, s16
	ds_read_b128 v[182:185], v158 offset:49152
	ds_read_b128 v[186:189], v158 offset:50176
	ds_read_b128 v[190:193], v158 offset:51200
	ds_read_b128 v[194:197], v158 offset:52224
	ds_read_b128 v[198:201], v158 offset:53248
	ds_read_b128 v[202:205], v158 offset:54272
	ds_read_b128 v[206:209], v158 offset:55296
	ds_read_b128 v[214:217], v158 offset:56320
	global_load_lds_dwordx4 v[210:211], off
	s_add_i32 m0, s16, 0x2000
	s_add_u32 s16, s28, 0xb0080
	v_lshl_add_u64 v[210:211], v[218:219], 0, s[10:11]
	s_addc_u32 s17, s29, 0
	s_add_i32 s24, s39, s2
	global_load_lds_dwordx4 v[210:211], off
	v_lshl_add_u64 v[210:211], s[16:17], 0, v[138:139]
	s_mov_b32 m0, s24
	s_nop 0
	global_load_lds_dwordx4 v[210:211], off
	v_lshl_add_u64 v[210:211], s[16:17], 0, v[142:143]
	s_add_i32 m0, s24, 0x2000
	s_nop 0
	global_load_lds_dwordx4 v[210:211], off
	v_lshl_add_u64 v[210:211], v[220:221], 0, s[10:11]
	s_mov_b32 m0, s5
	s_nop 0
	global_load_lds_dwordx4 v[210:211], off
	v_lshl_add_u64 v[210:211], v[222:223], 0, s[10:11]
	s_mov_b32 m0, s35
	s_nop 0
	global_load_lds_dwordx4 v[210:211], off
	s_waitcnt vmcnt(8)
	s_waitcnt lgkmcnt(0)
	s_barrier
	s_setprio 1
	s_waitcnt lgkmcnt(0)
	v_mfma_f32_16x16x32_bf16 v[60:63], v[128:131], v[182:185], v[60:63]
	v_mfma_f32_16x16x32_bf16 v[56:59], v[150:153], v[182:185], v[56:59]
	v_mfma_f32_16x16x32_bf16 v[44:47], v[128:131], v[190:193], v[44:47]
	v_mfma_f32_16x16x32_bf16 v[40:43], v[150:153], v[190:193], v[40:43]
	v_mfma_f32_16x16x32_bf16 v[28:31], v[128:131], v[198:201], v[28:31]
	v_mfma_f32_16x16x32_bf16 v[24:27], v[150:153], v[198:201], v[24:27]
	v_mfma_f32_16x16x32_bf16 v[12:15], v[128:131], v[206:209], v[12:15]
	v_mfma_f32_16x16x32_bf16 v[8:11], v[150:153], v[206:209], v[8:11]
	v_mfma_f32_16x16x32_bf16 v[60:63], v[132:135], v[186:189], v[60:63]
	v_mfma_f32_16x16x32_bf16 v[56:59], v[162:165], v[186:189], v[56:59]
	v_mfma_f32_16x16x32_bf16 v[44:47], v[132:135], v[194:197], v[44:47]
	v_mfma_f32_16x16x32_bf16 v[40:43], v[162:165], v[194:197], v[40:43]
	v_mfma_f32_16x16x32_bf16 v[28:31], v[132:135], v[202:205], v[28:31]
	v_mfma_f32_16x16x32_bf16 v[24:27], v[162:165], v[202:205], v[24:27]
	v_mfma_f32_16x16x32_bf16 v[12:15], v[132:135], v[214:217], v[12:15]
	v_mfma_f32_16x16x32_bf16 v[8:11], v[162:165], v[214:217], v[8:11]
	s_setprio 0
	s_setprio 1
	v_mfma_f32_16x16x32_bf16 v[52:55], v[166:169], v[182:185], v[52:55]
	v_mfma_f32_16x16x32_bf16 v[48:51], v[174:177], v[182:185], v[48:51]
	v_mfma_f32_16x16x32_bf16 v[36:39], v[166:169], v[190:193], v[36:39]
	v_mfma_f32_16x16x32_bf16 v[32:35], v[174:177], v[190:193], v[32:35]
	v_mfma_f32_16x16x32_bf16 v[20:23], v[166:169], v[198:201], v[20:23]
	v_mfma_f32_16x16x32_bf16 v[16:19], v[174:177], v[198:201], v[16:19]
	v_mfma_f32_16x16x32_bf16 v[4:7], v[166:169], v[206:209], v[4:7]
	v_mfma_f32_16x16x32_bf16 v[0:3], v[174:177], v[206:209], v[0:3]
	v_mfma_f32_16x16x32_bf16 v[52:55], v[170:173], v[186:189], v[52:55]
	v_mfma_f32_16x16x32_bf16 v[48:51], v[178:181], v[186:189], v[48:51]
	v_mfma_f32_16x16x32_bf16 v[36:39], v[170:173], v[194:197], v[36:39]
	v_mfma_f32_16x16x32_bf16 v[32:35], v[178:181], v[194:197], v[32:35]
	v_mfma_f32_16x16x32_bf16 v[20:23], v[170:173], v[202:205], v[20:23]
	v_mfma_f32_16x16x32_bf16 v[16:19], v[178:181], v[202:205], v[16:19]
	v_mfma_f32_16x16x32_bf16 v[4:7], v[170:173], v[214:217], v[4:7]
	v_mfma_f32_16x16x32_bf16 v[0:3], v[178:181], v[214:217], v[0:3]
	s_setprio 0
	s_add_i32 s65, s65, 2
	s_add_u32 s55, s55, 0x100
	s_addc_u32 s64, s64, 0
	s_cmp_gt_u32 s65, 41
	s_mov_b64 s[24:25], s[26:27]
	s_barrier
	s_cbranch_scc0 .LBB0_721
	v_lshl_add_u32 v152, s53, 8, v154
	v_ashrrev_i32_e32 v153, 31, v152
	s_lshl_b32 s16, s45, 8
	v_lshlrev_b64 v[128:129], 11, v[152:153]
	s_ashr_i32 s17, s16, 31
	v_lshl_add_u64 v[128:129], s[50:51], 0, v[128:129]
	v_lshl_add_u64 v[128:129], s[16:17], 1, v[128:129]
	v_lshl_add_u64 v[128:129], v[128:129], 0, s[14:15]
	v_lshl_add_u64 v[150:151], v[128:129], 0, v[144:145]
	s_mov_b32 s16, 0x8000
	v_add_co_u32_e32 v128, vcc, s16, v150
	global_load_dwordx4 v[164:167], v[150:151], off
	global_load_dwordx4 v[168:171], v[150:151], off offset:256
	v_addc_co_u32_e32 v129, vcc, 0, v151, vcc
	global_load_dwordx4 v[132:135], v[128:129], off
	s_nop 0
	global_load_dwordx4 v[128:131], v[128:129], off offset:256
	s_and_b64 vcc, exec, s[12:13]
	s_cbranch_vccz .LBB0_724
	s_barrier

; #define PG8_STAGE(bufoff, gbase, voff) do { _Pragma("unroll") for (int _i = 0; _i < 2; ++_i) \
;     __builtin_amdgcn_global_load_lds((const unsigned*)((const char*)(gbase) + (voff)[_i]), (PG8_LAS unsigned*)(lds + (bufoff) + ldsw + _i * 8192), 16, 0, 0); } while (0)
; #define PG8_LDA(dst, b, h) do { _Pragma("unroll") for (int m = 0; m < 4; ++m) _Pragma("unroll") for (int k = 0; k < 2; ++k) dst[m][k] = *(const PG8_LAS bf16x8*)(lds + PG8_SA(b, h) + aoff + m * 2048 + k * 1024); } while (0)
; #define PG8_LDB(dst, b, h) do { _Pragma("unroll") for (int n = 0; n < 2; ++n) _Pragma("unroll") for (int k = 0; k < 2; ++k) dst[n][k] = *(const PG8_LAS bf16x8*)(lds + PG8_SB(b, h) + boff + n * 2048 + k * 1024); } while (0)
; #define PG8_WAIT_V(n) asm volatile("s_waitcnt vmcnt(" #n ")" ::: "memory")
; #define PG8_WAIT_L(n) asm volatile("s_waitcnt lgkmcnt(" #n ")" ::: "memory")
; #define PG8_BAR __builtin_amdgcn_s_barrier()
; template <class Epi, class Sched>
; DI void gemm_phase(PG8_LAS unsigned char* lds, const Gemm g, const Sched& S, const Epi& E) {
;     ...
;     for (int t = 0; t < nt; t += 2) {
;       const bool last = (t == nt - 2);
;       const char* a1 = cA + (size_t)(t + 1) * kstep;
;       const char* a2 = last ? nA : cA + (size_t)(t + 2) * kstep; const char* b2 = last ? nB : cB + (size_t)(t + 2) * kstep;
;       const char* a3 = a2 + kstep; const char* b3 = b2 + kstep;
;       PG8_LDB(B0, 0, 0); PG8_LDB(B1, 0, 1); PG8_SCHED; PG8_LDA(At, 0, 0); PG8_STAGE(PG8_SA(1, 1), a1 + hstepA, voffA);
;       PG8_WAIT_V(8); PG8_WAIT_L(0); PG8_BAR; PG8_MMA(0, 0, At, B0); PG8_MMA(0, 1, At, B1); PG8_BAR; PG8_SCHED;
;       PG8_LDA(At, 0, 1); PG8_STAGE(PG8_SB(0, 0), b2, voffB); PG8_STAGE(PG8_SB(0, 1), b2 + hstepB, voffB); PG8_STAGE(PG8_SA(0, 0), a2, voffA);
;       PG8_WAIT_V(8); PG8_WAIT_L(0); PG8_BAR; PG8_MMA(1, 0, At, B0); PG8_MMA(1, 1, At, B1); PG8_BAR; PG8_SCHED;
;       PG8_LDB(B0, 1, 0); PG8_LDB(B1, 1, 1); PG8_SCHED; PG8_LDA(At, 1, 0); PG8_STAGE(PG8_SA(0, 1), a2 + hstepA, voffA);
;       PG8_WAIT_V(8); PG8_WAIT_L(0); PG8_BAR; PG8_MMA(0, 0, At, B0); PG8_MMA(0, 1, At, B1); PG8_BAR; PG8_SCHED;
;       PG8_LDA(At, 1, 1); PG8_STAGE(PG8_SB(1, 0), b3, voffB); PG8_STAGE(PG8_SB(1, 1), b3 + hstepB, voffB); PG8_STAGE(PG8_SA(1, 0), a3, voffA);
;       PG8_WAIT_V(8); PG8_WAIT_L(0); PG8_BAR; PG8_MMA(1, 0, At, B0); PG8_MMA(1, 1, At, B1); PG8_BAR; PG8_SCHED;
;     }
.LBB0_807:
	ds_read_b128 v[144:147], v195
	ds_read_b128 v[148:151], v195 offset:1024
	ds_read_b128 v[152:155], v195 offset:2048
	ds_read_b128 v[156:159], v195 offset:3072
	ds_read_b128 v[160:163], v196
	ds_read_b128 v[164:167], v196 offset:1024
	ds_read_b128 v[168:171], v196 offset:2048
	ds_read_b128 v[172:175], v196 offset:3072
	s_add_u32 s16, s10, 0xfffc0080
	s_addc_u32 s17, s11, -1
	s_cmp_eq_u32 s73, 12
	s_cselect_b32 s45, s1, s17
	s_cselect_b32 s44, s9, s16
	s_cselect_b32 s41, s22, s72
	s_cselect_b32 s40, s29, s31
	v_lshl_add_u64 v[192:193], s[10:11], 0, v[138:139]
	s_add_i32 m0, s3, 0xc000
	ds_read_b128 v[176:179], v197
	ds_read_b128 v[180:183], v197 offset:1024
	ds_read_b128 v[184:187], v197 offset:2048
	ds_read_b128 v[188:191], v197 offset:3072
	ds_read_b128 v[202:205], v197 offset:4096
	ds_read_b128 v[206:209], v197 offset:5120
	ds_read_b128 v[214:217], v197 offset:6144
	ds_read_b128 v[218:221], v197 offset:7168
	global_load_lds_dwordx4 v[192:193], off
	v_lshl_add_u64 v[192:193], s[10:11], 0, v[140:141]
	s_add_i32 m0, s3, 0xe000
	s_nop 0
	global_load_lds_dwordx4 v[192:193], off
	s_waitcnt vmcnt(8)
	s_waitcnt lgkmcnt(0)
	s_barrier
	s_setprio 1
	s_waitcnt lgkmcnt(0)
	v_mfma_f32_16x16x32_bf16 v[124:127], v[144:147], v[176:179], v[124:127]
	v_mfma_f32_16x16x32_bf16 v[120:123], v[152:155], v[176:179], v[120:123]
	v_mfma_f32_16x16x32_bf16 v[108:111], v[144:147], v[184:187], v[108:111]
	v_mfma_f32_16x16x32_bf16 v[104:107], v[152:155], v[184:187], v[104:107]
	v_mfma_f32_16x16x32_bf16 v[92:95], v[144:147], v[202:205], v[92:95]
	v_mfma_f32_16x16x32_bf16 v[88:91], v[152:155], v[202:205], v[88:91]
	v_mfma_f32_16x16x32_bf16 v[76:79], v[144:147], v[214:217], v[76:79]
	v_mfma_f32_16x16x32_bf16 v[72:75], v[152:155], v[214:217], v[72:75]
	v_mfma_f32_16x16x32_bf16 v[124:127], v[148:151], v[180:183], v[124:127]
	v_mfma_f32_16x16x32_bf16 v[120:123], v[156:159], v[180:183], v[120:123]
	v_mfma_f32_16x16x32_bf16 v[108:111], v[148:151], v[188:191], v[108:111]
	v_mfma_f32_16x16x32_bf16 v[104:107], v[156:159], v[188:191], v[104:107]
	v_mfma_f32_16x16x32_bf16 v[92:95], v[148:151], v[206:209], v[92:95]
	v_mfma_f32_16x16x32_bf16 v[88:91], v[156:159], v[206:209], v[88:91]
	v_mfma_f32_16x16x32_bf16 v[76:79], v[148:151], v[218:221], v[76:79]
	v_mfma_f32_16x16x32_bf16 v[72:75], v[156:159], v[218:221], v[72:75]
	s_setprio 0
	s_setprio 1
	v_mfma_f32_16x16x32_bf16 v[116:119], v[160:163], v[176:179], v[116:119]
	v_mfma_f32_16x16x32_bf16 v[112:115], v[168:171], v[176:179], v[112:115]
	v_mfma_f32_16x16x32_bf16 v[100:103], v[160:163], v[184:187], v[100:103]
	v_mfma_f32_16x16x32_bf16 v[96:99], v[168:171], v[184:187], v[96:99]
	v_mfma_f32_16x16x32_bf16 v[84:87], v[160:163], v[202:205], v[84:87]
	v_mfma_f32_16x16x32_bf16 v[80:83], v[168:171], v[202:205], v[80:83]
	v_mfma_f32_16x16x32_bf16 v[68:71], v[160:163], v[214:217], v[68:71]
	v_mfma_f32_16x16x32_bf16 v[64:67], v[168:171], v[214:217], v[64:67]
	v_mfma_f32_16x16x32_bf16 v[116:119], v[164:167], v[180:183], v[116:119]
	v_mfma_f32_16x16x32_bf16 v[112:115], v[172:175], v[180:183], v[112:115]
	v_mfma_f32_16x16x32_bf16 v[100:103], v[164:167], v[188:191], v[100:103]
	v_mfma_f32_16x16x32_bf16 v[96:99], v[172:175], v[188:191], v[96:99]
	v_mfma_f32_16x16x32_bf16 v[84:87], v[164:167], v[206:209], v[84:87]
	v_mfma_f32_16x16x32_bf16 v[80:83], v[172:175], v[206:209], v[80:83]
	v_mfma_f32_16x16x32_bf16 v[68:71], v[164:167], v[218:221], v[68:71]
	v_mfma_f32_16x16x32_bf16 v[64:67], v[172:175], v[218:221], v[64:67]
	s_setprio 0
	s_barrier
	s_add_i32 s16, s4, s2
	v_lshl_add_u64 v[192:193], s[40:41], 0, v[130:131]
	s_mov_b32 m0, s16
	ds_read_b128 v[176:179], v197 offset:16384
	ds_read_b128 v[180:183], v197 offset:17408
	ds_read_b128 v[184:187], v197 offset:18432
	ds_read_b128 v[188:191], v197 offset:19456
	ds_read_b128 v[202:205], v197 offset:20480
	ds_read_b128 v[206:209], v197 offset:21504
	ds_read_b128 v[214:217], v197 offset:22528
	ds_read_b128 v[218:221], v197 offset:23552
	global_load_lds_dwordx4 v[192:193], off
	s_add_i32 m0, s16, 0x2000
	s_add_u32 s16, s40, 0x40000
	v_lshl_add_u64 v[210:211], s[40:41], 0, v[134:135]
	s_addc_u32 s17, s41, 0
	s_add_i32 s33, s5, s2
	global_load_lds_dwordx4 v[210:211], off
	v_lshl_add_u64 v[222:223], s[16:17], 0, v[130:131]
	s_mov_b32 m0, s33
	v_lshl_add_u64 v[224:225], s[44:45], 0, v[132:133]
	global_load_lds_dwordx4 v[222:223], off
	v_lshl_add_u64 v[222:223], s[16:17], 0, v[134:135]
	s_add_i32 m0, s33, 0x2000
	s_nop 0
	global_load_lds_dwordx4 v[222:223], off
	v_lshl_add_u64 v[222:223], s[44:45], 0, v[128:129]
	s_mov_b32 m0, s3
	s_nop 0
	global_load_lds_dwordx4 v[222:223], off
	s_mov_b32 m0, s27
	s_nop 0
	global_load_lds_dwordx4 v[224:225], off
	s_waitcnt vmcnt(8)
	s_waitcnt lgkmcnt(0)
	s_barrier
; #define PG8_STAGE(bufoff, gbase, voff) do { _Pragma("unroll") for (int _i = 0; _i < 2; ++_i) \
;     __builtin_amdgcn_global_load_lds((const unsigned*)((const char*)(gbase) + (voff)[_i]), (PG8_LAS unsigned*)(lds + (bufoff) + ldsw + _i * 8192), 16, 0, 0); } while (0)
; #define PG8_LDA(dst, b, h) do { _Pragma("unroll") for (int m = 0; m < 4; ++m) _Pragma("unroll") for (int k = 0; k < 2; ++k) dst[m][k] = *(const PG8_LAS bf16x8*)(lds + PG8_SA(b, h) + aoff + m * 2048 + k * 1024); } while (0)
; #define PG8_LDB(dst, b, h) do { _Pragma("unroll") for (int n = 0; n < 2; ++n) _Pragma("unroll") for (int k = 0; k < 2; ++k) dst[n][k] = *(const PG8_LAS bf16x8*)(lds + PG8_SB(b, h) + boff + n * 2048 + k * 1024); } while (0)
; #define PG8_MMA(ai, bj, At, Bt) do { __builtin_amdgcn_s_setprio(1); _Pragma("unroll") for (int m = 0; m < 4; ++m) _Pragma("unroll") for (int n = 0; n < 2; ++n) _Pragma("unroll") for (int k = 0; k < 2; ++k) \
;     acc[ai][bj][m][n] = __builtin_amdgcn_mfma_f32_16x16x32_bf16(Bt[n][k], At[m][k], acc[ai][bj][m][n], 0, 0, 0); __builtin_amdgcn_s_setprio(0); } while (0)
; #define PG8_WAIT_V(n) asm volatile("s_waitcnt vmcnt(" #n ")" ::: "memory")
; #define PG8_WAIT_L(n) asm volatile("s_waitcnt lgkmcnt(" #n ")" ::: "memory")
; #define PG8_BAR __builtin_amdgcn_s_barrier()
; #define PG8_SCHED __builtin_amdgcn_sched_barrier(0)
; template <class Epi, class Sched>
; DI void gemm_phase(PG8_LAS unsigned char* lds, const Gemm g, const Sched& S, const Epi& E) {
;     ...
;       PG8_WAIT_V(8); PG8_WAIT_L(0); PG8_BAR; PG8_MMA(0, 0, At, B0); PG8_MMA(0, 1, At, B1); PG8_BAR; PG8_SCHED;
;       PG8_LDA(At, 0, 1); PG8_STAGE(PG8_SB(0, 0), b2, voffB); PG8_STAGE(PG8_SB(0, 1), b2 + hstepB, voffB); PG8_STAGE(PG8_SA(0, 0), a2, voffA);
;       PG8_WAIT_V(8); PG8_WAIT_L(0); PG8_BAR; PG8_MMA(1, 0, At, B0); PG8_MMA(1, 1, At, B1); PG8_BAR; PG8_SCHED;
;       PG8_LDB(B0, 1, 0); PG8_LDB(B1, 1, 1); PG8_SCHED; PG8_LDA(At, 1, 0); PG8_STAGE(PG8_SA(0, 1), a2 + hstepA, voffA);
;       PG8_WAIT_V(8); PG8_WAIT_L(0); PG8_BAR; PG8_MMA(0, 0, At, B0); PG8_MMA(0, 1, At, B1); PG8_BAR; PG8_SCHED;
;       PG8_LDA(At, 1, 1); PG8_STAGE(PG8_SB(1, 0), b3, voffB); PG8_STAGE(PG8_SB(1, 1), b3 + hstepB, voffB); PG8_STAGE(PG8_SA(1, 0), a3, voffA);
	s_setprio 1
	s_waitcnt lgkmcnt(0)
	v_mfma_f32_16x16x32_bf16 v[60:63], v[144:147], v[176:179], v[60:63]
	v_mfma_f32_16x16x32_bf16 v[56:59], v[152:155], v[176:179], v[56:59]
	v_mfma_f32_16x16x32_bf16 v[44:47], v[144:147], v[184:187], v[44:47]
	v_mfma_f32_16x16x32_bf16 v[40:43], v[152:155], v[184:187], v[40:43]
	v_mfma_f32_16x16x32_bf16 v[28:31], v[144:147], v[202:205], v[28:31]
	v_mfma_f32_16x16x32_bf16 v[24:27], v[152:155], v[202:205], v[24:27]
	v_mfma_f32_16x16x32_bf16 v[12:15], v[144:147], v[214:217], v[12:15]
	v_mfma_f32_16x16x32_bf16 v[8:11], v[152:155], v[214:217], v[8:11]
	v_mfma_f32_16x16x32_bf16 v[60:63], v[148:151], v[180:183], v[60:63]
	v_mfma_f32_16x16x32_bf16 v[56:59], v[156:159], v[180:183], v[56:59]
	v_mfma_f32_16x16x32_bf16 v[44:47], v[148:151], v[188:191], v[44:47]
	v_mfma_f32_16x16x32_bf16 v[40:43], v[156:159], v[188:191], v[40:43]
	v_mfma_f32_16x16x32_bf16 v[28:31], v[148:151], v[206:209], v[28:31]
	v_mfma_f32_16x16x32_bf16 v[24:27], v[156:159], v[206:209], v[24:27]
	v_mfma_f32_16x16x32_bf16 v[12:15], v[148:151], v[218:221], v[12:15]
	v_mfma_f32_16x16x32_bf16 v[8:11], v[156:159], v[218:221], v[8:11]
	s_setprio 0
	s_setprio 1
	v_mfma_f32_16x16x32_bf16 v[52:55], v[160:163], v[176:179], v[52:55]
	v_mfma_f32_16x16x32_bf16 v[48:51], v[168:171], v[176:179], v[48:51]
	v_mfma_f32_16x16x32_bf16 v[36:39], v[160:163], v[184:187], v[36:39]
	v_mfma_f32_16x16x32_bf16 v[32:35], v[168:171], v[184:187], v[32:35]
	v_mfma_f32_16x16x32_bf16 v[20:23], v[160:163], v[202:205], v[20:23]
	v_mfma_f32_16x16x32_bf16 v[16:19], v[168:171], v[202:205], v[16:19]
	v_mfma_f32_16x16x32_bf16 v[4:7], v[160:163], v[214:217], v[4:7]
	v_mfma_f32_16x16x32_bf16 v[0:3], v[168:171], v[214:217], v[0:3]
	v_mfma_f32_16x16x32_bf16 v[52:55], v[164:167], v[180:183], v[52:55]
	v_mfma_f32_16x16x32_bf16 v[48:51], v[172:175], v[180:183], v[48:51]
	v_mfma_f32_16x16x32_bf16 v[36:39], v[164:167], v[188:191], v[36:39]
	v_mfma_f32_16x16x32_bf16 v[32:35], v[172:175], v[188:191], v[32:35]
	v_mfma_f32_16x16x32_bf16 v[20:23], v[164:167], v[206:209], v[20:23]
	v_mfma_f32_16x16x32_bf16 v[16:19], v[172:175], v[206:209], v[16:19]
	v_mfma_f32_16x16x32_bf16 v[4:7], v[164:167], v[218:221], v[4:7]
	v_mfma_f32_16x16x32_bf16 v[0:3], v[172:175], v[218:221], v[0:3]
	s_setprio 0
	s_barrier
	ds_read_b128 v[144:147], v199
	ds_read_b128 v[148:151], v199 offset:1024
	ds_read_b128 v[152:155], v199 offset:2048
	ds_read_b128 v[156:159], v199 offset:3072
	ds_read_b128 v[160:163], v200
	ds_read_b128 v[164:167], v200 offset:1024
	ds_read_b128 v[168:171], v200 offset:2048
	ds_read_b128 v[172:175], v200 offset:3072
	s_add_u32 s16, s44, 0x40000
	s_addc_u32 s17, s45, 0
	s_mov_b32 m0, s53
	v_lshl_add_u64 v[226:227], s[16:17], 0, v[128:129]
	ds_read_b128 v[176:179], v197 offset:32768
	ds_read_b128 v[180:183], v197 offset:33792
	ds_read_b128 v[184:187], v197 offset:34816
	ds_read_b128 v[188:191], v197 offset:35840
	ds_read_b128 v[202:205], v197 offset:36864
	ds_read_b128 v[206:209], v197 offset:37888
	ds_read_b128 v[214:217], v197 offset:38912
	ds_read_b128 v[218:221], v197 offset:39936
	global_load_lds_dwordx4 v[226:227], off
	v_lshl_add_u64 v[226:227], s[16:17], 0, v[132:133]
	s_mov_b32 m0, s55
	s_nop 0
	global_load_lds_dwordx4 v[226:227], off
	s_waitcnt vmcnt(8)
	s_waitcnt lgkmcnt(0)
	s_barrier
	s_setprio 1
	s_waitcnt lgkmcnt(0)
	v_mfma_f32_16x16x32_bf16 v[124:127], v[144:147], v[176:179], v[124:127]
	v_mfma_f32_16x16x32_bf16 v[120:123], v[152:155], v[176:179], v[120:123]
	v_mfma_f32_16x16x32_bf16 v[108:111], v[144:147], v[184:187], v[108:111]
	v_mfma_f32_16x16x32_bf16 v[104:107], v[152:155], v[184:187], v[104:107]
	v_mfma_f32_16x16x32_bf16 v[92:95], v[144:147], v[202:205], v[92:95]
	v_mfma_f32_16x16x32_bf16 v[88:91], v[152:155], v[202:205], v[88:91]
	v_mfma_f32_16x16x32_bf16 v[76:79], v[144:147], v[214:217], v[76:79]
	v_mfma_f32_16x16x32_bf16 v[72:75], v[152:155], v[214:217], v[72:75]
	v_mfma_f32_16x16x32_bf16 v[124:127], v[148:151], v[180:183], v[124:127]
	v_mfma_f32_16x16x32_bf16 v[120:123], v[156:159], v[180:183], v[120:123]
	v_mfma_f32_16x16x32_bf16 v[108:111], v[148:151], v[188:191], v[108:111]
	v_mfma_f32_16x16x32_bf16 v[104:107], v[156:159], v[188:191], v[104:107]
	v_mfma_f32_16x16x32_bf16 v[92:95], v[148:151], v[206:209], v[92:95]
	v_mfma_f32_16x16x32_bf16 v[88:91], v[156:159], v[206:209], v[88:91]
	v_mfma_f32_16x16x32_bf16 v[76:79], v[148:151], v[218:221], v[76:79]
	v_mfma_f32_16x16x32_bf16 v[72:75], v[156:159], v[218:221], v[72:75]
	s_setprio 0
	s_setprio 1
	v_mfma_f32_16x16x32_bf16 v[116:119], v[160:163], v[176:179], v[116:119]
	v_mfma_f32_16x16x32_bf16 v[112:115], v[168:171], v[176:179], v[112:115]
	v_mfma_f32_16x16x32_bf16 v[100:103], v[160:163], v[184:187], v[100:103]
	v_mfma_f32_16x16x32_bf16 v[96:99], v[168:171], v[184:187], v[96:99]
	v_mfma_f32_16x16x32_bf16 v[84:87], v[160:163], v[202:205], v[84:87]
	v_mfma_f32_16x16x32_bf16 v[80:83], v[168:171], v[202:205], v[80:83]
	v_mfma_f32_16x16x32_bf16 v[68:71], v[160:163], v[214:217], v[68:71]
	v_mfma_f32_16x16x32_bf16 v[64:67], v[168:171], v[214:217], v[64:67]
	v_mfma_f32_16x16x32_bf16 v[116:119], v[164:167], v[180:183], v[116:119]
	v_mfma_f32_16x16x32_bf16 v[112:115], v[172:175], v[180:183], v[112:115]
	v_mfma_f32_16x16x32_bf16 v[100:103], v[164:167], v[188:191], v[100:103]
	v_mfma_f32_16x16x32_bf16 v[96:99], v[172:175], v[188:191], v[96:99]
	v_mfma_f32_16x16x32_bf16 v[84:87], v[164:167], v[206:209], v[84:87]
	v_mfma_f32_16x16x32_bf16 v[80:83], v[172:175], v[206:209], v[80:83]
	v_mfma_f32_16x16x32_bf16 v[68:71], v[164:167], v[218:221], v[68:71]
	v_mfma_f32_16x16x32_bf16 v[64:67], v[172:175], v[218:221], v[64:67]
	s_setprio 0
	s_barrier
; #define PG8_STAGE(bufoff, gbase, voff) do { _Pragma("unroll") for (int _i = 0; _i < 2; ++_i) \
;     __builtin_amdgcn_global_load_lds((const unsigned*)((const char*)(gbase) + (voff)[_i]), (PG8_LAS unsigned*)(lds + (bufoff) + ldsw + _i * 8192), 16, 0, 0); } while (0)
; #define PG8_LDA(dst, b, h) do { _Pragma("unroll") for (int m = 0; m < 4; ++m) _Pragma("unroll") for (int k = 0; k < 2; ++k) dst[m][k] = *(const PG8_LAS bf16x8*)(lds + PG8_SA(b, h) + aoff + m * 2048 + k * 1024); } while (0)
; #define PG8_LDB(dst, b, h) do { _Pragma("unroll") for (int n = 0; n < 2; ++n) _Pragma("unroll") for (int k = 0; k < 2; ++k) dst[n][k] = *(const PG8_LAS bf16x8*)(lds + PG8_SB(b, h) + boff + n * 2048 + k * 1024); } while (0)
; #define PG8_MMA(ai, bj, At, Bt) do { __builtin_amdgcn_s_setprio(1); _Pragma("unroll") for (int m = 0; m < 4; ++m) _Pragma("unroll") for (int n = 0; n < 2; ++n) _Pragma("unroll") for (int k = 0; k < 2; ++k) \
;     acc[ai][bj][m][n] = __builtin_amdgcn_mfma_f32_16x16x32_bf16(Bt[n][k], At[m][k], acc[ai][bj][m][n], 0, 0, 0); __builtin_amdgcn_s_setprio(0); } while (0)
; #define PG8_WAIT_V(n) asm volatile("s_waitcnt vmcnt(" #n ")" ::: "memory")
; #define PG8_WAIT_L(n) asm volatile("s_waitcnt lgkmcnt(" #n ")" ::: "memory")
; #define PG8_BAR __builtin_amdgcn_s_barrier()
; #define PG8_SCHED __builtin_amdgcn_sched_barrier(0)
; DI void rows_rstd(float (&rs)[2][4], const float* ps, const Unit& u, int wr, int fr, int fq, int p_lo, int p_hi, float inv_dim) {
;   f32x4 pv[2][4];
; #pragma unroll
;   for (int ai = 0; ai < 2; ++ai)
; #pragma unroll
;     for (int m = 0; m < 4; ++m) pv[ai][m] = *(const f32x4*)(ps + (size_t)(u.pm * BM + ai * HALF + wr * 64 + m * 16 + fr) * 16 + 4 * fq);
; template <class Epi, class Sched>
; DI void gemm_phase(PG8_LAS unsigned char* lds, const Gemm g, const Sched& S, const Epi& E) {
;     ...
;       PG8_LDB(B0, 1, 0); PG8_LDB(B1, 1, 1); PG8_SCHED; PG8_LDA(At, 1, 0); PG8_STAGE(PG8_SA(0, 1), a2 + hstepA, voffA);
;       PG8_WAIT_V(8); PG8_WAIT_L(0); PG8_BAR; PG8_MMA(0, 0, At, B0); PG8_MMA(0, 1, At, B1); PG8_BAR; PG8_SCHED;
;       PG8_LDA(At, 1, 1); PG8_STAGE(PG8_SB(1, 0), b3, voffB); PG8_STAGE(PG8_SB(1, 1), b3 + hstepB, voffB); PG8_STAGE(PG8_SA(1, 0), a3, voffA);
;       PG8_WAIT_V(8); PG8_WAIT_L(0); PG8_BAR; PG8_MMA(1, 0, At, B0); PG8_MMA(1, 1, At, B1); PG8_BAR; PG8_SCHED;
;     }
;     if (wr == 0) PG8_BAR;
	s_add_i32 s16, s69, s2
	v_lshl_add_u64 v[192:193], v[192:193], 0, s[14:15]
	s_mov_b32 m0, s16
	ds_read_b128 v[176:179], v197 offset:49152
	ds_read_b128 v[180:183], v197 offset:50176
	ds_read_b128 v[184:187], v197 offset:51200
	ds_read_b128 v[188:191], v197 offset:52224
	ds_read_b128 v[202:205], v197 offset:53248
	ds_read_b128 v[206:209], v197 offset:54272
	ds_read_b128 v[214:217], v197 offset:55296
	ds_read_b128 v[218:221], v197 offset:56320
	global_load_lds_dwordx4 v[192:193], off
	s_add_i32 m0, s16, 0x2000
	s_add_u32 s16, s40, 0x40080
	v_lshl_add_u64 v[192:193], v[210:211], 0, s[14:15]
	s_addc_u32 s17, s41, 0
	s_add_i32 s33, s70, s2
	global_load_lds_dwordx4 v[192:193], off
	v_lshl_add_u64 v[192:193], s[16:17], 0, v[130:131]
	s_mov_b32 m0, s33
	s_nop 0
	global_load_lds_dwordx4 v[192:193], off
	v_lshl_add_u64 v[192:193], s[16:17], 0, v[134:135]
	s_add_i32 m0, s33, 0x2000
	s_nop 0
	global_load_lds_dwordx4 v[192:193], off
	v_lshl_add_u64 v[192:193], v[222:223], 0, s[14:15]
	s_mov_b32 m0, s65
	s_nop 0
	global_load_lds_dwordx4 v[192:193], off
	v_lshl_add_u64 v[192:193], v[224:225], 0, s[14:15]
	s_mov_b32 m0, s66
	s_nop 0
	global_load_lds_dwordx4 v[192:193], off
	s_waitcnt vmcnt(8)
	s_waitcnt lgkmcnt(0)
	s_barrier
	s_setprio 1
	s_waitcnt lgkmcnt(0)
	v_mfma_f32_16x16x32_bf16 v[60:63], v[144:147], v[176:179], v[60:63]
	v_mfma_f32_16x16x32_bf16 v[56:59], v[152:155], v[176:179], v[56:59]
	v_mfma_f32_16x16x32_bf16 v[44:47], v[144:147], v[184:187], v[44:47]
	v_mfma_f32_16x16x32_bf16 v[40:43], v[152:155], v[184:187], v[40:43]
	v_mfma_f32_16x16x32_bf16 v[28:31], v[144:147], v[202:205], v[28:31]
	v_mfma_f32_16x16x32_bf16 v[24:27], v[152:155], v[202:205], v[24:27]
	v_mfma_f32_16x16x32_bf16 v[12:15], v[144:147], v[214:217], v[12:15]
	v_mfma_f32_16x16x32_bf16 v[8:11], v[152:155], v[214:217], v[8:11]
	v_mfma_f32_16x16x32_bf16 v[60:63], v[148:151], v[180:183], v[60:63]
	v_mfma_f32_16x16x32_bf16 v[56:59], v[156:159], v[180:183], v[56:59]
	v_mfma_f32_16x16x32_bf16 v[44:47], v[148:151], v[188:191], v[44:47]
	v_mfma_f32_16x16x32_bf16 v[40:43], v[156:159], v[188:191], v[40:43]
	v_mfma_f32_16x16x32_bf16 v[28:31], v[148:151], v[206:209], v[28:31]
	v_mfma_f32_16x16x32_bf16 v[24:27], v[156:159], v[206:209], v[24:27]
	v_mfma_f32_16x16x32_bf16 v[12:15], v[148:151], v[218:221], v[12:15]
	v_mfma_f32_16x16x32_bf16 v[8:11], v[156:159], v[218:221], v[8:11]
	s_setprio 0
	s_setprio 1
	v_mfma_f32_16x16x32_bf16 v[52:55], v[160:163], v[176:179], v[52:55]
	v_mfma_f32_16x16x32_bf16 v[48:51], v[168:171], v[176:179], v[48:51]
	v_mfma_f32_16x16x32_bf16 v[36:39], v[160:163], v[184:187], v[36:39]
	v_mfma_f32_16x16x32_bf16 v[32:35], v[168:171], v[184:187], v[32:35]
	v_mfma_f32_16x16x32_bf16 v[20:23], v[160:163], v[202:205], v[20:23]
	v_mfma_f32_16x16x32_bf16 v[16:19], v[168:171], v[202:205], v[16:19]
	v_mfma_f32_16x16x32_bf16 v[4:7], v[160:163], v[214:217], v[4:7]
	v_mfma_f32_16x16x32_bf16 v[0:3], v[168:171], v[214:217], v[0:3]
	v_mfma_f32_16x16x32_bf16 v[52:55], v[164:167], v[180:183], v[52:55]
	v_mfma_f32_16x16x32_bf16 v[48:51], v[172:175], v[180:183], v[48:51]
	v_mfma_f32_16x16x32_bf16 v[36:39], v[164:167], v[188:191], v[36:39]
	v_mfma_f32_16x16x32_bf16 v[32:35], v[172:175], v[188:191], v[32:35]
	v_mfma_f32_16x16x32_bf16 v[20:23], v[164:167], v[206:209], v[20:23]
	v_mfma_f32_16x16x32_bf16 v[16:19], v[172:175], v[206:209], v[16:19]
	v_mfma_f32_16x16x32_bf16 v[4:7], v[164:167], v[218:221], v[4:7]
	v_mfma_f32_16x16x32_bf16 v[0:3], v[172:175], v[218:221], v[0:3]
	s_setprio 0
	s_add_i32 s73, s73, 2
	s_add_u32 s10, s10, 0x100
	s_addc_u32 s11, s11, 0
	s_add_u32 s31, s31, 0x100
	s_addc_u32 s72, s72, 0
	s_cmp_gt_u32 s73, 13
	s_barrier
	s_cbranch_scc0 .LBB0_807
	v_lshl_add_u32 v184, s8, 8, v143
	v_or_b32_e32 v180, 16, v184
	v_ashrrev_i32_e32 v181, 31, v180
	v_or_b32_e32 v172, 32, v184
	v_lshlrev_b64 v[178:179], 6, v[180:181]
	v_ashrrev_i32_e32 v173, 31, v172
	v_ashrrev_i32_e32 v185, 31, v184
	v_lshl_add_u64 v[144:145], v[136:137], 0, v[178:179]
	v_lshlrev_b64 v[170:171], 6, v[172:173]
	v_lshlrev_b64 v[182:183], 6, v[184:185]
	v_lshl_add_u64 v[146:147], v[136:137], 0, v[170:171]
	global_load_dwordx4 v[162:165], v[144:145], off
	global_load_dwordx4 v[174:177], v[146:147], off
	v_lshl_add_u64 v[144:145], v[136:137], 0, v[182:183]
	global_load_dwordx4 v[186:189], v[144:145], off
	v_or_b32_e32 v168, 48, v184
	v_ashrrev_i32_e32 v169, 31, v168
	v_add_u32_e32 v160, 0x80, v184
	v_add_u32_e32 v156, 0x90, v184
	v_lshlrev_b64 v[166:167], 6, v[168:169]
	v_ashrrev_i32_e32 v161, 31, v160
	v_ashrrev_i32_e32 v157, 31, v156
	v_lshl_add_u64 v[144:145], v[136:137], 0, v[166:167]
	v_lshlrev_b64 v[158:159], 6, v[160:161]
	v_lshlrev_b64 v[154:155], 6, v[156:157]
	v_lshl_add_u64 v[146:147], v[136:137], 0, v[158:159]
	global_load_dwordx4 v[190:193], v[144:145], off
	global_load_dwordx4 v[202:205], v[146:147], off
	v_lshl_add_u64 v[144:145], v[136:137], 0, v[154:155]
	global_load_dwordx4 v[206:209], v[144:145], off
	v_add_u32_e32 v150, 0xa0, v184
	v_ashrrev_i32_e32 v151, 31, v150
	v_lshlrev_b64 v[148:149], 6, v[150:151]
	v_add_u32_e32 v146, 0xb0, v184
	v_lshl_add_u64 v[144:145], v[136:137], 0, v[148:149]
	v_ashrrev_i32_e32 v147, 31, v146
	global_load_dwordx4 v[214:217], v[144:145], off
	v_lshlrev_b64 v[144:145], 6, v[146:147]
	v_lshl_add_u64 v[152:153], v[136:137], 0, v[144:145]
	global_load_dwordx4 v[218:221], v[152:153], off
	s_and_b64 vcc, exec, s[20:21]
	s_cbranch_vccz .LBB0_810
	s_barrier

; #define PG8_STAGE(bufoff, gbase, voff) do { _Pragma("unroll") for (int _i = 0; _i < 2; ++_i) \
;     __builtin_amdgcn_global_load_lds((const unsigned*)((const char*)(gbase) + (voff)[_i]), (PG8_LAS unsigned*)(lds + (bufoff) + ldsw + _i * 8192), 16, 0, 0); } while (0)
; #define PG8_LDA(dst, b, h) do { _Pragma("unroll") for (int m = 0; m < 4; ++m) _Pragma("unroll") for (int k = 0; k < 2; ++k) dst[m][k] = *(const PG8_LAS bf16x8*)(lds + PG8_SA(b, h) + aoff + m * 2048 + k * 1024); } while (0)
; #define PG8_LDB(dst, b, h) do { _Pragma("unroll") for (int n = 0; n < 2; ++n) _Pragma("unroll") for (int k = 0; k < 2; ++k) dst[n][k] = *(const PG8_LAS bf16x8*)(lds + PG8_SB(b, h) + boff + n * 2048 + k * 1024); } while (0)
; #define PG8_MMA(ai, bj, At, Bt) do { __builtin_amdgcn_s_setprio(1); _Pragma("unroll") for (int m = 0; m < 4; ++m) _Pragma("unroll") for (int n = 0; n < 2; ++n) _Pragma("unroll") for (int k = 0; k < 2; ++k) \
;     acc[ai][bj][m][n] = __builtin_amdgcn_mfma_f32_16x16x32_bf16(Bt[n][k], At[m][k], acc[ai][bj][m][n], 0, 0, 0); __builtin_amdgcn_s_setprio(0); } while (0)
; #define PG8_WAIT_V(n) asm volatile("s_waitcnt vmcnt(" #n ")" ::: "memory")
; #define PG8_WAIT_L(n) asm volatile("s_waitcnt lgkmcnt(" #n ")" ::: "memory")
; #define PG8_BAR __builtin_amdgcn_s_barrier()
; #define PG8_SCHED __builtin_amdgcn_sched_barrier(0)
; template <class Epi, class Sched>
; DI void gemm_phase(PG8_LAS unsigned char* lds, const Gemm g, const Sched& S, const Epi& E) {
;     ...
;       PG8_LDB(B0, 0, 0); PG8_LDB(B1, 0, 1); PG8_SCHED; PG8_LDA(At, 0, 0); PG8_STAGE(PG8_SA(1, 1), a1 + hstepA, voffA);
;       PG8_WAIT_V(8); PG8_WAIT_L(0); PG8_BAR; PG8_MMA(0, 0, At, B0); PG8_MMA(0, 1, At, B1); PG8_BAR; PG8_SCHED;
;       PG8_LDA(At, 0, 1); PG8_STAGE(PG8_SB(0, 0), b2, voffB); PG8_STAGE(PG8_SB(0, 1), b2 + hstepB, voffB); PG8_STAGE(PG8_SA(0, 0), a2, voffA);
;       PG8_WAIT_V(8); PG8_WAIT_L(0); PG8_BAR; PG8_MMA(1, 0, At, B0); PG8_MMA(1, 1, At, B1); PG8_BAR; PG8_SCHED;
.LBB0_930:
	ds_read_b128 v[128:131], v191
	ds_read_b128 v[132:135], v191 offset:1024
	ds_read_b128 v[136:139], v191 offset:2048
	ds_read_b128 v[140:143], v191 offset:3072
	ds_read_b128 v[144:147], v192
	ds_read_b128 v[148:151], v192 offset:1024
	ds_read_b128 v[152:155], v192 offset:2048
	ds_read_b128 v[172:175], v192 offset:3072
	s_add_u32 s12, s0, 0x100
	s_addc_u32 s13, s1, 0
	s_cmp_eq_u32 s74, 8
	s_cselect_b32 s39, s35, s13
	s_cselect_b32 s38, s34, s12
	s_cselect_b32 s15, s37, s73
	s_cselect_b32 s14, s36, s72
	s_mov_b32 m0, s65
	v_lshl_add_u64 v[188:189], s[0:1], 0, v[166:167]
	ds_read_b128 v[176:179], v193
	ds_read_b128 v[180:183], v193 offset:1024
	ds_read_b128 v[184:187], v193 offset:2048
	ds_read_b128 v[198:201], v193 offset:3072
	ds_read_b128 v[202:205], v193 offset:4096
	ds_read_b128 v[206:209], v193 offset:5120
	ds_read_b128 v[214:217], v193 offset:6144
	ds_read_b128 v[218:221], v193 offset:7168
	global_load_lds_dwordx4 v[188:189], off
	v_lshl_add_u64 v[188:189], s[0:1], 0, v[168:169]
	s_add_i32 m0, s3, 0xe000
	s_nop 0
	global_load_lds_dwordx4 v[188:189], off
	s_waitcnt vmcnt(8)
	s_waitcnt lgkmcnt(0)
	s_barrier
	s_setprio 1
	s_waitcnt lgkmcnt(0)
	v_mfma_f32_16x16x32_bf16 v[120:123], v[128:131], v[176:179], v[120:123]
	v_mfma_f32_16x16x32_bf16 v[124:127], v[136:139], v[176:179], v[124:127]
	v_mfma_f32_16x16x32_bf16 v[104:107], v[128:131], v[184:187], v[104:107]
	v_mfma_f32_16x16x32_bf16 v[108:111], v[136:139], v[184:187], v[108:111]
	v_mfma_f32_16x16x32_bf16 v[88:91], v[128:131], v[202:205], v[88:91]
	v_mfma_f32_16x16x32_bf16 v[92:95], v[136:139], v[202:205], v[92:95]
	v_mfma_f32_16x16x32_bf16 v[72:75], v[128:131], v[214:217], v[72:75]
	v_mfma_f32_16x16x32_bf16 v[76:79], v[136:139], v[214:217], v[76:79]
	v_mfma_f32_16x16x32_bf16 v[120:123], v[132:135], v[180:183], v[120:123]
	v_mfma_f32_16x16x32_bf16 v[124:127], v[140:143], v[180:183], v[124:127]
	v_mfma_f32_16x16x32_bf16 v[104:107], v[132:135], v[198:201], v[104:107]
	v_mfma_f32_16x16x32_bf16 v[108:111], v[140:143], v[198:201], v[108:111]
	v_mfma_f32_16x16x32_bf16 v[88:91], v[132:135], v[206:209], v[88:91]
	v_mfma_f32_16x16x32_bf16 v[92:95], v[140:143], v[206:209], v[92:95]
	v_mfma_f32_16x16x32_bf16 v[72:75], v[132:135], v[218:221], v[72:75]
	v_mfma_f32_16x16x32_bf16 v[76:79], v[140:143], v[218:221], v[76:79]
	s_setprio 0
	s_setprio 1
	v_mfma_f32_16x16x32_bf16 v[112:115], v[144:147], v[176:179], v[112:115]
	v_mfma_f32_16x16x32_bf16 v[116:119], v[152:155], v[176:179], v[116:119]
	v_mfma_f32_16x16x32_bf16 v[96:99], v[144:147], v[184:187], v[96:99]
	v_mfma_f32_16x16x32_bf16 v[100:103], v[152:155], v[184:187], v[100:103]
	v_mfma_f32_16x16x32_bf16 v[80:83], v[144:147], v[202:205], v[80:83]
	v_mfma_f32_16x16x32_bf16 v[84:87], v[152:155], v[202:205], v[84:87]
	v_mfma_f32_16x16x32_bf16 v[64:67], v[144:147], v[214:217], v[64:67]
	v_mfma_f32_16x16x32_bf16 v[68:71], v[152:155], v[214:217], v[68:71]
	v_mfma_f32_16x16x32_bf16 v[112:115], v[148:151], v[180:183], v[112:115]
	v_mfma_f32_16x16x32_bf16 v[116:119], v[172:175], v[180:183], v[116:119]
	v_mfma_f32_16x16x32_bf16 v[96:99], v[148:151], v[198:201], v[96:99]
	v_mfma_f32_16x16x32_bf16 v[100:103], v[172:175], v[198:201], v[100:103]
	v_mfma_f32_16x16x32_bf16 v[80:83], v[148:151], v[206:209], v[80:83]
	v_mfma_f32_16x16x32_bf16 v[84:87], v[172:175], v[206:209], v[84:87]
	v_mfma_f32_16x16x32_bf16 v[64:67], v[148:151], v[218:221], v[64:67]
	v_mfma_f32_16x16x32_bf16 v[68:71], v[172:175], v[218:221], v[68:71]
	s_setprio 0
	s_barrier
	s_add_i32 s0, s44, s2
	v_lshl_add_u64 v[188:189], s[14:15], 0, v[158:159]
	s_mov_b32 m0, s0
	ds_read_b128 v[176:179], v193 offset:16384
	ds_read_b128 v[180:183], v193 offset:17408
	ds_read_b128 v[184:187], v193 offset:18432
	ds_read_b128 v[198:201], v193 offset:19456
	ds_read_b128 v[202:205], v193 offset:20480
	ds_read_b128 v[206:209], v193 offset:21504
	ds_read_b128 v[214:217], v193 offset:22528
	ds_read_b128 v[218:221], v193 offset:23552
	global_load_lds_dwordx4 v[188:189], off
	s_add_i32 m0, s0, 0x2000
	s_add_u32 s0, s14, 0x30000
	v_lshl_add_u64 v[210:211], s[14:15], 0, v[162:163]
	s_addc_u32 s1, s15, 0
	s_add_i32 s16, s45, s2
	global_load_lds_dwordx4 v[210:211], off
	v_lshl_add_u64 v[222:223], s[0:1], 0, v[158:159]
	s_mov_b32 m0, s16
	v_lshl_add_u64 v[224:225], s[38:39], 0, v[160:161]
	global_load_lds_dwordx4 v[222:223], off
	v_lshl_add_u64 v[222:223], s[0:1], 0, v[162:163]
	s_add_i32 m0, s16, 0x2000
	s_nop 0
	global_load_lds_dwordx4 v[222:223], off
	v_lshl_add_u64 v[222:223], s[38:39], 0, v[156:157]
	s_mov_b32 m0, s3
	s_nop 0
	global_load_lds_dwordx4 v[222:223], off
	s_mov_b32 m0, s4
	s_nop 0
	global_load_lds_dwordx4 v[224:225], off
	s_waitcnt vmcnt(8)
	s_waitcnt lgkmcnt(0)
	s_barrier
; #define PG8_STAGE(bufoff, gbase, voff) do { _Pragma("unroll") for (int _i = 0; _i < 2; ++_i) \
;     __builtin_amdgcn_global_load_lds((const unsigned*)((const char*)(gbase) + (voff)[_i]), (PG8_LAS unsigned*)(lds + (bufoff) + ldsw + _i * 8192), 16, 0, 0); } while (0)
; #define PG8_LDA(dst, b, h) do { _Pragma("unroll") for (int m = 0; m < 4; ++m) _Pragma("unroll") for (int k = 0; k < 2; ++k) dst[m][k] = *(const PG8_LAS bf16x8*)(lds + PG8_SA(b, h) + aoff + m * 2048 + k * 1024); } while (0)
; #define PG8_LDB(dst, b, h) do { _Pragma("unroll") for (int n = 0; n < 2; ++n) _Pragma("unroll") for (int k = 0; k < 2; ++k) dst[n][k] = *(const PG8_LAS bf16x8*)(lds + PG8_SB(b, h) + boff + n * 2048 + k * 1024); } while (0)
; #define PG8_MMA(ai, bj, At, Bt) do { __builtin_amdgcn_s_setprio(1); _Pragma("unroll") for (int m = 0; m < 4; ++m) _Pragma("unroll") for (int n = 0; n < 2; ++n) _Pragma("unroll") for (int k = 0; k < 2; ++k) \
;     acc[ai][bj][m][n] = __builtin_amdgcn_mfma_f32_16x16x32_bf16(Bt[n][k], At[m][k], acc[ai][bj][m][n], 0, 0, 0); __builtin_amdgcn_s_setprio(0); } while (0)
; #define PG8_WAIT_V(n) asm volatile("s_waitcnt vmcnt(" #n ")" ::: "memory")
; #define PG8_WAIT_L(n) asm volatile("s_waitcnt lgkmcnt(" #n ")" ::: "memory")
; #define PG8_BAR __builtin_amdgcn_s_barrier()
; #define PG8_SCHED __builtin_amdgcn_sched_barrier(0)
; template <class Epi, class Sched>
; DI void gemm_phase(PG8_LAS unsigned char* lds, const Gemm g, const Sched& S, const Epi& E) {
;     ...
;       PG8_WAIT_V(8); PG8_WAIT_L(0); PG8_BAR; PG8_MMA(1, 0, At, B0); PG8_MMA(1, 1, At, B1); PG8_BAR; PG8_SCHED;
;       PG8_LDB(B0, 1, 0); PG8_LDB(B1, 1, 1); PG8_SCHED; PG8_LDA(At, 1, 0); PG8_STAGE(PG8_SA(0, 1), a2 + hstepA, voffA);
;       PG8_WAIT_V(8); PG8_WAIT_L(0); PG8_BAR; PG8_MMA(0, 0, At, B0); PG8_MMA(0, 1, At, B1); PG8_BAR; PG8_SCHED;
	s_setprio 1
	s_waitcnt lgkmcnt(0)
	v_mfma_f32_16x16x32_bf16 v[56:59], v[128:131], v[176:179], v[56:59]
	v_mfma_f32_16x16x32_bf16 v[60:63], v[136:139], v[176:179], v[60:63]
	v_mfma_f32_16x16x32_bf16 v[40:43], v[128:131], v[184:187], v[40:43]
	v_mfma_f32_16x16x32_bf16 v[44:47], v[136:139], v[184:187], v[44:47]
	v_mfma_f32_16x16x32_bf16 v[24:27], v[128:131], v[202:205], v[24:27]
	v_mfma_f32_16x16x32_bf16 v[28:31], v[136:139], v[202:205], v[28:31]
	v_mfma_f32_16x16x32_bf16 v[8:11], v[128:131], v[214:217], v[8:11]
	v_mfma_f32_16x16x32_bf16 v[12:15], v[136:139], v[214:217], v[12:15]
	v_mfma_f32_16x16x32_bf16 v[56:59], v[132:135], v[180:183], v[56:59]
	v_mfma_f32_16x16x32_bf16 v[60:63], v[140:143], v[180:183], v[60:63]
	v_mfma_f32_16x16x32_bf16 v[40:43], v[132:135], v[198:201], v[40:43]
	v_mfma_f32_16x16x32_bf16 v[44:47], v[140:143], v[198:201], v[44:47]
	v_mfma_f32_16x16x32_bf16 v[24:27], v[132:135], v[206:209], v[24:27]
	v_mfma_f32_16x16x32_bf16 v[28:31], v[140:143], v[206:209], v[28:31]
	v_mfma_f32_16x16x32_bf16 v[8:11], v[132:135], v[218:221], v[8:11]
	v_mfma_f32_16x16x32_bf16 v[12:15], v[140:143], v[218:221], v[12:15]
	s_setprio 0
	s_setprio 1
	v_mfma_f32_16x16x32_bf16 v[48:51], v[144:147], v[176:179], v[48:51]
	v_mfma_f32_16x16x32_bf16 v[52:55], v[152:155], v[176:179], v[52:55]
	v_mfma_f32_16x16x32_bf16 v[32:35], v[144:147], v[184:187], v[32:35]
	v_mfma_f32_16x16x32_bf16 v[36:39], v[152:155], v[184:187], v[36:39]
	v_mfma_f32_16x16x32_bf16 v[16:19], v[144:147], v[202:205], v[16:19]
	v_mfma_f32_16x16x32_bf16 v[20:23], v[152:155], v[202:205], v[20:23]
	v_mfma_f32_16x16x32_bf16 v[4:7], v[144:147], v[214:217], v[4:7]
	v_mfma_f32_16x16x32_bf16 v[0:3], v[152:155], v[214:217], v[0:3]
	v_mfma_f32_16x16x32_bf16 v[48:51], v[148:151], v[180:183], v[48:51]
	v_mfma_f32_16x16x32_bf16 v[52:55], v[172:175], v[180:183], v[52:55]
	v_mfma_f32_16x16x32_bf16 v[32:35], v[148:151], v[198:201], v[32:35]
	v_mfma_f32_16x16x32_bf16 v[36:39], v[172:175], v[198:201], v[36:39]
	v_mfma_f32_16x16x32_bf16 v[16:19], v[148:151], v[206:209], v[16:19]
	v_mfma_f32_16x16x32_bf16 v[20:23], v[172:175], v[206:209], v[20:23]
	v_mfma_f32_16x16x32_bf16 v[4:7], v[148:151], v[218:221], v[4:7]
	v_mfma_f32_16x16x32_bf16 v[0:3], v[172:175], v[218:221], v[0:3]
	s_setprio 0
	s_barrier
	ds_read_b128 v[128:131], v195
	ds_read_b128 v[132:135], v195 offset:1024
	ds_read_b128 v[136:139], v195 offset:2048
	ds_read_b128 v[140:143], v195 offset:3072
	ds_read_b128 v[144:147], v196
	ds_read_b128 v[148:151], v196 offset:1024
	ds_read_b128 v[152:155], v196 offset:2048
	ds_read_b128 v[172:175], v196 offset:3072
	s_add_u32 s0, s38, 0x58000
	s_addc_u32 s1, s39, 0
	s_mov_b32 m0, s5
	v_lshl_add_u64 v[226:227], s[0:1], 0, v[156:157]
	ds_read_b128 v[176:179], v193 offset:32768
	ds_read_b128 v[180:183], v193 offset:33792
	ds_read_b128 v[184:187], v193 offset:34816
	ds_read_b128 v[198:201], v193 offset:35840
	ds_read_b128 v[202:205], v193 offset:36864
	ds_read_b128 v[206:209], v193 offset:37888
	ds_read_b128 v[214:217], v193 offset:38912
	ds_read_b128 v[218:221], v193 offset:39936
	global_load_lds_dwordx4 v[226:227], off
	v_lshl_add_u64 v[226:227], s[0:1], 0, v[160:161]
	s_mov_b32 m0, s18
	s_nop 0
	global_load_lds_dwordx4 v[226:227], off
	s_waitcnt vmcnt(8)
	s_waitcnt lgkmcnt(0)
	s_barrier
	s_setprio 1
	s_waitcnt lgkmcnt(0)
	v_mfma_f32_16x16x32_bf16 v[120:123], v[128:131], v[176:179], v[120:123]
	v_mfma_f32_16x16x32_bf16 v[124:127], v[136:139], v[176:179], v[124:127]
	v_mfma_f32_16x16x32_bf16 v[104:107], v[128:131], v[184:187], v[104:107]
	v_mfma_f32_16x16x32_bf16 v[108:111], v[136:139], v[184:187], v[108:111]
	v_mfma_f32_16x16x32_bf16 v[88:91], v[128:131], v[202:205], v[88:91]
	v_mfma_f32_16x16x32_bf16 v[92:95], v[136:139], v[202:205], v[92:95]
	v_mfma_f32_16x16x32_bf16 v[72:75], v[128:131], v[214:217], v[72:75]
	v_mfma_f32_16x16x32_bf16 v[76:79], v[136:139], v[214:217], v[76:79]
	v_mfma_f32_16x16x32_bf16 v[120:123], v[132:135], v[180:183], v[120:123]
	v_mfma_f32_16x16x32_bf16 v[124:127], v[140:143], v[180:183], v[124:127]
	v_mfma_f32_16x16x32_bf16 v[104:107], v[132:135], v[198:201], v[104:107]
	v_mfma_f32_16x16x32_bf16 v[108:111], v[140:143], v[198:201], v[108:111]
	v_mfma_f32_16x16x32_bf16 v[88:91], v[132:135], v[206:209], v[88:91]
	v_mfma_f32_16x16x32_bf16 v[92:95], v[140:143], v[206:209], v[92:95]
	v_mfma_f32_16x16x32_bf16 v[72:75], v[132:135], v[218:221], v[72:75]
	v_mfma_f32_16x16x32_bf16 v[76:79], v[140:143], v[218:221], v[76:79]
	s_setprio 0
	s_setprio 1
	v_mfma_f32_16x16x32_bf16 v[112:115], v[144:147], v[176:179], v[112:115]
	v_mfma_f32_16x16x32_bf16 v[116:119], v[152:155], v[176:179], v[116:119]
	v_mfma_f32_16x16x32_bf16 v[96:99], v[144:147], v[184:187], v[96:99]
	v_mfma_f32_16x16x32_bf16 v[100:103], v[152:155], v[184:187], v[100:103]
	v_mfma_f32_16x16x32_bf16 v[80:83], v[144:147], v[202:205], v[80:83]
	v_mfma_f32_16x16x32_bf16 v[84:87], v[152:155], v[202:205], v[84:87]
	v_mfma_f32_16x16x32_bf16 v[64:67], v[144:147], v[214:217], v[64:67]
	v_mfma_f32_16x16x32_bf16 v[68:71], v[152:155], v[214:217], v[68:71]
	v_mfma_f32_16x16x32_bf16 v[112:115], v[148:151], v[180:183], v[112:115]
	v_mfma_f32_16x16x32_bf16 v[116:119], v[172:175], v[180:183], v[116:119]
	v_mfma_f32_16x16x32_bf16 v[96:99], v[148:151], v[198:201], v[96:99]
	v_mfma_f32_16x16x32_bf16 v[100:103], v[172:175], v[198:201], v[100:103]
	v_mfma_f32_16x16x32_bf16 v[80:83], v[148:151], v[206:209], v[80:83]
	v_mfma_f32_16x16x32_bf16 v[84:87], v[172:175], v[206:209], v[84:87]
	v_mfma_f32_16x16x32_bf16 v[64:67], v[148:151], v[218:221], v[64:67]
	v_mfma_f32_16x16x32_bf16 v[68:71], v[172:175], v[218:221], v[68:71]
	s_setprio 0
	s_barrier
; #define PG8_STAGE(bufoff, gbase, voff) do { _Pragma("unroll") for (int _i = 0; _i < 2; ++_i) \
;     __builtin_amdgcn_global_load_lds((const unsigned*)((const char*)(gbase) + (voff)[_i]), (PG8_LAS unsigned*)(lds + (bufoff) + ldsw + _i * 8192), 16, 0, 0); } while (0)
; #define PG8_LDA(dst, b, h) do { _Pragma("unroll") for (int m = 0; m < 4; ++m) _Pragma("unroll") for (int k = 0; k < 2; ++k) dst[m][k] = *(const PG8_LAS bf16x8*)(lds + PG8_SA(b, h) + aoff + m * 2048 + k * 1024); } while (0)
; #define PG8_MMA(ai, bj, At, Bt) do { __builtin_amdgcn_s_setprio(1); _Pragma("unroll") for (int m = 0; m < 4; ++m) _Pragma("unroll") for (int n = 0; n < 2; ++n) _Pragma("unroll") for (int k = 0; k < 2; ++k) \
;     acc[ai][bj][m][n] = __builtin_amdgcn_mfma_f32_16x16x32_bf16(Bt[n][k], At[m][k], acc[ai][bj][m][n], 0, 0, 0); __builtin_amdgcn_s_setprio(0); } while (0)
; #define PG8_WAIT_V(n) asm volatile("s_waitcnt vmcnt(" #n ")" ::: "memory")
; #define PG8_WAIT_L(n) asm volatile("s_waitcnt lgkmcnt(" #n ")" ::: "memory")
; #define PG8_BAR __builtin_amdgcn_s_barrier()
; #define PG8_SCHED __builtin_amdgcn_sched_barrier(0)
; template <class Epi, class Sched>
; DI void gemm_phase(PG8_LAS unsigned char* lds, const Gemm g, const Sched& S, const Epi& E) {
;     ...
;       PG8_LDA(At, 1, 1); PG8_STAGE(PG8_SB(1, 0), b3, voffB); PG8_STAGE(PG8_SB(1, 1), b3 + hstepB, voffB); PG8_STAGE(PG8_SA(1, 0), a3, voffA);
;       PG8_WAIT_V(8); PG8_WAIT_L(0); PG8_BAR; PG8_MMA(1, 0, At, B0); PG8_MMA(1, 1, At, B1); PG8_BAR; PG8_SCHED;
;     }
;     if (wr == 0) PG8_BAR;
	s_add_i32 s0, s66, s2
	v_lshl_add_u64 v[188:189], v[188:189], 0, s[26:27]
	s_mov_b32 m0, s0
	ds_read_b128 v[176:179], v193 offset:49152
	ds_read_b128 v[180:183], v193 offset:50176
	ds_read_b128 v[184:187], v193 offset:51200
	ds_read_b128 v[198:201], v193 offset:52224
	ds_read_b128 v[202:205], v193 offset:53248
	ds_read_b128 v[206:209], v193 offset:54272
	ds_read_b128 v[214:217], v193 offset:55296
	ds_read_b128 v[218:221], v193 offset:56320
	global_load_lds_dwordx4 v[188:189], off
	s_add_i32 m0, s0, 0x2000
	s_add_u32 s0, s14, 0x30080
	v_lshl_add_u64 v[188:189], v[210:211], 0, s[26:27]
	s_addc_u32 s1, s15, 0
	s_add_i32 s14, s67, s2
	global_load_lds_dwordx4 v[188:189], off
	v_lshl_add_u64 v[188:189], s[0:1], 0, v[158:159]
	s_mov_b32 m0, s14
	s_nop 0
	global_load_lds_dwordx4 v[188:189], off
	v_lshl_add_u64 v[188:189], s[0:1], 0, v[162:163]
	s_add_i32 m0, s14, 0x2000
	s_nop 0
	global_load_lds_dwordx4 v[188:189], off
	v_lshl_add_u64 v[188:189], v[222:223], 0, s[26:27]
	s_mov_b32 m0, s19
	s_nop 0
	global_load_lds_dwordx4 v[188:189], off
	v_lshl_add_u64 v[188:189], v[224:225], 0, s[26:27]
	s_mov_b32 m0, s31
	s_nop 0
	global_load_lds_dwordx4 v[188:189], off
	s_waitcnt vmcnt(8)
	s_waitcnt lgkmcnt(0)
	s_barrier
	s_setprio 1
	s_waitcnt lgkmcnt(0)
	v_mfma_f32_16x16x32_bf16 v[56:59], v[128:131], v[176:179], v[56:59]
	v_mfma_f32_16x16x32_bf16 v[60:63], v[136:139], v[176:179], v[60:63]
	v_mfma_f32_16x16x32_bf16 v[40:43], v[128:131], v[184:187], v[40:43]
	v_mfma_f32_16x16x32_bf16 v[44:47], v[136:139], v[184:187], v[44:47]
	v_mfma_f32_16x16x32_bf16 v[24:27], v[128:131], v[202:205], v[24:27]
	v_mfma_f32_16x16x32_bf16 v[28:31], v[136:139], v[202:205], v[28:31]
	v_mfma_f32_16x16x32_bf16 v[8:11], v[128:131], v[214:217], v[8:11]
	v_mfma_f32_16x16x32_bf16 v[12:15], v[136:139], v[214:217], v[12:15]
	v_mfma_f32_16x16x32_bf16 v[56:59], v[132:135], v[180:183], v[56:59]
	v_mfma_f32_16x16x32_bf16 v[60:63], v[140:143], v[180:183], v[60:63]
	v_mfma_f32_16x16x32_bf16 v[40:43], v[132:135], v[198:201], v[40:43]
	v_mfma_f32_16x16x32_bf16 v[44:47], v[140:143], v[198:201], v[44:47]
	v_mfma_f32_16x16x32_bf16 v[24:27], v[132:135], v[206:209], v[24:27]
	v_mfma_f32_16x16x32_bf16 v[28:31], v[140:143], v[206:209], v[28:31]
	v_mfma_f32_16x16x32_bf16 v[8:11], v[132:135], v[218:221], v[8:11]
	v_mfma_f32_16x16x32_bf16 v[12:15], v[140:143], v[218:221], v[12:15]
	s_setprio 0
	s_setprio 1
	v_mfma_f32_16x16x32_bf16 v[48:51], v[144:147], v[176:179], v[48:51]
	v_mfma_f32_16x16x32_bf16 v[52:55], v[152:155], v[176:179], v[52:55]
	v_mfma_f32_16x16x32_bf16 v[32:35], v[144:147], v[184:187], v[32:35]
	v_mfma_f32_16x16x32_bf16 v[36:39], v[152:155], v[184:187], v[36:39]
	v_mfma_f32_16x16x32_bf16 v[16:19], v[144:147], v[202:205], v[16:19]
	v_mfma_f32_16x16x32_bf16 v[20:23], v[152:155], v[202:205], v[20:23]
	v_mfma_f32_16x16x32_bf16 v[4:7], v[144:147], v[214:217], v[4:7]
	v_mfma_f32_16x16x32_bf16 v[0:3], v[152:155], v[214:217], v[0:3]
	v_mfma_f32_16x16x32_bf16 v[48:51], v[148:151], v[180:183], v[48:51]
	v_mfma_f32_16x16x32_bf16 v[52:55], v[172:175], v[180:183], v[52:55]
	v_mfma_f32_16x16x32_bf16 v[32:35], v[148:151], v[198:201], v[32:35]
	v_mfma_f32_16x16x32_bf16 v[36:39], v[172:175], v[198:201], v[36:39]
	v_mfma_f32_16x16x32_bf16 v[16:19], v[148:151], v[206:209], v[16:19]
	v_mfma_f32_16x16x32_bf16 v[20:23], v[172:175], v[206:209], v[20:23]
	v_mfma_f32_16x16x32_bf16 v[4:7], v[148:151], v[218:221], v[4:7]
	v_mfma_f32_16x16x32_bf16 v[0:3], v[172:175], v[218:221], v[0:3]
	s_setprio 0
	s_add_i32 s74, s74, 2
	s_add_u32 s72, s72, 0x100
	s_addc_u32 s73, s73, 0
	s_cmp_gt_u32 s74, 9
	s_mov_b64 s[0:1], s[12:13]
	s_barrier
	s_cbranch_scc0 .LBB0_930
	s_and_b64 vcc, exec, s[28:29]
	s_cbranch_vccz .LBB0_933
	s_barrier

; #define PG8_STAGE(bufoff, gbase, voff) do { _Pragma("unroll") for (int _i = 0; _i < 2; ++_i) \
;     __builtin_amdgcn_global_load_lds((const unsigned*)((const char*)(gbase) + (voff)[_i]), (PG8_LAS unsigned*)(lds + (bufoff) + ldsw + _i * 8192), 16, 0, 0); } while (0)
; #define PG8_LDA(dst, b, h) do { _Pragma("unroll") for (int m = 0; m < 4; ++m) _Pragma("unroll") for (int k = 0; k < 2; ++k) dst[m][k] = *(const PG8_LAS bf16x8*)(lds + PG8_SA(b, h) + aoff + m * 2048 + k * 1024); } while (0)
; #define PG8_LDB(dst, b, h) do { _Pragma("unroll") for (int n = 0; n < 2; ++n) _Pragma("unroll") for (int k = 0; k < 2; ++k) dst[n][k] = *(const PG8_LAS bf16x8*)(lds + PG8_SB(b, h) + boff + n * 2048 + k * 1024); } while (0)
; #define PG8_MMA(ai, bj, At, Bt) do { __builtin_amdgcn_s_setprio(1); _Pragma("unroll") for (int m = 0; m < 4; ++m) _Pragma("unroll") for (int n = 0; n < 2; ++n) _Pragma("unroll") for (int k = 0; k < 2; ++k) \
;     acc[ai][bj][m][n] = __builtin_amdgcn_mfma_f32_16x16x32_bf16(Bt[n][k], At[m][k], acc[ai][bj][m][n], 0, 0, 0); __builtin_amdgcn_s_setprio(0); } while (0)
; #define PG8_WAIT_V(n) asm volatile("s_waitcnt vmcnt(" #n ")" ::: "memory")
; #define PG8_WAIT_L(n) asm volatile("s_waitcnt lgkmcnt(" #n ")" ::: "memory")
; #define PG8_BAR __builtin_amdgcn_s_barrier()
; #define PG8_SCHED __builtin_amdgcn_sched_barrier(0)
; template <class Epi, class Sched>
; DI void gemm_phase(PG8_LAS unsigned char* lds, const Gemm g, const Sched& S, const Epi& E) {
;     ...
;       PG8_LDB(B0, 0, 0); PG8_LDB(B1, 0, 1); PG8_SCHED; PG8_LDA(At, 0, 0); PG8_STAGE(PG8_SA(1, 1), a1 + hstepA, voffA);
;       PG8_WAIT_V(8); PG8_WAIT_L(0); PG8_BAR; PG8_MMA(0, 0, At, B0); PG8_MMA(0, 1, At, B1); PG8_BAR; PG8_SCHED;
;       PG8_LDA(At, 0, 1); PG8_STAGE(PG8_SB(0, 0), b2, voffB); PG8_STAGE(PG8_SB(0, 1), b2 + hstepB, voffB); PG8_STAGE(PG8_SA(0, 0), a2, voffA);
;       PG8_WAIT_V(8); PG8_WAIT_L(0); PG8_BAR; PG8_MMA(1, 0, At, B0); PG8_MMA(1, 1, At, B1); PG8_BAR; PG8_SCHED;
.LBB0_1300:
	ds_read_b128 v[128:131], v156
	ds_read_b128 v[132:135], v156 offset:1024
	ds_read_b128 v[150:153], v156 offset:2048
	ds_read_b128 v[162:165], v156 offset:3072
	ds_read_b128 v[166:169], v157
	ds_read_b128 v[170:173], v157 offset:1024
	ds_read_b128 v[174:177], v157 offset:2048
	ds_read_b128 v[178:181], v157 offset:3072
	s_add_u32 s17, s62, 0xfffc0080
	s_addc_u32 s33, s63, -1
	s_cmp_eq_u32 s75, 12
	s_cselect_b32 s67, s39, s33
	s_cselect_b32 s66, s59, s17
	s_cselect_b32 s65, s37, s74
	s_cselect_b32 s64, s61, s73
	v_lshl_add_u64 v[210:211], s[62:63], 0, v[146:147]
	s_add_i32 m0, s53, 0xc000
	ds_read_b128 v[182:185], v158
	ds_read_b128 v[186:189], v158 offset:1024
	ds_read_b128 v[190:193], v158 offset:2048
	ds_read_b128 v[194:197], v158 offset:3072
	ds_read_b128 v[198:201], v158 offset:4096
	ds_read_b128 v[202:205], v158 offset:5120
	ds_read_b128 v[206:209], v158 offset:6144
	ds_read_b128 v[214:217], v158 offset:7168
	global_load_lds_dwordx4 v[210:211], off
	v_lshl_add_u64 v[210:211], s[62:63], 0, v[148:149]
	s_add_i32 m0, s53, 0xe000
	s_nop 0
	global_load_lds_dwordx4 v[210:211], off
	s_waitcnt vmcnt(8)
	s_waitcnt lgkmcnt(0)
	s_barrier
	s_setprio 1
	s_waitcnt lgkmcnt(0)
	v_mfma_f32_16x16x32_bf16 v[124:127], v[128:131], v[182:185], v[124:127]
	v_mfma_f32_16x16x32_bf16 v[120:123], v[150:153], v[182:185], v[120:123]
	v_mfma_f32_16x16x32_bf16 v[108:111], v[128:131], v[190:193], v[108:111]
	v_mfma_f32_16x16x32_bf16 v[104:107], v[150:153], v[190:193], v[104:107]
	v_mfma_f32_16x16x32_bf16 v[92:95], v[128:131], v[198:201], v[92:95]
	v_mfma_f32_16x16x32_bf16 v[88:91], v[150:153], v[198:201], v[88:91]
	v_mfma_f32_16x16x32_bf16 v[76:79], v[128:131], v[206:209], v[76:79]
	v_mfma_f32_16x16x32_bf16 v[72:75], v[150:153], v[206:209], v[72:75]
	v_mfma_f32_16x16x32_bf16 v[124:127], v[132:135], v[186:189], v[124:127]
	v_mfma_f32_16x16x32_bf16 v[120:123], v[162:165], v[186:189], v[120:123]
	v_mfma_f32_16x16x32_bf16 v[108:111], v[132:135], v[194:197], v[108:111]
	v_mfma_f32_16x16x32_bf16 v[104:107], v[162:165], v[194:197], v[104:107]
	v_mfma_f32_16x16x32_bf16 v[92:95], v[132:135], v[202:205], v[92:95]
	v_mfma_f32_16x16x32_bf16 v[88:91], v[162:165], v[202:205], v[88:91]
	v_mfma_f32_16x16x32_bf16 v[76:79], v[132:135], v[214:217], v[76:79]
	v_mfma_f32_16x16x32_bf16 v[72:75], v[162:165], v[214:217], v[72:75]
	s_setprio 0
	s_setprio 1
	v_mfma_f32_16x16x32_bf16 v[116:119], v[166:169], v[182:185], v[116:119]
	v_mfma_f32_16x16x32_bf16 v[112:115], v[174:177], v[182:185], v[112:115]
	v_mfma_f32_16x16x32_bf16 v[100:103], v[166:169], v[190:193], v[100:103]
	v_mfma_f32_16x16x32_bf16 v[96:99], v[174:177], v[190:193], v[96:99]
	v_mfma_f32_16x16x32_bf16 v[84:87], v[166:169], v[198:201], v[84:87]
	v_mfma_f32_16x16x32_bf16 v[80:83], v[174:177], v[198:201], v[80:83]
	v_mfma_f32_16x16x32_bf16 v[68:71], v[166:169], v[206:209], v[68:71]
	v_mfma_f32_16x16x32_bf16 v[64:67], v[174:177], v[206:209], v[64:67]
	v_mfma_f32_16x16x32_bf16 v[116:119], v[170:173], v[186:189], v[116:119]
	v_mfma_f32_16x16x32_bf16 v[112:115], v[178:181], v[186:189], v[112:115]
	v_mfma_f32_16x16x32_bf16 v[100:103], v[170:173], v[194:197], v[100:103]
	v_mfma_f32_16x16x32_bf16 v[96:99], v[178:181], v[194:197], v[96:99]
	v_mfma_f32_16x16x32_bf16 v[84:87], v[170:173], v[202:205], v[84:87]
	v_mfma_f32_16x16x32_bf16 v[80:83], v[178:181], v[202:205], v[80:83]
	v_mfma_f32_16x16x32_bf16 v[68:71], v[170:173], v[214:217], v[68:71]
	v_mfma_f32_16x16x32_bf16 v[64:67], v[178:181], v[214:217], v[64:67]
	s_setprio 0
	s_barrier
	s_add_i32 s17, s69, s16
	v_lshl_add_u64 v[210:211], s[64:65], 0, v[138:139]
	s_mov_b32 m0, s17
	ds_read_b128 v[182:185], v158 offset:16384
	ds_read_b128 v[186:189], v158 offset:17408
	ds_read_b128 v[190:193], v158 offset:18432
	ds_read_b128 v[194:197], v158 offset:19456
	ds_read_b128 v[198:201], v158 offset:20480
	ds_read_b128 v[202:205], v158 offset:21504
	ds_read_b128 v[206:209], v158 offset:22528
	ds_read_b128 v[214:217], v158 offset:23552
	global_load_lds_dwordx4 v[210:211], off
	s_add_i32 m0, s17, 0x2000
	s_add_u32 s56, s64, 0x40000
	v_lshl_add_u64 v[218:219], s[64:65], 0, v[142:143]
	s_addc_u32 s57, s65, 0
	s_add_i32 s17, s70, s16
	global_load_lds_dwordx4 v[218:219], off
	v_lshl_add_u64 v[220:221], s[56:57], 0, v[138:139]
	s_mov_b32 m0, s17
	v_lshl_add_u64 v[222:223], s[66:67], 0, v[140:141]
	global_load_lds_dwordx4 v[220:221], off
	v_lshl_add_u64 v[220:221], s[56:57], 0, v[142:143]
	s_add_i32 m0, s17, 0x2000
	s_nop 0
	global_load_lds_dwordx4 v[220:221], off
	v_lshl_add_u64 v[220:221], s[66:67], 0, v[136:137]
	s_mov_b32 m0, s53
	s_nop 0
	global_load_lds_dwordx4 v[220:221], off
	s_mov_b32 m0, s18
	s_nop 0
	global_load_lds_dwordx4 v[222:223], off
	s_waitcnt vmcnt(8)
	s_waitcnt lgkmcnt(0)
	s_barrier
; #define PG8_STAGE(bufoff, gbase, voff) do { _Pragma("unroll") for (int _i = 0; _i < 2; ++_i) \
;     __builtin_amdgcn_global_load_lds((const unsigned*)((const char*)(gbase) + (voff)[_i]), (PG8_LAS unsigned*)(lds + (bufoff) + ldsw + _i * 8192), 16, 0, 0); } while (0)
; #define PG8_LDA(dst, b, h) do { _Pragma("unroll") for (int m = 0; m < 4; ++m) _Pragma("unroll") for (int k = 0; k < 2; ++k) dst[m][k] = *(const PG8_LAS bf16x8*)(lds + PG8_SA(b, h) + aoff + m * 2048 + k * 1024); } while (0)
; #define PG8_LDB(dst, b, h) do { _Pragma("unroll") for (int n = 0; n < 2; ++n) _Pragma("unroll") for (int k = 0; k < 2; ++k) dst[n][k] = *(const PG8_LAS bf16x8*)(lds + PG8_SB(b, h) + boff + n * 2048 + k * 1024); } while (0)
; #define PG8_MMA(ai, bj, At, Bt) do { __builtin_amdgcn_s_setprio(1); _Pragma("unroll") for (int m = 0; m < 4; ++m) _Pragma("unroll") for (int n = 0; n < 2; ++n) _Pragma("unroll") for (int k = 0; k < 2; ++k) \
;     acc[ai][bj][m][n] = __builtin_amdgcn_mfma_f32_16x16x32_bf16(Bt[n][k], At[m][k], acc[ai][bj][m][n], 0, 0, 0); __builtin_amdgcn_s_setprio(0); } while (0)
; #define PG8_WAIT_V(n) asm volatile("s_waitcnt vmcnt(" #n ")" ::: "memory")
; #define PG8_WAIT_L(n) asm volatile("s_waitcnt lgkmcnt(" #n ")" ::: "memory")
; #define PG8_BAR __builtin_amdgcn_s_barrier()
; #define PG8_SCHED __builtin_amdgcn_sched_barrier(0)
; template <class Epi, class Sched>
; DI void gemm_phase(PG8_LAS unsigned char* lds, const Gemm g, const Sched& S, const Epi& E) {
;     ...
;       PG8_WAIT_V(8); PG8_WAIT_L(0); PG8_BAR; PG8_MMA(1, 0, At, B0); PG8_MMA(1, 1, At, B1); PG8_BAR; PG8_SCHED;
;       PG8_LDB(B0, 1, 0); PG8_LDB(B1, 1, 1); PG8_SCHED; PG8_LDA(At, 1, 0); PG8_STAGE(PG8_SA(0, 1), a2 + hstepA, voffA);
;       PG8_WAIT_V(8); PG8_WAIT_L(0); PG8_BAR; PG8_MMA(0, 0, At, B0); PG8_MMA(0, 1, At, B1); PG8_BAR; PG8_SCHED;
	s_setprio 1
	s_waitcnt lgkmcnt(0)
	v_mfma_f32_16x16x32_bf16 v[60:63], v[128:131], v[182:185], v[60:63]
	v_mfma_f32_16x16x32_bf16 v[56:59], v[150:153], v[182:185], v[56:59]
	v_mfma_f32_16x16x32_bf16 v[44:47], v[128:131], v[190:193], v[44:47]
	v_mfma_f32_16x16x32_bf16 v[40:43], v[150:153], v[190:193], v[40:43]
	v_mfma_f32_16x16x32_bf16 v[28:31], v[128:131], v[198:201], v[28:31]
	v_mfma_f32_16x16x32_bf16 v[24:27], v[150:153], v[198:201], v[24:27]
	v_mfma_f32_16x16x32_bf16 v[12:15], v[128:131], v[206:209], v[12:15]
	v_mfma_f32_16x16x32_bf16 v[8:11], v[150:153], v[206:209], v[8:11]
	v_mfma_f32_16x16x32_bf16 v[60:63], v[132:135], v[186:189], v[60:63]
	v_mfma_f32_16x16x32_bf16 v[56:59], v[162:165], v[186:189], v[56:59]
	v_mfma_f32_16x16x32_bf16 v[44:47], v[132:135], v[194:197], v[44:47]
	v_mfma_f32_16x16x32_bf16 v[40:43], v[162:165], v[194:197], v[40:43]
	v_mfma_f32_16x16x32_bf16 v[28:31], v[132:135], v[202:205], v[28:31]
	v_mfma_f32_16x16x32_bf16 v[24:27], v[162:165], v[202:205], v[24:27]
	v_mfma_f32_16x16x32_bf16 v[12:15], v[132:135], v[214:217], v[12:15]
	v_mfma_f32_16x16x32_bf16 v[8:11], v[162:165], v[214:217], v[8:11]
	s_setprio 0
	s_setprio 1
	v_mfma_f32_16x16x32_bf16 v[52:55], v[166:169], v[182:185], v[52:55]
	v_mfma_f32_16x16x32_bf16 v[48:51], v[174:177], v[182:185], v[48:51]
	v_mfma_f32_16x16x32_bf16 v[36:39], v[166:169], v[190:193], v[36:39]
	v_mfma_f32_16x16x32_bf16 v[32:35], v[174:177], v[190:193], v[32:35]
	v_mfma_f32_16x16x32_bf16 v[20:23], v[166:169], v[198:201], v[20:23]
	v_mfma_f32_16x16x32_bf16 v[16:19], v[174:177], v[198:201], v[16:19]
	v_mfma_f32_16x16x32_bf16 v[4:7], v[166:169], v[206:209], v[4:7]
	v_mfma_f32_16x16x32_bf16 v[0:3], v[174:177], v[206:209], v[0:3]
	v_mfma_f32_16x16x32_bf16 v[52:55], v[170:173], v[186:189], v[52:55]
	v_mfma_f32_16x16x32_bf16 v[48:51], v[178:181], v[186:189], v[48:51]
	v_mfma_f32_16x16x32_bf16 v[36:39], v[170:173], v[194:197], v[36:39]
	v_mfma_f32_16x16x32_bf16 v[32:35], v[178:181], v[194:197], v[32:35]
	v_mfma_f32_16x16x32_bf16 v[20:23], v[170:173], v[202:205], v[20:23]
	v_mfma_f32_16x16x32_bf16 v[16:19], v[178:181], v[202:205], v[16:19]
	v_mfma_f32_16x16x32_bf16 v[4:7], v[170:173], v[214:217], v[4:7]
	v_mfma_f32_16x16x32_bf16 v[0:3], v[178:181], v[214:217], v[0:3]
	s_setprio 0
	s_barrier
	s_mov_b32 s17, 0x18000
	s_addk_i32 s17, 0x110
	v_add_u32_e32 v161, s17, v155
	ds_read_b128 v[128:131], v161
	ds_read_b128 v[132:135], v161 offset:1024
	ds_read_b128 v[150:153], v161 offset:2048
	ds_read_b128 v[162:165], v161 offset:3072
	ds_read_b128 v[166:169], v160
	ds_read_b128 v[170:173], v160 offset:1024
	ds_read_b128 v[174:177], v160 offset:2048
	ds_read_b128 v[178:181], v160 offset:3072
	s_add_u32 s56, s66, 0x40000
	s_addc_u32 s57, s67, 0
	s_mov_b32 m0, s19
	v_lshl_add_u64 v[224:225], s[56:57], 0, v[136:137]
	ds_read_b128 v[182:185], v158 offset:32768
	ds_read_b128 v[186:189], v158 offset:33792
	ds_read_b128 v[190:193], v158 offset:34816
	ds_read_b128 v[194:197], v158 offset:35840
	ds_read_b128 v[198:201], v158 offset:36864
	ds_read_b128 v[202:205], v158 offset:37888
	ds_read_b128 v[206:209], v158 offset:38912
	ds_read_b128 v[214:217], v158 offset:39936
	global_load_lds_dwordx4 v[224:225], off
	v_lshl_add_u64 v[224:225], s[56:57], 0, v[140:141]
	s_mov_b32 m0, s54
	s_nop 0
	global_load_lds_dwordx4 v[224:225], off
	s_waitcnt vmcnt(8)
	s_waitcnt lgkmcnt(0)
	s_barrier
	s_setprio 1
	s_waitcnt lgkmcnt(0)
	v_mfma_f32_16x16x32_bf16 v[124:127], v[128:131], v[182:185], v[124:127]
	v_mfma_f32_16x16x32_bf16 v[120:123], v[150:153], v[182:185], v[120:123]
	v_mfma_f32_16x16x32_bf16 v[108:111], v[128:131], v[190:193], v[108:111]
	v_mfma_f32_16x16x32_bf16 v[104:107], v[150:153], v[190:193], v[104:107]
	v_mfma_f32_16x16x32_bf16 v[92:95], v[128:131], v[198:201], v[92:95]
	v_mfma_f32_16x16x32_bf16 v[88:91], v[150:153], v[198:201], v[88:91]
	v_mfma_f32_16x16x32_bf16 v[76:79], v[128:131], v[206:209], v[76:79]
	v_mfma_f32_16x16x32_bf16 v[72:75], v[150:153], v[206:209], v[72:75]
	v_mfma_f32_16x16x32_bf16 v[124:127], v[132:135], v[186:189], v[124:127]
	v_mfma_f32_16x16x32_bf16 v[120:123], v[162:165], v[186:189], v[120:123]
	v_mfma_f32_16x16x32_bf16 v[108:111], v[132:135], v[194:197], v[108:111]
	v_mfma_f32_16x16x32_bf16 v[104:107], v[162:165], v[194:197], v[104:107]
	v_mfma_f32_16x16x32_bf16 v[92:95], v[132:135], v[202:205], v[92:95]
	v_mfma_f32_16x16x32_bf16 v[88:91], v[162:165], v[202:205], v[88:91]
	v_mfma_f32_16x16x32_bf16 v[76:79], v[132:135], v[214:217], v[76:79]
	v_mfma_f32_16x16x32_bf16 v[72:75], v[162:165], v[214:217], v[72:75]
	s_setprio 0
	s_setprio 1
	v_mfma_f32_16x16x32_bf16 v[116:119], v[166:169], v[182:185], v[116:119]
	v_mfma_f32_16x16x32_bf16 v[112:115], v[174:177], v[182:185], v[112:115]
	v_mfma_f32_16x16x32_bf16 v[100:103], v[166:169], v[190:193], v[100:103]
	v_mfma_f32_16x16x32_bf16 v[96:99], v[174:177], v[190:193], v[96:99]
	v_mfma_f32_16x16x32_bf16 v[84:87], v[166:169], v[198:201], v[84:87]
	v_mfma_f32_16x16x32_bf16 v[80:83], v[174:177], v[198:201], v[80:83]
	v_mfma_f32_16x16x32_bf16 v[68:71], v[166:169], v[206:209], v[68:71]
	v_mfma_f32_16x16x32_bf16 v[64:67], v[174:177], v[206:209], v[64:67]
	v_mfma_f32_16x16x32_bf16 v[116:119], v[170:173], v[186:189], v[116:119]
	v_mfma_f32_16x16x32_bf16 v[112:115], v[178:181], v[186:189], v[112:115]
	v_mfma_f32_16x16x32_bf16 v[100:103], v[170:173], v[194:197], v[100:103]
	v_mfma_f32_16x16x32_bf16 v[96:99], v[178:181], v[194:197], v[96:99]
	v_mfma_f32_16x16x32_bf16 v[84:87], v[170:173], v[202:205], v[84:87]
	v_mfma_f32_16x16x32_bf16 v[80:83], v[178:181], v[202:205], v[80:83]
	v_mfma_f32_16x16x32_bf16 v[68:71], v[170:173], v[214:217], v[68:71]
	v_mfma_f32_16x16x32_bf16 v[64:67], v[178:181], v[214:217], v[64:67]
	s_setprio 0
	s_barrier
; #define PG8_STAGE(bufoff, gbase, voff) do { _Pragma("unroll") for (int _i = 0; _i < 2; ++_i) \
;     __builtin_amdgcn_global_load_lds((const unsigned*)((const char*)(gbase) + (voff)[_i]), (PG8_LAS unsigned*)(lds + (bufoff) + ldsw + _i * 8192), 16, 0, 0); } while (0)
; #define PG8_LDA(dst, b, h) do { _Pragma("unroll") for (int m = 0; m < 4; ++m) _Pragma("unroll") for (int k = 0; k < 2; ++k) dst[m][k] = *(const PG8_LAS bf16x8*)(lds + PG8_SA(b, h) + aoff + m * 2048 + k * 1024); } while (0)
; #define PG8_MMA(ai, bj, At, Bt) do { __builtin_amdgcn_s_setprio(1); _Pragma("unroll") for (int m = 0; m < 4; ++m) _Pragma("unroll") for (int n = 0; n < 2; ++n) _Pragma("unroll") for (int k = 0; k < 2; ++k) \
;     acc[ai][bj][m][n] = __builtin_amdgcn_mfma_f32_16x16x32_bf16(Bt[n][k], At[m][k], acc[ai][bj][m][n], 0, 0, 0); __builtin_amdgcn_s_setprio(0); } while (0)
; #define PG8_WAIT_V(n) asm volatile("s_waitcnt vmcnt(" #n ")" ::: "memory")
; #define PG8_WAIT_L(n) asm volatile("s_waitcnt lgkmcnt(" #n ")" ::: "memory")
; #define PG8_BAR __builtin_amdgcn_s_barrier()
; #define PG8_SCHED __builtin_amdgcn_sched_barrier(0)
;   DI void operator()(const f32x4 (&acc)[2][2][4][2], const Unit& u, int wr, int wc, int fr, int fq) const {
;     ...
;     RES_LD(0)
; #pragma unroll
;     for (int i = 0; i < 8; ++i) {
;       const int ai = i >> 2, m = i & 3;
;       if (i + 1 < 8) RES_LD(i + 1)
; template <class Epi, class Sched>
; DI void gemm_phase(PG8_LAS unsigned char* lds, const Gemm g, const Sched& S, const Epi& E) {
;     ...
;       PG8_LDA(At, 1, 1); PG8_STAGE(PG8_SB(1, 0), b3, voffB); PG8_STAGE(PG8_SB(1, 1), b3 + hstepB, voffB); PG8_STAGE(PG8_SA(1, 0), a3, voffA);
;       PG8_WAIT_V(8); PG8_WAIT_L(0); PG8_BAR; PG8_MMA(1, 0, At, B0); PG8_MMA(1, 1, At, B1); PG8_BAR; PG8_SCHED;
;     }
;     if (wr == 0) PG8_BAR;
	s_add_i32 s17, s17, s16
	v_lshl_add_u64 v[210:211], v[210:211], 0, s[6:7]
	s_mov_b32 m0, s17
	ds_read_b128 v[182:185], v158 offset:49152
	ds_read_b128 v[186:189], v158 offset:50176
	ds_read_b128 v[190:193], v158 offset:51200
	ds_read_b128 v[194:197], v158 offset:52224
	ds_read_b128 v[198:201], v158 offset:53248
	ds_read_b128 v[202:205], v158 offset:54272
	ds_read_b128 v[206:209], v158 offset:55296
	ds_read_b128 v[214:217], v158 offset:56320
	global_load_lds_dwordx4 v[210:211], off
	s_add_i32 m0, s17, 0x2000
	s_add_u32 s56, s64, 0x40080
	v_lshl_add_u64 v[210:211], v[218:219], 0, s[6:7]
	s_addc_u32 s57, s65, 0
	s_add_i32 s17, s71, s16
	global_load_lds_dwordx4 v[210:211], off
	v_lshl_add_u64 v[210:211], s[56:57], 0, v[138:139]
	s_mov_b32 m0, s17
	s_nop 0
	global_load_lds_dwordx4 v[210:211], off
	v_lshl_add_u64 v[210:211], s[56:57], 0, v[142:143]
	s_add_i32 m0, s17, 0x2000
	s_nop 0
	global_load_lds_dwordx4 v[210:211], off
	v_lshl_add_u64 v[210:211], v[220:221], 0, s[6:7]
	s_mov_b32 m0, s5
	s_nop 0
	global_load_lds_dwordx4 v[210:211], off
	v_lshl_add_u64 v[210:211], v[222:223], 0, s[6:7]
	s_mov_b32 m0, s55
	s_nop 0
	global_load_lds_dwordx4 v[210:211], off
	s_waitcnt vmcnt(8)
	s_waitcnt lgkmcnt(0)
	s_barrier
	s_setprio 1
	s_waitcnt lgkmcnt(0)
	v_mfma_f32_16x16x32_bf16 v[60:63], v[128:131], v[182:185], v[60:63]
	v_mfma_f32_16x16x32_bf16 v[56:59], v[150:153], v[182:185], v[56:59]
	v_mfma_f32_16x16x32_bf16 v[44:47], v[128:131], v[190:193], v[44:47]
	v_mfma_f32_16x16x32_bf16 v[40:43], v[150:153], v[190:193], v[40:43]
	v_mfma_f32_16x16x32_bf16 v[28:31], v[128:131], v[198:201], v[28:31]
	v_mfma_f32_16x16x32_bf16 v[24:27], v[150:153], v[198:201], v[24:27]
	v_mfma_f32_16x16x32_bf16 v[12:15], v[128:131], v[206:209], v[12:15]
	v_mfma_f32_16x16x32_bf16 v[8:11], v[150:153], v[206:209], v[8:11]
	v_mfma_f32_16x16x32_bf16 v[60:63], v[132:135], v[186:189], v[60:63]
	v_mfma_f32_16x16x32_bf16 v[56:59], v[162:165], v[186:189], v[56:59]
	v_mfma_f32_16x16x32_bf16 v[44:47], v[132:135], v[194:197], v[44:47]
	v_mfma_f32_16x16x32_bf16 v[40:43], v[162:165], v[194:197], v[40:43]
	v_mfma_f32_16x16x32_bf16 v[28:31], v[132:135], v[202:205], v[28:31]
	v_mfma_f32_16x16x32_bf16 v[24:27], v[162:165], v[202:205], v[24:27]
	v_mfma_f32_16x16x32_bf16 v[12:15], v[132:135], v[214:217], v[12:15]
	v_mfma_f32_16x16x32_bf16 v[8:11], v[162:165], v[214:217], v[8:11]
	s_setprio 0
	s_setprio 1
	v_mfma_f32_16x16x32_bf16 v[52:55], v[166:169], v[182:185], v[52:55]
	v_mfma_f32_16x16x32_bf16 v[48:51], v[174:177], v[182:185], v[48:51]
	v_mfma_f32_16x16x32_bf16 v[36:39], v[166:169], v[190:193], v[36:39]
	v_mfma_f32_16x16x32_bf16 v[32:35], v[174:177], v[190:193], v[32:35]
	v_mfma_f32_16x16x32_bf16 v[20:23], v[166:169], v[198:201], v[20:23]
	v_mfma_f32_16x16x32_bf16 v[16:19], v[174:177], v[198:201], v[16:19]
	v_mfma_f32_16x16x32_bf16 v[4:7], v[166:169], v[206:209], v[4:7]
	v_mfma_f32_16x16x32_bf16 v[0:3], v[174:177], v[206:209], v[0:3]
	v_mfma_f32_16x16x32_bf16 v[52:55], v[170:173], v[186:189], v[52:55]
	v_mfma_f32_16x16x32_bf16 v[48:51], v[178:181], v[186:189], v[48:51]
	v_mfma_f32_16x16x32_bf16 v[36:39], v[170:173], v[194:197], v[36:39]
	v_mfma_f32_16x16x32_bf16 v[32:35], v[178:181], v[194:197], v[32:35]
	v_mfma_f32_16x16x32_bf16 v[20:23], v[170:173], v[202:205], v[20:23]
	v_mfma_f32_16x16x32_bf16 v[16:19], v[178:181], v[202:205], v[16:19]
	v_mfma_f32_16x16x32_bf16 v[4:7], v[170:173], v[214:217], v[4:7]
	v_mfma_f32_16x16x32_bf16 v[0:3], v[178:181], v[214:217], v[0:3]
	s_setprio 0
	s_add_i32 s75, s75, 2
	s_add_u32 s62, s62, 0x100
	s_addc_u32 s63, s63, 0
	s_add_u32 s73, s73, 0x100
	s_addc_u32 s74, s74, 0
	s_cmp_gt_u32 s75, 13
	s_barrier
	s_cbranch_scc0 .LBB0_1300
	v_lshl_add_u32 v152, s60, 8, v154
	v_ashrrev_i32_e32 v153, 31, v152
	s_lshl_b32 s56, s58, 8
	v_lshlrev_b64 v[128:129], 11, v[152:153]
	s_ashr_i32 s57, s56, 31
	v_lshl_add_u64 v[128:129], s[50:51], 0, v[128:129]
	v_lshl_add_u64 v[128:129], s[56:57], 1, v[128:129]
	v_lshl_add_u64 v[128:129], v[128:129], 0, s[10:11]
	v_lshl_add_u64 v[150:151], v[128:129], 0, v[144:145]
	s_mov_b32 s17, 0x8000
	v_add_co_u32_e32 v128, vcc, s17, v150
	global_load_dwordx4 v[164:167], v[150:151], off
	global_load_dwordx4 v[168:171], v[150:151], off offset:256
	v_addc_co_u32_e32 v129, vcc, 0, v151, vcc
	global_load_dwordx4 v[132:135], v[128:129], off
	s_nop 0
	global_load_dwordx4 v[128:131], v[128:129], off offset:256
	s_and_b64 vcc, exec, s[8:9]
	s_cbranch_vccz .LBB0_1303
	s_barrier

; #define PG8_STAGE(bufoff, gbase, voff) do { _Pragma("unroll") for (int _i = 0; _i < 2; ++_i) \
;     __builtin_amdgcn_global_load_lds((const unsigned*)((const char*)(gbase) + (voff)[_i]), (PG8_LAS unsigned*)(lds + (bufoff) + ldsw + _i * 8192), 16, 0, 0); } while (0)
; #define PG8_LDA(dst, b, h) do { _Pragma("unroll") for (int m = 0; m < 4; ++m) _Pragma("unroll") for (int k = 0; k < 2; ++k) dst[m][k] = *(const PG8_LAS bf16x8*)(lds + PG8_SA(b, h) + aoff + m * 2048 + k * 1024); } while (0)
; #define PG8_LDB(dst, b, h) do { _Pragma("unroll") for (int n = 0; n < 2; ++n) _Pragma("unroll") for (int k = 0; k < 2; ++k) dst[n][k] = *(const PG8_LAS bf16x8*)(lds + PG8_SB(b, h) + boff + n * 2048 + k * 1024); } while (0)
; #define PG8_MMA(ai, bj, At, Bt) do { __builtin_amdgcn_s_setprio(1); _Pragma("unroll") for (int m = 0; m < 4; ++m) _Pragma("unroll") for (int n = 0; n < 2; ++n) _Pragma("unroll") for (int k = 0; k < 2; ++k) \
;     acc[ai][bj][m][n] = __builtin_amdgcn_mfma_f32_16x16x32_bf16(Bt[n][k], At[m][k], acc[ai][bj][m][n], 0, 0, 0); __builtin_amdgcn_s_setprio(0); } while (0)
; #define PG8_WAIT_V(n) asm volatile("s_waitcnt vmcnt(" #n ")" ::: "memory")
; #define PG8_WAIT_L(n) asm volatile("s_waitcnt lgkmcnt(" #n ")" ::: "memory")
; #define PG8_BAR __builtin_amdgcn_s_barrier()
; #define PG8_SCHED __builtin_amdgcn_sched_barrier(0)
; template <class Epi, class Sched>
; DI void gemm_phase(PG8_LAS unsigned char* lds, const Gemm g, const Sched& S, const Epi& E) {
;     ...
;       PG8_LDB(B0, 0, 0); PG8_LDB(B1, 0, 1); PG8_SCHED; PG8_LDA(At, 0, 0); PG8_STAGE(PG8_SA(1, 1), a1 + hstepA, voffA);
;       PG8_WAIT_V(8); PG8_WAIT_L(0); PG8_BAR; PG8_MMA(0, 0, At, B0); PG8_MMA(0, 1, At, B1); PG8_BAR; PG8_SCHED;
;       PG8_LDA(At, 0, 1); PG8_STAGE(PG8_SB(0, 0), b2, voffB); PG8_STAGE(PG8_SB(0, 1), b2 + hstepB, voffB); PG8_STAGE(PG8_SA(0, 0), a2, voffA);
;       PG8_WAIT_V(8); PG8_WAIT_L(0); PG8_BAR; PG8_MMA(1, 0, At, B0); PG8_MMA(1, 1, At, B1); PG8_BAR; PG8_SCHED;
.LBB0_1384:
	ds_read_b128 v[144:147], v155
	ds_read_b128 v[156:159], v155 offset:1024
	ds_read_b128 v[174:177], v155 offset:2048
	ds_read_b128 v[178:181], v155 offset:3072
	ds_read_b128 v[182:185], v161
	ds_read_b128 v[186:189], v161 offset:1024
	ds_read_b128 v[190:193], v161 offset:2048
	ds_read_b128 v[194:197], v161 offset:3072
	s_add_u32 s30, s2, 0xfffc0080
	s_addc_u32 s31, s3, -1
	s_cmp_eq_u32 s55, 12
	s_cselect_b32 s35, s1, s31
	s_cselect_b32 s34, s23, s30
	s_cselect_b32 s31, s21, s54
	s_cselect_b32 s30, s49, s53
	v_lshl_add_u64 v[148:149], s[2:3], 0, v[140:141]
	s_add_i32 m0, s17, 0xc000
	ds_read_b128 v[198:201], v165
	ds_read_b128 v[202:205], v165 offset:1024
	ds_read_b128 v[206:209], v165 offset:2048
	ds_read_b128 v[214:217], v165 offset:3072
	ds_read_b128 v[218:221], v165 offset:4096
	ds_read_b128 v[222:225], v165 offset:5120
	ds_read_b128 v[226:229], v165 offset:6144
	ds_read_b128 v[230:233], v165 offset:7168
	global_load_lds_dwordx4 v[148:149], off
	v_lshl_add_u64 v[148:149], s[2:3], 0, v[142:143]
	s_add_i32 m0, s17, 0xe000
	s_nop 0
	global_load_lds_dwordx4 v[148:149], off
	s_waitcnt vmcnt(8)
	s_waitcnt lgkmcnt(0)
	s_barrier
	s_setprio 1
	s_waitcnt lgkmcnt(0)
	v_mfma_f32_16x16x32_bf16 v[124:127], v[144:147], v[198:201], v[124:127]
	v_mfma_f32_16x16x32_bf16 v[120:123], v[174:177], v[198:201], v[120:123]
	v_mfma_f32_16x16x32_bf16 v[108:111], v[144:147], v[206:209], v[108:111]
	v_mfma_f32_16x16x32_bf16 v[104:107], v[174:177], v[206:209], v[104:107]
	v_mfma_f32_16x16x32_bf16 v[92:95], v[144:147], v[218:221], v[92:95]
	v_mfma_f32_16x16x32_bf16 v[88:91], v[174:177], v[218:221], v[88:91]
	v_mfma_f32_16x16x32_bf16 v[76:79], v[144:147], v[226:229], v[76:79]
	v_mfma_f32_16x16x32_bf16 v[72:75], v[174:177], v[226:229], v[72:75]
	v_mfma_f32_16x16x32_bf16 v[124:127], v[156:159], v[202:205], v[124:127]
	v_mfma_f32_16x16x32_bf16 v[120:123], v[178:181], v[202:205], v[120:123]
	v_mfma_f32_16x16x32_bf16 v[108:111], v[156:159], v[214:217], v[108:111]
	v_mfma_f32_16x16x32_bf16 v[104:107], v[178:181], v[214:217], v[104:107]
	v_mfma_f32_16x16x32_bf16 v[92:95], v[156:159], v[222:225], v[92:95]
	v_mfma_f32_16x16x32_bf16 v[88:91], v[178:181], v[222:225], v[88:91]
	v_mfma_f32_16x16x32_bf16 v[76:79], v[156:159], v[230:233], v[76:79]
	v_mfma_f32_16x16x32_bf16 v[72:75], v[178:181], v[230:233], v[72:75]
	s_setprio 0
	s_setprio 1
	v_mfma_f32_16x16x32_bf16 v[116:119], v[182:185], v[198:201], v[116:119]
	v_mfma_f32_16x16x32_bf16 v[112:115], v[190:193], v[198:201], v[112:115]
	v_mfma_f32_16x16x32_bf16 v[100:103], v[182:185], v[206:209], v[100:103]
	v_mfma_f32_16x16x32_bf16 v[96:99], v[190:193], v[206:209], v[96:99]
	v_mfma_f32_16x16x32_bf16 v[84:87], v[182:185], v[218:221], v[84:87]
	v_mfma_f32_16x16x32_bf16 v[80:83], v[190:193], v[218:221], v[80:83]
	v_mfma_f32_16x16x32_bf16 v[68:71], v[182:185], v[226:229], v[68:71]
	v_mfma_f32_16x16x32_bf16 v[64:67], v[190:193], v[226:229], v[64:67]
	v_mfma_f32_16x16x32_bf16 v[116:119], v[186:189], v[202:205], v[116:119]
	v_mfma_f32_16x16x32_bf16 v[112:115], v[194:197], v[202:205], v[112:115]
	v_mfma_f32_16x16x32_bf16 v[100:103], v[186:189], v[214:217], v[100:103]
	v_mfma_f32_16x16x32_bf16 v[96:99], v[194:197], v[214:217], v[96:99]
	v_mfma_f32_16x16x32_bf16 v[84:87], v[186:189], v[222:225], v[84:87]
	v_mfma_f32_16x16x32_bf16 v[80:83], v[194:197], v[222:225], v[80:83]
	v_mfma_f32_16x16x32_bf16 v[68:71], v[186:189], v[230:233], v[68:71]
	v_mfma_f32_16x16x32_bf16 v[64:67], v[194:197], v[230:233], v[64:67]
	s_setprio 0
	s_barrier
	s_add_i32 s56, s37, s15
	v_lshl_add_u64 v[148:149], s[30:31], 0, v[132:133]
	s_mov_b32 m0, s56
	ds_read_b128 v[198:201], v165 offset:16384
	ds_read_b128 v[202:205], v165 offset:17408
	ds_read_b128 v[206:209], v165 offset:18432
	ds_read_b128 v[214:217], v165 offset:19456
	ds_read_b128 v[218:221], v165 offset:20480
	ds_read_b128 v[222:225], v165 offset:21504
	ds_read_b128 v[226:229], v165 offset:22528
	ds_read_b128 v[230:233], v165 offset:23552
	global_load_lds_dwordx4 v[148:149], off
	s_add_i32 m0, s56, 0x2000
	s_add_u32 s56, s30, 0x40000
	v_lshl_add_u64 v[152:153], s[30:31], 0, v[128:129]
	s_addc_u32 s57, s31, 0
	s_add_i32 s58, s38, s15
	global_load_lds_dwordx4 v[152:153], off
	v_lshl_add_u64 v[162:163], s[56:57], 0, v[132:133]
	s_mov_b32 m0, s58
	v_lshl_add_u64 v[166:167], s[34:35], 0, v[130:131]
	global_load_lds_dwordx4 v[162:163], off
	v_lshl_add_u64 v[162:163], s[56:57], 0, v[128:129]
	s_add_i32 m0, s58, 0x2000
	s_nop 0
	global_load_lds_dwordx4 v[162:163], off
	v_lshl_add_u64 v[162:163], s[34:35], 0, v[134:135]
	s_mov_b32 m0, s17
	s_nop 0
	global_load_lds_dwordx4 v[162:163], off
	s_mov_b32 m0, s4
	s_nop 0
	global_load_lds_dwordx4 v[166:167], off
	s_waitcnt vmcnt(8)
	s_waitcnt lgkmcnt(0)
	s_barrier
; #define PG8_STAGE(bufoff, gbase, voff) do { _Pragma("unroll") for (int _i = 0; _i < 2; ++_i) \
;     __builtin_amdgcn_global_load_lds((const unsigned*)((const char*)(gbase) + (voff)[_i]), (PG8_LAS unsigned*)(lds + (bufoff) + ldsw + _i * 8192), 16, 0, 0); } while (0)
; #define PG8_LDA(dst, b, h) do { _Pragma("unroll") for (int m = 0; m < 4; ++m) _Pragma("unroll") for (int k = 0; k < 2; ++k) dst[m][k] = *(const PG8_LAS bf16x8*)(lds + PG8_SA(b, h) + aoff + m * 2048 + k * 1024); } while (0)
; #define PG8_LDB(dst, b, h) do { _Pragma("unroll") for (int n = 0; n < 2; ++n) _Pragma("unroll") for (int k = 0; k < 2; ++k) dst[n][k] = *(const PG8_LAS bf16x8*)(lds + PG8_SB(b, h) + boff + n * 2048 + k * 1024); } while (0)
; #define PG8_MMA(ai, bj, At, Bt) do { __builtin_amdgcn_s_setprio(1); _Pragma("unroll") for (int m = 0; m < 4; ++m) _Pragma("unroll") for (int n = 0; n < 2; ++n) _Pragma("unroll") for (int k = 0; k < 2; ++k) \
;     acc[ai][bj][m][n] = __builtin_amdgcn_mfma_f32_16x16x32_bf16(Bt[n][k], At[m][k], acc[ai][bj][m][n], 0, 0, 0); __builtin_amdgcn_s_setprio(0); } while (0)
; #define PG8_WAIT_V(n) asm volatile("s_waitcnt vmcnt(" #n ")" ::: "memory")
; #define PG8_WAIT_L(n) asm volatile("s_waitcnt lgkmcnt(" #n ")" ::: "memory")
; #define PG8_BAR __builtin_amdgcn_s_barrier()
; #define PG8_SCHED __builtin_amdgcn_sched_barrier(0)
; template <class Epi, class Sched>
; DI void gemm_phase(PG8_LAS unsigned char* lds, const Gemm g, const Sched& S, const Epi& E) {
;     ...
;       PG8_WAIT_V(8); PG8_WAIT_L(0); PG8_BAR; PG8_MMA(1, 0, At, B0); PG8_MMA(1, 1, At, B1); PG8_BAR; PG8_SCHED;
;       PG8_LDB(B0, 1, 0); PG8_LDB(B1, 1, 1); PG8_SCHED; PG8_LDA(At, 1, 0); PG8_STAGE(PG8_SA(0, 1), a2 + hstepA, voffA);
;       PG8_WAIT_V(8); PG8_WAIT_L(0); PG8_BAR; PG8_MMA(0, 0, At, B0); PG8_MMA(0, 1, At, B1); PG8_BAR; PG8_SCHED;
	s_setprio 1
	s_waitcnt lgkmcnt(0)
	v_mfma_f32_16x16x32_bf16 v[60:63], v[144:147], v[198:201], v[60:63]
	v_mfma_f32_16x16x32_bf16 v[56:59], v[174:177], v[198:201], v[56:59]
	v_mfma_f32_16x16x32_bf16 v[44:47], v[144:147], v[206:209], v[44:47]
	v_mfma_f32_16x16x32_bf16 v[40:43], v[174:177], v[206:209], v[40:43]
	v_mfma_f32_16x16x32_bf16 v[28:31], v[144:147], v[218:221], v[28:31]
	v_mfma_f32_16x16x32_bf16 v[24:27], v[174:177], v[218:221], v[24:27]
	v_mfma_f32_16x16x32_bf16 v[12:15], v[144:147], v[226:229], v[12:15]
	v_mfma_f32_16x16x32_bf16 v[8:11], v[174:177], v[226:229], v[8:11]
	v_mfma_f32_16x16x32_bf16 v[60:63], v[156:159], v[202:205], v[60:63]
	v_mfma_f32_16x16x32_bf16 v[56:59], v[178:181], v[202:205], v[56:59]
	v_mfma_f32_16x16x32_bf16 v[44:47], v[156:159], v[214:217], v[44:47]
	v_mfma_f32_16x16x32_bf16 v[40:43], v[178:181], v[214:217], v[40:43]
	v_mfma_f32_16x16x32_bf16 v[28:31], v[156:159], v[222:225], v[28:31]
	v_mfma_f32_16x16x32_bf16 v[24:27], v[178:181], v[222:225], v[24:27]
	v_mfma_f32_16x16x32_bf16 v[12:15], v[156:159], v[230:233], v[12:15]
	v_mfma_f32_16x16x32_bf16 v[8:11], v[178:181], v[230:233], v[8:11]
	s_setprio 0
	s_setprio 1
	v_mfma_f32_16x16x32_bf16 v[52:55], v[182:185], v[198:201], v[52:55]
	v_mfma_f32_16x16x32_bf16 v[48:51], v[190:193], v[198:201], v[48:51]
	v_mfma_f32_16x16x32_bf16 v[36:39], v[182:185], v[206:209], v[36:39]
	v_mfma_f32_16x16x32_bf16 v[32:35], v[190:193], v[206:209], v[32:35]
	v_mfma_f32_16x16x32_bf16 v[20:23], v[182:185], v[218:221], v[20:23]
	v_mfma_f32_16x16x32_bf16 v[16:19], v[190:193], v[218:221], v[16:19]
	v_mfma_f32_16x16x32_bf16 v[4:7], v[182:185], v[226:229], v[4:7]
	v_mfma_f32_16x16x32_bf16 v[0:3], v[190:193], v[226:229], v[0:3]
	v_mfma_f32_16x16x32_bf16 v[52:55], v[186:189], v[202:205], v[52:55]
	v_mfma_f32_16x16x32_bf16 v[48:51], v[194:197], v[202:205], v[48:51]
	v_mfma_f32_16x16x32_bf16 v[36:39], v[186:189], v[214:217], v[36:39]
	v_mfma_f32_16x16x32_bf16 v[32:35], v[194:197], v[214:217], v[32:35]
	v_mfma_f32_16x16x32_bf16 v[20:23], v[186:189], v[222:225], v[20:23]
	v_mfma_f32_16x16x32_bf16 v[16:19], v[194:197], v[222:225], v[16:19]
	v_mfma_f32_16x16x32_bf16 v[4:7], v[186:189], v[230:233], v[4:7]
	v_mfma_f32_16x16x32_bf16 v[0:3], v[194:197], v[230:233], v[0:3]
	s_setprio 0
	s_barrier
	ds_read_b128 v[144:147], v171
	ds_read_b128 v[156:159], v171 offset:1024
	ds_read_b128 v[174:177], v171 offset:2048
	ds_read_b128 v[178:181], v171 offset:3072
	ds_read_b128 v[182:185], v173
	ds_read_b128 v[186:189], v173 offset:1024
	ds_read_b128 v[190:193], v173 offset:2048
	ds_read_b128 v[194:197], v173 offset:3072
	s_add_u32 s34, s34, 0x40000
	s_addc_u32 s35, s35, 0
	s_mov_b32 m0, s5
	v_lshl_add_u64 v[210:211], s[34:35], 0, v[134:135]
	ds_read_b128 v[198:201], v165 offset:32768
	ds_read_b128 v[202:205], v165 offset:33792
	ds_read_b128 v[206:209], v165 offset:34816
	ds_read_b128 v[214:217], v165 offset:35840
	ds_read_b128 v[218:221], v165 offset:36864
	ds_read_b128 v[222:225], v165 offset:37888
	ds_read_b128 v[226:229], v165 offset:38912
	ds_read_b128 v[230:233], v165 offset:39936
	global_load_lds_dwordx4 v[210:211], off
	v_lshl_add_u64 v[210:211], s[34:35], 0, v[130:131]
	s_mov_b32 m0, s19
	s_nop 0
	global_load_lds_dwordx4 v[210:211], off
	s_waitcnt vmcnt(8)
	s_waitcnt lgkmcnt(0)
	s_barrier
	s_setprio 1
	s_waitcnt lgkmcnt(0)
	v_mfma_f32_16x16x32_bf16 v[124:127], v[144:147], v[198:201], v[124:127]
	v_mfma_f32_16x16x32_bf16 v[120:123], v[174:177], v[198:201], v[120:123]
	v_mfma_f32_16x16x32_bf16 v[108:111], v[144:147], v[206:209], v[108:111]
	v_mfma_f32_16x16x32_bf16 v[104:107], v[174:177], v[206:209], v[104:107]
	v_mfma_f32_16x16x32_bf16 v[92:95], v[144:147], v[218:221], v[92:95]
	v_mfma_f32_16x16x32_bf16 v[88:91], v[174:177], v[218:221], v[88:91]
	v_mfma_f32_16x16x32_bf16 v[76:79], v[144:147], v[226:229], v[76:79]
	v_mfma_f32_16x16x32_bf16 v[72:75], v[174:177], v[226:229], v[72:75]
	v_mfma_f32_16x16x32_bf16 v[124:127], v[156:159], v[202:205], v[124:127]
	v_mfma_f32_16x16x32_bf16 v[120:123], v[178:181], v[202:205], v[120:123]
	v_mfma_f32_16x16x32_bf16 v[108:111], v[156:159], v[214:217], v[108:111]
	v_mfma_f32_16x16x32_bf16 v[104:107], v[178:181], v[214:217], v[104:107]
	v_mfma_f32_16x16x32_bf16 v[92:95], v[156:159], v[222:225], v[92:95]
	v_mfma_f32_16x16x32_bf16 v[88:91], v[178:181], v[222:225], v[88:91]
	v_mfma_f32_16x16x32_bf16 v[76:79], v[156:159], v[230:233], v[76:79]
	v_mfma_f32_16x16x32_bf16 v[72:75], v[178:181], v[230:233], v[72:75]
	s_setprio 0
	s_setprio 1
	v_mfma_f32_16x16x32_bf16 v[116:119], v[182:185], v[198:201], v[116:119]
	v_mfma_f32_16x16x32_bf16 v[112:115], v[190:193], v[198:201], v[112:115]
	v_mfma_f32_16x16x32_bf16 v[100:103], v[182:185], v[206:209], v[100:103]
	v_mfma_f32_16x16x32_bf16 v[96:99], v[190:193], v[206:209], v[96:99]
	v_mfma_f32_16x16x32_bf16 v[84:87], v[182:185], v[218:221], v[84:87]
	v_mfma_f32_16x16x32_bf16 v[80:83], v[190:193], v[218:221], v[80:83]
	v_mfma_f32_16x16x32_bf16 v[68:71], v[182:185], v[226:229], v[68:71]
	v_mfma_f32_16x16x32_bf16 v[64:67], v[190:193], v[226:229], v[64:67]
	v_mfma_f32_16x16x32_bf16 v[116:119], v[186:189], v[202:205], v[116:119]
	v_mfma_f32_16x16x32_bf16 v[112:115], v[194:197], v[202:205], v[112:115]
	v_mfma_f32_16x16x32_bf16 v[100:103], v[186:189], v[214:217], v[100:103]
	v_mfma_f32_16x16x32_bf16 v[96:99], v[194:197], v[214:217], v[96:99]
	v_mfma_f32_16x16x32_bf16 v[84:87], v[186:189], v[222:225], v[84:87]
	v_mfma_f32_16x16x32_bf16 v[80:83], v[194:197], v[222:225], v[80:83]
	v_mfma_f32_16x16x32_bf16 v[68:71], v[186:189], v[230:233], v[68:71]
	v_mfma_f32_16x16x32_bf16 v[64:67], v[194:197], v[230:233], v[64:67]
	s_setprio 0
	s_barrier
; #define PG8_STAGE(bufoff, gbase, voff) do { _Pragma("unroll") for (int _i = 0; _i < 2; ++_i) \
;     __builtin_amdgcn_global_load_lds((const unsigned*)((const char*)(gbase) + (voff)[_i]), (PG8_LAS unsigned*)(lds + (bufoff) + ldsw + _i * 8192), 16, 0, 0); } while (0)
; #define PG8_LDA(dst, b, h) do { _Pragma("unroll") for (int m = 0; m < 4; ++m) _Pragma("unroll") for (int k = 0; k < 2; ++k) dst[m][k] = *(const PG8_LAS bf16x8*)(lds + PG8_SA(b, h) + aoff + m * 2048 + k * 1024); } while (0)
; #define PG8_MMA(ai, bj, At, Bt) do { __builtin_amdgcn_s_setprio(1); _Pragma("unroll") for (int m = 0; m < 4; ++m) _Pragma("unroll") for (int n = 0; n < 2; ++n) _Pragma("unroll") for (int k = 0; k < 2; ++k) \
;     acc[ai][bj][m][n] = __builtin_amdgcn_mfma_f32_16x16x32_bf16(Bt[n][k], At[m][k], acc[ai][bj][m][n], 0, 0, 0); __builtin_amdgcn_s_setprio(0); } while (0)
; #define PG8_WAIT_V(n) asm volatile("s_waitcnt vmcnt(" #n ")" ::: "memory")
; #define PG8_WAIT_L(n) asm volatile("s_waitcnt lgkmcnt(" #n ")" ::: "memory")
; #define PG8_BAR __builtin_amdgcn_s_barrier()
; #define PG8_SCHED __builtin_amdgcn_sched_barrier(0)
; DI void rows_rstd(float (&rs)[2][4], const float* ps, const Unit& u, int wr, int fr, int fq, int p_lo, int p_hi, float inv_dim) {
;   f32x4 pv[2][4];
; #pragma unroll
;   for (int ai = 0; ai < 2; ++ai)
; #pragma unroll
;     for (int m = 0; m < 4; ++m) pv[ai][m] = *(const f32x4*)(ps + (size_t)(u.pm * BM + ai * HALF + wr * 64 + m * 16 + fr) * 16 + 4 * fq);
; template <class Epi, class Sched>
; DI void gemm_phase(PG8_LAS unsigned char* lds, const Gemm g, const Sched& S, const Epi& E) {
;     ...
;       PG8_LDA(At, 1, 1); PG8_STAGE(PG8_SB(1, 0), b3, voffB); PG8_STAGE(PG8_SB(1, 1), b3 + hstepB, voffB); PG8_STAGE(PG8_SA(1, 0), a3, voffA);
;       PG8_WAIT_V(8); PG8_WAIT_L(0); PG8_BAR; PG8_MMA(1, 0, At, B0); PG8_MMA(1, 1, At, B1); PG8_BAR; PG8_SCHED;
;     }
;     if (wr == 0) PG8_BAR;
	s_add_i32 s34, s41, s15
	v_lshl_add_u64 v[148:149], v[148:149], 0, s[8:9]
	s_mov_b32 m0, s34
	ds_read_b128 v[198:201], v165 offset:49152
	ds_read_b128 v[202:205], v165 offset:50176
	ds_read_b128 v[206:209], v165 offset:51200
	ds_read_b128 v[214:217], v165 offset:52224
	ds_read_b128 v[218:221], v165 offset:53248
	ds_read_b128 v[222:225], v165 offset:54272
	ds_read_b128 v[226:229], v165 offset:55296
	ds_read_b128 v[230:233], v165 offset:56320
	global_load_lds_dwordx4 v[148:149], off
	s_add_i32 m0, s34, 0x2000
	s_add_u32 s30, s30, 0x40080
	v_lshl_add_u64 v[148:149], v[152:153], 0, s[8:9]
	s_addc_u32 s31, s31, 0
	s_add_i32 s34, s44, s15
	global_load_lds_dwordx4 v[148:149], off
	v_lshl_add_u64 v[148:149], s[30:31], 0, v[132:133]
	s_mov_b32 m0, s34
	s_nop 0
	global_load_lds_dwordx4 v[148:149], off
	v_lshl_add_u64 v[148:149], s[30:31], 0, v[128:129]
	s_add_i32 m0, s34, 0x2000
	s_nop 0
	global_load_lds_dwordx4 v[148:149], off
	v_lshl_add_u64 v[148:149], v[162:163], 0, s[8:9]
	s_mov_b32 m0, s33
	s_nop 0
	global_load_lds_dwordx4 v[148:149], off
	v_lshl_add_u64 v[148:149], v[166:167], 0, s[8:9]
	s_mov_b32 m0, s36
	s_nop 0
	global_load_lds_dwordx4 v[148:149], off
	s_waitcnt vmcnt(8)
	s_waitcnt lgkmcnt(0)
	s_barrier
	s_setprio 1
	s_waitcnt lgkmcnt(0)
	v_mfma_f32_16x16x32_bf16 v[60:63], v[144:147], v[198:201], v[60:63]
	v_mfma_f32_16x16x32_bf16 v[56:59], v[174:177], v[198:201], v[56:59]
	v_mfma_f32_16x16x32_bf16 v[44:47], v[144:147], v[206:209], v[44:47]
	v_mfma_f32_16x16x32_bf16 v[40:43], v[174:177], v[206:209], v[40:43]
	v_mfma_f32_16x16x32_bf16 v[28:31], v[144:147], v[218:221], v[28:31]
	v_mfma_f32_16x16x32_bf16 v[24:27], v[174:177], v[218:221], v[24:27]
	v_mfma_f32_16x16x32_bf16 v[12:15], v[144:147], v[226:229], v[12:15]
	v_mfma_f32_16x16x32_bf16 v[8:11], v[174:177], v[226:229], v[8:11]
	v_mfma_f32_16x16x32_bf16 v[60:63], v[156:159], v[202:205], v[60:63]
	v_mfma_f32_16x16x32_bf16 v[56:59], v[178:181], v[202:205], v[56:59]
	v_mfma_f32_16x16x32_bf16 v[44:47], v[156:159], v[214:217], v[44:47]
	v_mfma_f32_16x16x32_bf16 v[40:43], v[178:181], v[214:217], v[40:43]
	v_mfma_f32_16x16x32_bf16 v[28:31], v[156:159], v[222:225], v[28:31]
	v_mfma_f32_16x16x32_bf16 v[24:27], v[178:181], v[222:225], v[24:27]
	v_mfma_f32_16x16x32_bf16 v[12:15], v[156:159], v[230:233], v[12:15]
	v_mfma_f32_16x16x32_bf16 v[8:11], v[178:181], v[230:233], v[8:11]
	s_setprio 0
	s_setprio 1
	v_mfma_f32_16x16x32_bf16 v[52:55], v[182:185], v[198:201], v[52:55]
	v_mfma_f32_16x16x32_bf16 v[48:51], v[190:193], v[198:201], v[48:51]
	v_mfma_f32_16x16x32_bf16 v[36:39], v[182:185], v[206:209], v[36:39]
	v_mfma_f32_16x16x32_bf16 v[32:35], v[190:193], v[206:209], v[32:35]
	v_mfma_f32_16x16x32_bf16 v[20:23], v[182:185], v[218:221], v[20:23]
	v_mfma_f32_16x16x32_bf16 v[16:19], v[190:193], v[218:221], v[16:19]
	v_mfma_f32_16x16x32_bf16 v[4:7], v[182:185], v[226:229], v[4:7]
	v_mfma_f32_16x16x32_bf16 v[0:3], v[190:193], v[226:229], v[0:3]
	v_mfma_f32_16x16x32_bf16 v[52:55], v[186:189], v[202:205], v[52:55]
	v_mfma_f32_16x16x32_bf16 v[48:51], v[194:197], v[202:205], v[48:51]
	v_mfma_f32_16x16x32_bf16 v[36:39], v[186:189], v[214:217], v[36:39]
	v_mfma_f32_16x16x32_bf16 v[32:35], v[194:197], v[214:217], v[32:35]
	v_mfma_f32_16x16x32_bf16 v[20:23], v[186:189], v[222:225], v[20:23]
	v_mfma_f32_16x16x32_bf16 v[16:19], v[194:197], v[222:225], v[16:19]
	v_mfma_f32_16x16x32_bf16 v[4:7], v[186:189], v[230:233], v[4:7]
	v_mfma_f32_16x16x32_bf16 v[0:3], v[194:197], v[230:233], v[0:3]
	s_setprio 0
	s_add_i32 s55, s55, 2
	s_add_u32 s2, s2, 0x100
	s_addc_u32 s3, s3, 0
	s_add_u32 s53, s53, 0x100
	s_addc_u32 s54, s54, 0
	s_cmp_gt_u32 s55, 13
	s_barrier
	s_cbranch_scc0 .LBB0_1384
	v_lshl_add_u32 v166, s0, 8, v151
	v_or_b32_e32 v162, 16, v166
	v_ashrrev_i32_e32 v167, 31, v166
	v_ashrrev_i32_e32 v163, 31, v162
	v_or_b32_e32 v158, 32, v166
	v_lshlrev_b64 v[146:147], 6, v[166:167]
	v_lshlrev_b64 v[144:145], 6, v[162:163]
	v_ashrrev_i32_e32 v159, 31, v158
	v_lshl_add_u64 v[146:147], v[138:139], 0, v[146:147]
	v_or_b32_e32 v156, 48, v166
	v_lshl_add_u64 v[144:145], v[138:139], 0, v[144:145]
	global_load_dwordx4 v[174:177], v[146:147], off
	v_lshlrev_b64 v[146:147], 6, v[158:159]
	v_ashrrev_i32_e32 v157, 31, v156
	v_lshl_add_u64 v[146:147], v[138:139], 0, v[146:147]
	global_load_dwordx4 v[178:181], v[144:145], off
	global_load_dwordx4 v[182:185], v[146:147], off
	v_lshlrev_b64 v[144:145], 6, v[156:157]
	v_lshl_add_u64 v[144:145], v[138:139], 0, v[144:145]
	global_load_dwordx4 v[186:189], v[144:145], off
	v_add_u32_e32 v152, 0x80, v166
	v_ashrrev_i32_e32 v153, 31, v152
	v_lshlrev_b64 v[144:145], 6, v[152:153]
	v_add_u32_e32 v148, 0x90, v166
	v_lshl_add_u64 v[144:145], v[138:139], 0, v[144:145]
	v_ashrrev_i32_e32 v149, 31, v148
	global_load_dwordx4 v[190:193], v[144:145], off
	v_lshlrev_b64 v[144:145], 6, v[148:149]
	v_lshl_add_u64 v[144:145], v[138:139], 0, v[144:145]
	global_load_dwordx4 v[194:197], v[144:145], off
	v_add_u32_e32 v144, 0xb0, v166
	v_ashrrev_i32_e32 v145, 31, v144
	v_lshlrev_b64 v[146:147], 6, v[144:145]
	v_lshl_add_u64 v[146:147], v[138:139], 0, v[146:147]
	global_load_dwordx4 v[198:201], v[146:147], off
	v_and_b32_e32 v147, 64, v169
	v_add_u32_e32 v146, 0xa0, v166
	v_add_u32_e32 v150, 64, v147
	v_ashrrev_i32_e32 v147, 31, v146
	v_lshlrev_b64 v[202:203], 6, v[146:147]
	v_lshl_add_u64 v[202:203], v[138:139], 0, v[202:203]
	global_load_dwordx4 v[202:205], v[202:203], off
	s_and_b64 vcc, exec, s[10:11]
	s_cbranch_vccz .LBB0_1387
	s_barrier

; #define PG8_STAGE(bufoff, gbase, voff) do { _Pragma("unroll") for (int _i = 0; _i < 2; ++_i) \
;     __builtin_amdgcn_global_load_lds((const unsigned*)((const char*)(gbase) + (voff)[_i]), (PG8_LAS unsigned*)(lds + (bufoff) + ldsw + _i * 8192), 16, 0, 0); } while (0)
; #define PG8_LDA(dst, b, h) do { _Pragma("unroll") for (int m = 0; m < 4; ++m) _Pragma("unroll") for (int k = 0; k < 2; ++k) dst[m][k] = *(const PG8_LAS bf16x8*)(lds + PG8_SA(b, h) + aoff + m * 2048 + k * 1024); } while (0)
; #define PG8_LDB(dst, b, h) do { _Pragma("unroll") for (int n = 0; n < 2; ++n) _Pragma("unroll") for (int k = 0; k < 2; ++k) dst[n][k] = *(const PG8_LAS bf16x8*)(lds + PG8_SB(b, h) + boff + n * 2048 + k * 1024); } while (0)
; #define PG8_MMA(ai, bj, At, Bt) do { __builtin_amdgcn_s_setprio(1); _Pragma("unroll") for (int m = 0; m < 4; ++m) _Pragma("unroll") for (int n = 0; n < 2; ++n) _Pragma("unroll") for (int k = 0; k < 2; ++k) \
;     acc[ai][bj][m][n] = __builtin_amdgcn_mfma_f32_16x16x32_bf16(Bt[n][k], At[m][k], acc[ai][bj][m][n], 0, 0, 0); __builtin_amdgcn_s_setprio(0); } while (0)
; #define PG8_WAIT_V(n) asm volatile("s_waitcnt vmcnt(" #n ")" ::: "memory")
; #define PG8_WAIT_L(n) asm volatile("s_waitcnt lgkmcnt(" #n ")" ::: "memory")
; #define PG8_BAR __builtin_amdgcn_s_barrier()
; #define PG8_SCHED __builtin_amdgcn_sched_barrier(0)
; template <class Epi, class Sched>
; DI void gemm_phase(PG8_LAS unsigned char* lds, const Gemm g, const Sched& S, const Epi& E) {
;     ...
;       PG8_LDB(B0, 0, 0); PG8_LDB(B1, 0, 1); PG8_SCHED; PG8_LDA(At, 0, 0); PG8_STAGE(PG8_SA(1, 1), a1 + hstepA, voffA);
;       PG8_WAIT_V(8); PG8_WAIT_L(0); PG8_BAR; PG8_MMA(0, 0, At, B0); PG8_MMA(0, 1, At, B1); PG8_BAR; PG8_SCHED;
;       PG8_LDA(At, 0, 1); PG8_STAGE(PG8_SB(0, 0), b2, voffB); PG8_STAGE(PG8_SB(0, 1), b2 + hstepB, voffB); PG8_STAGE(PG8_SA(0, 0), a2, voffA);
;       PG8_WAIT_V(8); PG8_WAIT_L(0); PG8_BAR; PG8_MMA(1, 0, At, B0); PG8_MMA(1, 1, At, B1); PG8_BAR; PG8_SCHED;
.LBB0_1456:
	ds_read_b128 v[150:153], v145
	ds_read_b128 v[154:157], v145 offset:1024
	ds_read_b128 v[158:161], v145 offset:2048
	ds_read_b128 v[162:165], v145 offset:3072
	ds_read_b128 v[166:169], v146
	ds_read_b128 v[170:173], v146 offset:1024
	ds_read_b128 v[174:177], v146 offset:2048
	ds_read_b128 v[178:181], v146 offset:3072
	s_add_u32 s14, s12, 0x100
	s_addc_u32 s15, s13, 0
	s_cmp_eq_u32 s60, 40
	s_cselect_b32 s19, s9, s15
	s_cselect_b32 s18, s8, s14
	s_cselect_b32 s17, s11, s59
	s_cselect_b32 s16, s10, s58
	s_mov_b32 m0, s49
	v_lshl_add_u64 v[142:143], s[12:13], 0, v[138:139]
	ds_read_b128 v[182:185], v147
	ds_read_b128 v[186:189], v147 offset:1024
	ds_read_b128 v[190:193], v147 offset:2048
	ds_read_b128 v[194:197], v147 offset:3072
	ds_read_b128 v[198:201], v147 offset:4096
	ds_read_b128 v[202:205], v147 offset:5120
	ds_read_b128 v[206:209], v147 offset:6144
	ds_read_b128 v[210:213], v147 offset:7168
	global_load_lds_dwordx4 v[142:143], off
	v_lshl_add_u64 v[142:143], s[12:13], 0, v[140:141]
	s_mov_b32 m0, s52
	s_nop 0
	global_load_lds_dwordx4 v[142:143], off
	s_waitcnt vmcnt(8)
	s_waitcnt lgkmcnt(0)
	s_barrier
	s_setprio 1
	s_waitcnt lgkmcnt(0)
	v_mfma_f32_16x16x32_bf16 v[124:127], v[150:153], v[182:185], v[124:127]
	v_mfma_f32_16x16x32_bf16 v[120:123], v[158:161], v[182:185], v[120:123]
	v_mfma_f32_16x16x32_bf16 v[108:111], v[150:153], v[190:193], v[108:111]
	v_mfma_f32_16x16x32_bf16 v[104:107], v[158:161], v[190:193], v[104:107]
	v_mfma_f32_16x16x32_bf16 v[92:95], v[150:153], v[198:201], v[92:95]
	v_mfma_f32_16x16x32_bf16 v[88:91], v[158:161], v[198:201], v[88:91]
	v_mfma_f32_16x16x32_bf16 v[76:79], v[150:153], v[206:209], v[76:79]
	v_mfma_f32_16x16x32_bf16 v[72:75], v[158:161], v[206:209], v[72:75]
	v_mfma_f32_16x16x32_bf16 v[124:127], v[154:157], v[186:189], v[124:127]
	v_mfma_f32_16x16x32_bf16 v[120:123], v[162:165], v[186:189], v[120:123]
	v_mfma_f32_16x16x32_bf16 v[108:111], v[154:157], v[194:197], v[108:111]
	v_mfma_f32_16x16x32_bf16 v[104:107], v[162:165], v[194:197], v[104:107]
	v_mfma_f32_16x16x32_bf16 v[92:95], v[154:157], v[202:205], v[92:95]
	v_mfma_f32_16x16x32_bf16 v[88:91], v[162:165], v[202:205], v[88:91]
	v_mfma_f32_16x16x32_bf16 v[76:79], v[154:157], v[210:213], v[76:79]
	v_mfma_f32_16x16x32_bf16 v[72:75], v[162:165], v[210:213], v[72:75]
	s_setprio 0
	s_setprio 1
	v_mfma_f32_16x16x32_bf16 v[116:119], v[166:169], v[182:185], v[116:119]
	v_mfma_f32_16x16x32_bf16 v[112:115], v[174:177], v[182:185], v[112:115]
	v_mfma_f32_16x16x32_bf16 v[100:103], v[166:169], v[190:193], v[100:103]
	v_mfma_f32_16x16x32_bf16 v[96:99], v[174:177], v[190:193], v[96:99]
	v_mfma_f32_16x16x32_bf16 v[84:87], v[166:169], v[198:201], v[84:87]
	v_mfma_f32_16x16x32_bf16 v[80:83], v[174:177], v[198:201], v[80:83]
	v_mfma_f32_16x16x32_bf16 v[68:71], v[166:169], v[206:209], v[68:71]
	v_mfma_f32_16x16x32_bf16 v[64:67], v[174:177], v[206:209], v[64:67]
	v_mfma_f32_16x16x32_bf16 v[116:119], v[170:173], v[186:189], v[116:119]
	v_mfma_f32_16x16x32_bf16 v[112:115], v[178:181], v[186:189], v[112:115]
	v_mfma_f32_16x16x32_bf16 v[100:103], v[170:173], v[194:197], v[100:103]
	v_mfma_f32_16x16x32_bf16 v[96:99], v[178:181], v[194:197], v[96:99]
	v_mfma_f32_16x16x32_bf16 v[84:87], v[170:173], v[202:205], v[84:87]
	v_mfma_f32_16x16x32_bf16 v[80:83], v[178:181], v[202:205], v[80:83]
	v_mfma_f32_16x16x32_bf16 v[68:71], v[170:173], v[210:213], v[68:71]
	v_mfma_f32_16x16x32_bf16 v[64:67], v[178:181], v[210:213], v[64:67]
	s_setprio 0
	s_barrier
	s_add_i32 s12, s33, s20
	v_lshl_add_u64 v[142:143], s[16:17], 0, v[132:133]
	s_mov_b32 m0, s12
	ds_read_b128 v[182:185], v147 offset:16384
	ds_read_b128 v[186:189], v147 offset:17408
	ds_read_b128 v[190:193], v147 offset:18432
	ds_read_b128 v[194:197], v147 offset:19456
	ds_read_b128 v[198:201], v147 offset:20480
	ds_read_b128 v[202:205], v147 offset:21504
	ds_read_b128 v[206:209], v147 offset:22528
	ds_read_b128 v[210:213], v147 offset:23552
	global_load_lds_dwordx4 v[142:143], off
	s_add_i32 m0, s12, 0x2000
	s_add_u32 s12, s16, 0xb0000
	v_lshl_add_u64 v[214:215], s[16:17], 0, v[128:129]
	s_addc_u32 s13, s17, 0
	s_add_i32 s61, s34, s20
	global_load_lds_dwordx4 v[214:215], off
	v_lshl_add_u64 v[216:217], s[12:13], 0, v[132:133]
	s_mov_b32 m0, s61
	v_lshl_add_u64 v[218:219], s[18:19], 0, v[130:131]
	global_load_lds_dwordx4 v[216:217], off
	v_lshl_add_u64 v[216:217], s[12:13], 0, v[128:129]
	s_add_i32 m0, s61, 0x2000
	s_nop 0
	global_load_lds_dwordx4 v[216:217], off
	v_lshl_add_u64 v[216:217], s[18:19], 0, v[134:135]
	s_mov_b32 m0, s22
	s_nop 0
	global_load_lds_dwordx4 v[216:217], off
	s_mov_b32 m0, s23
	s_nop 0
	global_load_lds_dwordx4 v[218:219], off
	s_waitcnt vmcnt(8)
	s_waitcnt lgkmcnt(0)
	s_barrier
; #define PG8_STAGE(bufoff, gbase, voff) do { _Pragma("unroll") for (int _i = 0; _i < 2; ++_i) \
;     __builtin_amdgcn_global_load_lds((const unsigned*)((const char*)(gbase) + (voff)[_i]), (PG8_LAS unsigned*)(lds + (bufoff) + ldsw + _i * 8192), 16, 0, 0); } while (0)
; #define PG8_LDA(dst, b, h) do { _Pragma("unroll") for (int m = 0; m < 4; ++m) _Pragma("unroll") for (int k = 0; k < 2; ++k) dst[m][k] = *(const PG8_LAS bf16x8*)(lds + PG8_SA(b, h) + aoff + m * 2048 + k * 1024); } while (0)
; #define PG8_LDB(dst, b, h) do { _Pragma("unroll") for (int n = 0; n < 2; ++n) _Pragma("unroll") for (int k = 0; k < 2; ++k) dst[n][k] = *(const PG8_LAS bf16x8*)(lds + PG8_SB(b, h) + boff + n * 2048 + k * 1024); } while (0)
; #define PG8_MMA(ai, bj, At, Bt) do { __builtin_amdgcn_s_setprio(1); _Pragma("unroll") for (int m = 0; m < 4; ++m) _Pragma("unroll") for (int n = 0; n < 2; ++n) _Pragma("unroll") for (int k = 0; k < 2; ++k) \
;     acc[ai][bj][m][n] = __builtin_amdgcn_mfma_f32_16x16x32_bf16(Bt[n][k], At[m][k], acc[ai][bj][m][n], 0, 0, 0); __builtin_amdgcn_s_setprio(0); } while (0)
; #define PG8_WAIT_V(n) asm volatile("s_waitcnt vmcnt(" #n ")" ::: "memory")
; #define PG8_WAIT_L(n) asm volatile("s_waitcnt lgkmcnt(" #n ")" ::: "memory")
; #define PG8_BAR __builtin_amdgcn_s_barrier()
; #define PG8_SCHED __builtin_amdgcn_sched_barrier(0)
; template <class Epi, class Sched>
; DI void gemm_phase(PG8_LAS unsigned char* lds, const Gemm g, const Sched& S, const Epi& E) {
;     ...
;       PG8_WAIT_V(8); PG8_WAIT_L(0); PG8_BAR; PG8_MMA(1, 0, At, B0); PG8_MMA(1, 1, At, B1); PG8_BAR; PG8_SCHED;
;       PG8_LDB(B0, 1, 0); PG8_LDB(B1, 1, 1); PG8_SCHED; PG8_LDA(At, 1, 0); PG8_STAGE(PG8_SA(0, 1), a2 + hstepA, voffA);
;       PG8_WAIT_V(8); PG8_WAIT_L(0); PG8_BAR; PG8_MMA(0, 0, At, B0); PG8_MMA(0, 1, At, B1); PG8_BAR; PG8_SCHED;
	s_setprio 1
	s_waitcnt lgkmcnt(0)
	v_mfma_f32_16x16x32_bf16 v[60:63], v[150:153], v[182:185], v[60:63]
	v_mfma_f32_16x16x32_bf16 v[56:59], v[158:161], v[182:185], v[56:59]
	v_mfma_f32_16x16x32_bf16 v[44:47], v[150:153], v[190:193], v[44:47]
	v_mfma_f32_16x16x32_bf16 v[40:43], v[158:161], v[190:193], v[40:43]
	v_mfma_f32_16x16x32_bf16 v[28:31], v[150:153], v[198:201], v[28:31]
	v_mfma_f32_16x16x32_bf16 v[24:27], v[158:161], v[198:201], v[24:27]
	v_mfma_f32_16x16x32_bf16 v[16:19], v[150:153], v[206:209], v[16:19]
	v_mfma_f32_16x16x32_bf16 v[8:11], v[158:161], v[206:209], v[8:11]
	v_mfma_f32_16x16x32_bf16 v[60:63], v[154:157], v[186:189], v[60:63]
	v_mfma_f32_16x16x32_bf16 v[56:59], v[162:165], v[186:189], v[56:59]
	v_mfma_f32_16x16x32_bf16 v[44:47], v[154:157], v[194:197], v[44:47]
	v_mfma_f32_16x16x32_bf16 v[40:43], v[162:165], v[194:197], v[40:43]
	v_mfma_f32_16x16x32_bf16 v[28:31], v[154:157], v[202:205], v[28:31]
	v_mfma_f32_16x16x32_bf16 v[24:27], v[162:165], v[202:205], v[24:27]
	v_mfma_f32_16x16x32_bf16 v[16:19], v[154:157], v[210:213], v[16:19]
	v_mfma_f32_16x16x32_bf16 v[8:11], v[162:165], v[210:213], v[8:11]
	s_setprio 0
	s_setprio 1
	v_mfma_f32_16x16x32_bf16 v[52:55], v[166:169], v[182:185], v[52:55]
	v_mfma_f32_16x16x32_bf16 v[48:51], v[174:177], v[182:185], v[48:51]
	v_mfma_f32_16x16x32_bf16 v[36:39], v[166:169], v[190:193], v[36:39]
	v_mfma_f32_16x16x32_bf16 v[32:35], v[174:177], v[190:193], v[32:35]
	v_mfma_f32_16x16x32_bf16 v[20:23], v[166:169], v[198:201], v[20:23]
	v_mfma_f32_16x16x32_bf16 v[12:15], v[174:177], v[198:201], v[12:15]
	v_mfma_f32_16x16x32_bf16 v[4:7], v[166:169], v[206:209], v[4:7]
	v_mfma_f32_16x16x32_bf16 v[0:3], v[174:177], v[206:209], v[0:3]
	v_mfma_f32_16x16x32_bf16 v[52:55], v[170:173], v[186:189], v[52:55]
	v_mfma_f32_16x16x32_bf16 v[48:51], v[178:181], v[186:189], v[48:51]
	v_mfma_f32_16x16x32_bf16 v[36:39], v[170:173], v[194:197], v[36:39]
	v_mfma_f32_16x16x32_bf16 v[32:35], v[178:181], v[194:197], v[32:35]
	v_mfma_f32_16x16x32_bf16 v[20:23], v[170:173], v[202:205], v[20:23]
	v_mfma_f32_16x16x32_bf16 v[12:15], v[178:181], v[202:205], v[12:15]
	v_mfma_f32_16x16x32_bf16 v[4:7], v[170:173], v[210:213], v[4:7]
	v_mfma_f32_16x16x32_bf16 v[0:3], v[178:181], v[210:213], v[0:3]
	s_setprio 0
	s_barrier
	s_add_i32 s61, s30, 0x110
	v_add_u32_e32 v149, s61, v144
	ds_read_b128 v[150:153], v149
	ds_read_b128 v[154:157], v149 offset:1024
	ds_read_b128 v[158:161], v149 offset:2048
	ds_read_b128 v[162:165], v149 offset:3072
	ds_read_b128 v[166:169], v148
	ds_read_b128 v[170:173], v148 offset:1024
	ds_read_b128 v[174:177], v148 offset:2048
	ds_read_b128 v[178:181], v148 offset:3072
	s_add_u32 s12, s18, 0xb0000
	s_addc_u32 s13, s19, 0
	s_mov_b32 m0, s24
	v_lshl_add_u64 v[220:221], s[12:13], 0, v[134:135]
	ds_read_b128 v[182:185], v147 offset:32768
	ds_read_b128 v[186:189], v147 offset:33792
	ds_read_b128 v[190:193], v147 offset:34816
	ds_read_b128 v[194:197], v147 offset:35840
	ds_read_b128 v[198:201], v147 offset:36864
	ds_read_b128 v[202:205], v147 offset:37888
	ds_read_b128 v[206:209], v147 offset:38912
	ds_read_b128 v[210:213], v147 offset:39936
	global_load_lds_dwordx4 v[220:221], off
	v_lshl_add_u64 v[220:221], s[12:13], 0, v[130:131]
	s_mov_b32 m0, s25
	s_nop 0
	global_load_lds_dwordx4 v[220:221], off
	s_waitcnt vmcnt(8)
	s_waitcnt lgkmcnt(0)
	s_barrier
	s_setprio 1
	s_waitcnt lgkmcnt(0)
	v_mfma_f32_16x16x32_bf16 v[124:127], v[150:153], v[182:185], v[124:127]
	v_mfma_f32_16x16x32_bf16 v[120:123], v[158:161], v[182:185], v[120:123]
	v_mfma_f32_16x16x32_bf16 v[108:111], v[150:153], v[190:193], v[108:111]
	v_mfma_f32_16x16x32_bf16 v[104:107], v[158:161], v[190:193], v[104:107]
	v_mfma_f32_16x16x32_bf16 v[92:95], v[150:153], v[198:201], v[92:95]
	v_mfma_f32_16x16x32_bf16 v[88:91], v[158:161], v[198:201], v[88:91]
	v_mfma_f32_16x16x32_bf16 v[76:79], v[150:153], v[206:209], v[76:79]
	v_mfma_f32_16x16x32_bf16 v[72:75], v[158:161], v[206:209], v[72:75]
	v_mfma_f32_16x16x32_bf16 v[124:127], v[154:157], v[186:189], v[124:127]
	v_mfma_f32_16x16x32_bf16 v[120:123], v[162:165], v[186:189], v[120:123]
	v_mfma_f32_16x16x32_bf16 v[108:111], v[154:157], v[194:197], v[108:111]
	v_mfma_f32_16x16x32_bf16 v[104:107], v[162:165], v[194:197], v[104:107]
	v_mfma_f32_16x16x32_bf16 v[92:95], v[154:157], v[202:205], v[92:95]
	v_mfma_f32_16x16x32_bf16 v[88:91], v[162:165], v[202:205], v[88:91]
	v_mfma_f32_16x16x32_bf16 v[76:79], v[154:157], v[210:213], v[76:79]
	v_mfma_f32_16x16x32_bf16 v[72:75], v[162:165], v[210:213], v[72:75]
	s_setprio 0
	s_setprio 1
	v_mfma_f32_16x16x32_bf16 v[116:119], v[166:169], v[182:185], v[116:119]
	v_mfma_f32_16x16x32_bf16 v[112:115], v[174:177], v[182:185], v[112:115]
	v_mfma_f32_16x16x32_bf16 v[100:103], v[166:169], v[190:193], v[100:103]
	v_mfma_f32_16x16x32_bf16 v[96:99], v[174:177], v[190:193], v[96:99]
	v_mfma_f32_16x16x32_bf16 v[84:87], v[166:169], v[198:201], v[84:87]
	v_mfma_f32_16x16x32_bf16 v[80:83], v[174:177], v[198:201], v[80:83]
	v_mfma_f32_16x16x32_bf16 v[68:71], v[166:169], v[206:209], v[68:71]
	v_mfma_f32_16x16x32_bf16 v[64:67], v[174:177], v[206:209], v[64:67]
	v_mfma_f32_16x16x32_bf16 v[116:119], v[170:173], v[186:189], v[116:119]
	v_mfma_f32_16x16x32_bf16 v[112:115], v[178:181], v[186:189], v[112:115]
	v_mfma_f32_16x16x32_bf16 v[100:103], v[170:173], v[194:197], v[100:103]
	v_mfma_f32_16x16x32_bf16 v[96:99], v[178:181], v[194:197], v[96:99]
	v_mfma_f32_16x16x32_bf16 v[84:87], v[170:173], v[202:205], v[84:87]
	v_mfma_f32_16x16x32_bf16 v[80:83], v[178:181], v[202:205], v[80:83]
	v_mfma_f32_16x16x32_bf16 v[68:71], v[170:173], v[210:213], v[68:71]
	v_mfma_f32_16x16x32_bf16 v[64:67], v[178:181], v[210:213], v[64:67]
	s_setprio 0
	s_barrier
; #define PG8_STAGE(bufoff, gbase, voff) do { _Pragma("unroll") for (int _i = 0; _i < 2; ++_i) \
;     __builtin_amdgcn_global_load_lds((const unsigned*)((const char*)(gbase) + (voff)[_i]), (PG8_LAS unsigned*)(lds + (bufoff) + ldsw + _i * 8192), 16, 0, 0); } while (0)
; #define PG8_LDA(dst, b, h) do { _Pragma("unroll") for (int m = 0; m < 4; ++m) _Pragma("unroll") for (int k = 0; k < 2; ++k) dst[m][k] = *(const PG8_LAS bf16x8*)(lds + PG8_SA(b, h) + aoff + m * 2048 + k * 1024); } while (0)
; #define PG8_MMA(ai, bj, At, Bt) do { __builtin_amdgcn_s_setprio(1); _Pragma("unroll") for (int m = 0; m < 4; ++m) _Pragma("unroll") for (int n = 0; n < 2; ++n) _Pragma("unroll") for (int k = 0; k < 2; ++k) \
;     acc[ai][bj][m][n] = __builtin_amdgcn_mfma_f32_16x16x32_bf16(Bt[n][k], At[m][k], acc[ai][bj][m][n], 0, 0, 0); __builtin_amdgcn_s_setprio(0); } while (0)
; #define PG8_WAIT_V(n) asm volatile("s_waitcnt vmcnt(" #n ")" ::: "memory")
; #define PG8_WAIT_L(n) asm volatile("s_waitcnt lgkmcnt(" #n ")" ::: "memory")
; #define PG8_BAR __builtin_amdgcn_s_barrier()
; #define PG8_SCHED __builtin_amdgcn_sched_barrier(0)
;   DI void operator()(const f32x4 (&acc)[2][2][4][2], const Unit& u, int wr, int wc, int fr, int fq) const {
;     ...
;     RES_LD(0)
; #pragma unroll
;     for (int i = 0; i < 8; ++i) {
;       const int ai = i >> 2, m = i & 3;
;       if (i + 1 < 8) RES_LD(i + 1)
; template <class Epi, class Sched>
; DI void gemm_phase(PG8_LAS unsigned char* lds, const Gemm g, const Sched& S, const Epi& E) {
;     ...
;       PG8_LDA(At, 1, 1); PG8_STAGE(PG8_SB(1, 0), b3, voffB); PG8_STAGE(PG8_SB(1, 1), b3 + hstepB, voffB); PG8_STAGE(PG8_SA(1, 0), a3, voffA);
;       PG8_WAIT_V(8); PG8_WAIT_L(0); PG8_BAR; PG8_MMA(1, 0, At, B0); PG8_MMA(1, 1, At, B1); PG8_BAR; PG8_SCHED;
;     }
;     if (wr == 0) PG8_BAR;
	s_add_i32 s12, s61, s20
	v_lshl_add_u64 v[142:143], v[142:143], 0, s[4:5]
	s_mov_b32 m0, s12
	ds_read_b128 v[182:185], v147 offset:49152
	ds_read_b128 v[186:189], v147 offset:50176
	ds_read_b128 v[190:193], v147 offset:51200
	ds_read_b128 v[194:197], v147 offset:52224
	ds_read_b128 v[198:201], v147 offset:53248
	ds_read_b128 v[202:205], v147 offset:54272
	ds_read_b128 v[206:209], v147 offset:55296
	ds_read_b128 v[210:213], v147 offset:56320
	global_load_lds_dwordx4 v[142:143], off
	s_add_i32 m0, s12, 0x2000
	s_add_u32 s12, s16, 0xb0080
	v_lshl_add_u64 v[142:143], v[214:215], 0, s[4:5]
	s_addc_u32 s13, s17, 0
	s_add_i32 s16, s53, s20
	global_load_lds_dwordx4 v[142:143], off
	v_lshl_add_u64 v[142:143], s[12:13], 0, v[132:133]
	s_mov_b32 m0, s16
	s_nop 0
	global_load_lds_dwordx4 v[142:143], off
	v_lshl_add_u64 v[142:143], s[12:13], 0, v[128:129]
	s_add_i32 m0, s16, 0x2000
	s_nop 0
	global_load_lds_dwordx4 v[142:143], off
	v_lshl_add_u64 v[142:143], v[216:217], 0, s[4:5]
	s_mov_b32 m0, s28
	s_nop 0
	global_load_lds_dwordx4 v[142:143], off
	v_lshl_add_u64 v[142:143], v[218:219], 0, s[4:5]
	s_mov_b32 m0, s29
	s_nop 0
	global_load_lds_dwordx4 v[142:143], off
	s_waitcnt vmcnt(8)
	s_waitcnt lgkmcnt(0)
	s_barrier
	s_setprio 1
	s_waitcnt lgkmcnt(0)
	v_mfma_f32_16x16x32_bf16 v[60:63], v[150:153], v[182:185], v[60:63]
	v_mfma_f32_16x16x32_bf16 v[56:59], v[158:161], v[182:185], v[56:59]
	v_mfma_f32_16x16x32_bf16 v[44:47], v[150:153], v[190:193], v[44:47]
	v_mfma_f32_16x16x32_bf16 v[40:43], v[158:161], v[190:193], v[40:43]
	v_mfma_f32_16x16x32_bf16 v[28:31], v[150:153], v[198:201], v[28:31]
	v_mfma_f32_16x16x32_bf16 v[24:27], v[158:161], v[198:201], v[24:27]
	v_mfma_f32_16x16x32_bf16 v[16:19], v[150:153], v[206:209], v[16:19]
	v_mfma_f32_16x16x32_bf16 v[8:11], v[158:161], v[206:209], v[8:11]
	v_mfma_f32_16x16x32_bf16 v[60:63], v[154:157], v[186:189], v[60:63]
	v_mfma_f32_16x16x32_bf16 v[56:59], v[162:165], v[186:189], v[56:59]
	v_mfma_f32_16x16x32_bf16 v[44:47], v[154:157], v[194:197], v[44:47]
	v_mfma_f32_16x16x32_bf16 v[40:43], v[162:165], v[194:197], v[40:43]
	v_mfma_f32_16x16x32_bf16 v[28:31], v[154:157], v[202:205], v[28:31]
	v_mfma_f32_16x16x32_bf16 v[24:27], v[162:165], v[202:205], v[24:27]
	v_mfma_f32_16x16x32_bf16 v[16:19], v[154:157], v[210:213], v[16:19]
	v_mfma_f32_16x16x32_bf16 v[8:11], v[162:165], v[210:213], v[8:11]
	s_setprio 0
	s_setprio 1
	v_mfma_f32_16x16x32_bf16 v[52:55], v[166:169], v[182:185], v[52:55]
	v_mfma_f32_16x16x32_bf16 v[48:51], v[174:177], v[182:185], v[48:51]
	v_mfma_f32_16x16x32_bf16 v[36:39], v[166:169], v[190:193], v[36:39]
	v_mfma_f32_16x16x32_bf16 v[32:35], v[174:177], v[190:193], v[32:35]
	v_mfma_f32_16x16x32_bf16 v[20:23], v[166:169], v[198:201], v[20:23]
	v_mfma_f32_16x16x32_bf16 v[12:15], v[174:177], v[198:201], v[12:15]
	v_mfma_f32_16x16x32_bf16 v[4:7], v[166:169], v[206:209], v[4:7]
	v_mfma_f32_16x16x32_bf16 v[0:3], v[174:177], v[206:209], v[0:3]
	v_mfma_f32_16x16x32_bf16 v[52:55], v[170:173], v[186:189], v[52:55]
	v_mfma_f32_16x16x32_bf16 v[48:51], v[178:181], v[186:189], v[48:51]
	v_mfma_f32_16x16x32_bf16 v[36:39], v[170:173], v[194:197], v[36:39]
	v_mfma_f32_16x16x32_bf16 v[32:35], v[178:181], v[194:197], v[32:35]
	v_mfma_f32_16x16x32_bf16 v[20:23], v[170:173], v[202:205], v[20:23]
	v_mfma_f32_16x16x32_bf16 v[12:15], v[178:181], v[202:205], v[12:15]
	v_mfma_f32_16x16x32_bf16 v[4:7], v[170:173], v[210:213], v[4:7]
	v_mfma_f32_16x16x32_bf16 v[0:3], v[178:181], v[210:213], v[0:3]
	s_setprio 0
	s_add_i32 s60, s60, 2
	s_add_u32 s58, s58, 0x100
	s_addc_u32 s59, s59, 0
	s_cmp_gt_u32 s60, 41
	s_mov_b64 s[12:13], s[14:15]
	s_barrier
	s_cbranch_scc0 .LBB0_1456
	v_lshl_add_u32 v142, s57, 8, v137
	v_ashrrev_i32_e32 v143, 31, v142
	s_lshl_b32 s12, s56, 8
	v_lshlrev_b64 v[142:143], 10, v[142:143]
	s_ashr_i32 s13, s12, 31
	v_lshl_add_u64 v[166:167], v[142:143], 0, s[12:13]
	v_or_b32_e32 v166, v166, v136
	v_lshl_add_u64 v[142:143], v[166:167], 1, s[50:51]
	v_add_co_u32_e32 v162, vcc, s31, v142
	global_load_dwordx4 v[150:153], v[142:143], off
	global_load_dwordx4 v[154:157], v[142:143], off offset:256
	v_addc_co_u32_e32 v163, vcc, 0, v143, vcc
	global_load_dwordx4 v[158:161], v[162:163], off
	s_nop 0
	global_load_dwordx4 v[162:165], v[162:163], off offset:256
	s_and_b64 vcc, exec, s[6:7]
	s_cbranch_vccz .LBB0_1459
	s_barrier
